# static-priority strategy, step b alone: the per-phase s_setprio flips inside the nine 8-phase GEMM K loops removed (timing-only edit)
# speedup vs baseline: 1.0087x; 1.0028x over previous
.LBB0_93:
	ds_read_b128 v[74:77], v189
	ds_read_b128 v[78:81], v189 offset:1024
	ds_read_b128 v[82:85], v189 offset:2048
	ds_read_b128 v[86:89], v189 offset:3072
	s_add_u32 s34, s4, 0xfffc0080
	s_addc_u32 s35, s5, -1
	s_cmp_eq_u32 s36, 12
	s_cselect_b32 s67, s11, s35
	s_cselect_b32 s66, s20, s34
	s_cselect_b32 s35, s9, s23
	s_cselect_b32 s34, s21, s22
	v_lshl_add_u64 v[220:221], s[4:5], 0, v[158:159]
	s_add_i32 m0, s65, 0xc000
	ds_read_b128 v[166:169], v190
	ds_read_b128 v[192:195], v190 offset:1024
	ds_read_b128 v[196:199], v190 offset:2048
	ds_read_b128 v[200:203], v190 offset:3072
	ds_read_b128 v[204:207], v190 offset:4096
	ds_read_b128 v[208:211], v190 offset:5120
	ds_read_b128 v[212:215], v190 offset:6144
	ds_read_b128 v[216:219], v190 offset:7168
	global_load_lds_dwordx4 v[220:221], off
	v_lshl_add_u64 v[220:221], s[4:5], 0, v[160:161]
	s_add_i32 m0, s65, 0xe000
	s_nop 0
	global_load_lds_dwordx4 v[220:221], off
	s_waitcnt lgkmcnt(8)
	s_barrier
	s_waitcnt lgkmcnt(0)
	s_waitcnt lgkmcnt(0)
	v_mfma_f32_16x16x32_bf16 v[142:145], v[74:77], v[166:169], v[142:145]
	v_mfma_f32_16x16x32_bf16 v[138:141], v[82:85], v[166:169], v[138:141]
	v_mfma_f32_16x16x32_bf16 v[126:129], v[74:77], v[196:199], v[126:129]
	v_mfma_f32_16x16x32_bf16 v[122:125], v[82:85], v[196:199], v[122:125]
	v_mfma_f32_16x16x32_bf16 v[110:113], v[74:77], v[204:207], v[110:113]
	v_mfma_f32_16x16x32_bf16 v[106:109], v[82:85], v[204:207], v[106:109]
	v_mfma_f32_16x16x32_bf16 v[94:97], v[74:77], v[212:215], v[94:97]
	v_mfma_f32_16x16x32_bf16 v[90:93], v[82:85], v[212:215], v[90:93]
	v_mfma_f32_16x16x32_bf16 v[142:145], v[78:81], v[192:195], v[142:145]
	v_mfma_f32_16x16x32_bf16 v[138:141], v[86:89], v[192:195], v[138:141]
	v_mfma_f32_16x16x32_bf16 v[126:129], v[78:81], v[200:203], v[126:129]
	v_mfma_f32_16x16x32_bf16 v[122:125], v[86:89], v[200:203], v[122:125]
	v_mfma_f32_16x16x32_bf16 v[110:113], v[78:81], v[208:211], v[110:113]
	v_mfma_f32_16x16x32_bf16 v[106:109], v[86:89], v[208:211], v[106:109]
	v_mfma_f32_16x16x32_bf16 v[94:97], v[78:81], v[216:219], v[94:97]
	v_mfma_f32_16x16x32_bf16 v[90:93], v[86:89], v[216:219], v[90:93]
	s_barrier
	s_add_i32 s37, s95, s71
	v_lshl_add_u64 v[236:237], s[34:35], 0, v[152:153]
	s_mov_b32 m0, s37
	ds_read_b128 v[220:223], v191
	ds_read_b128 v[224:227], v191 offset:1024
	ds_read_b128 v[228:231], v191 offset:2048
	ds_read_b128 v[232:235], v191 offset:3072
	global_load_lds_dwordx4 v[236:237], off
	v_lshl_add_u64 v[238:239], s[34:35], 0, v[156:157]
	s_add_i32 m0, s37, 0x2000
	s_nop 0
	global_load_lds_dwordx4 v[238:239], off
	s_barrier
	s_waitcnt lgkmcnt(0)
	s_waitcnt lgkmcnt(0)
	v_mfma_f32_16x16x32_bf16 v[134:137], v[220:223], v[166:169], v[134:137]
	v_mfma_f32_16x16x32_bf16 v[130:133], v[228:231], v[166:169], v[130:133]
	v_mfma_f32_16x16x32_bf16 v[118:121], v[220:223], v[196:199], v[118:121]
	v_mfma_f32_16x16x32_bf16 v[114:117], v[228:231], v[196:199], v[114:117]
	v_mfma_f32_16x16x32_bf16 v[102:105], v[220:223], v[204:207], v[102:105]
	v_mfma_f32_16x16x32_bf16 v[98:101], v[228:231], v[204:207], v[98:101]
	v_mfma_f32_16x16x32_bf16 v[70:73], v[220:223], v[212:215], v[70:73]
	v_mfma_f32_16x16x32_bf16 v[66:69], v[228:231], v[212:215], v[66:69]
	v_mfma_f32_16x16x32_bf16 v[134:137], v[224:227], v[192:195], v[134:137]
	v_mfma_f32_16x16x32_bf16 v[130:133], v[232:235], v[192:195], v[130:133]
	v_mfma_f32_16x16x32_bf16 v[118:121], v[224:227], v[200:203], v[118:121]
	v_mfma_f32_16x16x32_bf16 v[114:117], v[232:235], v[200:203], v[114:117]
	v_mfma_f32_16x16x32_bf16 v[102:105], v[224:227], v[208:211], v[102:105]
	v_mfma_f32_16x16x32_bf16 v[98:101], v[232:235], v[208:211], v[98:101]
	v_mfma_f32_16x16x32_bf16 v[70:73], v[224:227], v[216:219], v[70:73]
	v_mfma_f32_16x16x32_bf16 v[66:69], v[232:235], v[216:219], v[66:69]
	s_mov_b32 m0, s65
	v_lshl_add_u64 v[240:241], s[66:67], 0, v[150:151]
	s_barrier
	ds_read_b128 v[166:169], v190 offset:16384
	ds_read_b128 v[192:195], v190 offset:17408
	ds_read_b128 v[196:199], v190 offset:18432
	ds_read_b128 v[200:203], v190 offset:19456
	ds_read_b128 v[204:207], v190 offset:20480
	ds_read_b128 v[208:211], v190 offset:21504
	ds_read_b128 v[212:215], v190 offset:22528
	ds_read_b128 v[216:219], v190 offset:23552
	global_load_lds_dwordx4 v[240:241], off
	v_lshl_add_u64 v[242:243], s[66:67], 0, v[154:155]
	s_mov_b32 m0, s84
	s_nop 0
	global_load_lds_dwordx4 v[242:243], off
	s_barrier
	s_waitcnt lgkmcnt(0)
	s_waitcnt lgkmcnt(0)
	v_mfma_f32_16x16x32_bf16 v[62:65], v[74:77], v[166:169], v[62:65]
	v_mfma_f32_16x16x32_bf16 v[58:61], v[82:85], v[166:169], v[58:61]
	v_mfma_f32_16x16x32_bf16 v[46:49], v[74:77], v[196:199], v[46:49]
	v_mfma_f32_16x16x32_bf16 v[42:45], v[82:85], v[196:199], v[42:45]
	v_mfma_f32_16x16x32_bf16 v[30:33], v[74:77], v[204:207], v[30:33]
	v_mfma_f32_16x16x32_bf16 v[26:29], v[82:85], v[204:207], v[26:29]
	v_mfma_f32_16x16x32_bf16 v[14:17], v[74:77], v[212:215], v[14:17]
	v_mfma_f32_16x16x32_bf16 v[10:13], v[82:85], v[212:215], v[10:13]
	v_mfma_f32_16x16x32_bf16 v[62:65], v[78:81], v[192:195], v[62:65]
	v_mfma_f32_16x16x32_bf16 v[58:61], v[86:89], v[192:195], v[58:61]
	v_mfma_f32_16x16x32_bf16 v[46:49], v[78:81], v[200:203], v[46:49]
	v_mfma_f32_16x16x32_bf16 v[42:45], v[86:89], v[200:203], v[42:45]
	v_mfma_f32_16x16x32_bf16 v[30:33], v[78:81], v[208:211], v[30:33]
	v_mfma_f32_16x16x32_bf16 v[26:29], v[86:89], v[208:211], v[26:29]
	v_mfma_f32_16x16x32_bf16 v[14:17], v[78:81], v[216:219], v[14:17]
	v_mfma_f32_16x16x32_bf16 v[10:13], v[86:89], v[216:219], v[10:13]
	s_barrier
	s_add_u32 s38, s34, 0x40000
	s_addc_u32 s39, s35, 0
	s_add_i32 s37, s96, s71
	v_lshl_add_u64 v[74:75], s[38:39], 0, v[152:153]
	s_mov_b32 m0, s37
	s_nop 0
	global_load_lds_dwordx4 v[74:75], off
	v_lshl_add_u64 v[74:75], s[38:39], 0, v[156:157]
	s_add_i32 m0, s37, 0x2000
	s_nop 0
	global_load_lds_dwordx4 v[74:75], off
	s_waitcnt vmcnt(6)
	s_barrier
	v_mfma_f32_16x16x32_bf16 v[54:57], v[220:223], v[166:169], v[54:57]
	v_mfma_f32_16x16x32_bf16 v[50:53], v[228:231], v[166:169], v[50:53]
	v_mfma_f32_16x16x32_bf16 v[38:41], v[220:223], v[196:199], v[38:41]
	v_mfma_f32_16x16x32_bf16 v[34:37], v[228:231], v[196:199], v[34:37]
	v_mfma_f32_16x16x32_bf16 v[22:25], v[220:223], v[204:207], v[22:25]
	v_mfma_f32_16x16x32_bf16 v[18:21], v[228:231], v[204:207], v[18:21]
	v_mfma_f32_16x16x32_bf16 v[6:9], v[220:223], v[212:215], v[6:9]
	v_mfma_f32_16x16x32_bf16 v[2:5], v[228:231], v[212:215], v[2:5]
	v_mfma_f32_16x16x32_bf16 v[54:57], v[224:227], v[192:195], v[54:57]
	v_mfma_f32_16x16x32_bf16 v[50:53], v[232:235], v[192:195], v[50:53]
	v_mfma_f32_16x16x32_bf16 v[38:41], v[224:227], v[200:203], v[38:41]
	v_mfma_f32_16x16x32_bf16 v[34:37], v[232:235], v[200:203], v[34:37]
	v_mfma_f32_16x16x32_bf16 v[22:25], v[224:227], v[208:211], v[22:25]
	v_mfma_f32_16x16x32_bf16 v[18:21], v[232:235], v[208:211], v[18:21]
	v_mfma_f32_16x16x32_bf16 v[6:9], v[224:227], v[216:219], v[6:9]
	v_mfma_f32_16x16x32_bf16 v[2:5], v[232:235], v[216:219], v[2:5]
	s_add_i32 s37, 0, 0x18000
	v_add_u32_e32 v86, s37, v187
	s_barrier
	ds_read_b128 v[74:77], v86
	ds_read_b128 v[78:81], v86 offset:1024
	ds_read_b128 v[82:85], v86 offset:2048
	ds_read_b128 v[86:89], v86 offset:3072
	s_add_u32 s38, s66, 0x40000
	s_addc_u32 s39, s67, 0
	s_mov_b32 m0, s85
	v_lshl_add_u64 v[220:221], s[38:39], 0, v[150:151]
	ds_read_b128 v[166:169], v190 offset:32768
	ds_read_b128 v[192:195], v190 offset:33792
	ds_read_b128 v[196:199], v190 offset:34816
	ds_read_b128 v[200:203], v190 offset:35840
	ds_read_b128 v[204:207], v190 offset:36864
	ds_read_b128 v[208:211], v190 offset:37888
	ds_read_b128 v[212:215], v190 offset:38912
	ds_read_b128 v[216:219], v190 offset:39936
	global_load_lds_dwordx4 v[220:221], off
	v_lshl_add_u64 v[220:221], s[38:39], 0, v[154:155]
	s_mov_b32 m0, s86
	s_nop 0
	global_load_lds_dwordx4 v[220:221], off
	s_waitcnt lgkmcnt(8)
	s_barrier
	s_waitcnt lgkmcnt(0)
	s_waitcnt lgkmcnt(0)
	v_mfma_f32_16x16x32_bf16 v[142:145], v[74:77], v[166:169], v[142:145]
	v_mfma_f32_16x16x32_bf16 v[138:141], v[82:85], v[166:169], v[138:141]
	v_mfma_f32_16x16x32_bf16 v[126:129], v[74:77], v[196:199], v[126:129]
	v_mfma_f32_16x16x32_bf16 v[122:125], v[82:85], v[196:199], v[122:125]
	v_mfma_f32_16x16x32_bf16 v[110:113], v[74:77], v[204:207], v[110:113]
	v_mfma_f32_16x16x32_bf16 v[106:109], v[82:85], v[204:207], v[106:109]
	v_mfma_f32_16x16x32_bf16 v[94:97], v[74:77], v[212:215], v[94:97]
	v_mfma_f32_16x16x32_bf16 v[90:93], v[82:85], v[212:215], v[90:93]
	v_mfma_f32_16x16x32_bf16 v[142:145], v[78:81], v[192:195], v[142:145]
	v_mfma_f32_16x16x32_bf16 v[138:141], v[86:89], v[192:195], v[138:141]
	v_mfma_f32_16x16x32_bf16 v[126:129], v[78:81], v[200:203], v[126:129]
	v_mfma_f32_16x16x32_bf16 v[122:125], v[86:89], v[200:203], v[122:125]
	v_mfma_f32_16x16x32_bf16 v[110:113], v[78:81], v[208:211], v[110:113]
	v_mfma_f32_16x16x32_bf16 v[106:109], v[86:89], v[208:211], v[106:109]
	v_mfma_f32_16x16x32_bf16 v[94:97], v[78:81], v[216:219], v[94:97]
	v_mfma_f32_16x16x32_bf16 v[90:93], v[86:89], v[216:219], v[90:93]
	s_barrier
	s_add_i32 s38, 0, 0x1c000
	s_add_i32 s37, s37, s71
	v_add_u32_e32 v146, s38, v187
	v_lshl_add_u64 v[236:237], v[236:237], 0, s[6:7]
	s_mov_b32 m0, s37
	ds_read_b128 v[220:223], v146
	ds_read_b128 v[224:227], v146 offset:1024
	ds_read_b128 v[228:231], v146 offset:2048
	ds_read_b128 v[232:235], v146 offset:3072
	global_load_lds_dwordx4 v[236:237], off
	v_lshl_add_u64 v[236:237], v[238:239], 0, s[6:7]
	s_add_i32 m0, s37, 0x2000
	s_nop 0
	global_load_lds_dwordx4 v[236:237], off
	s_barrier
	s_waitcnt lgkmcnt(0)
	s_waitcnt lgkmcnt(0)
	v_mfma_f32_16x16x32_bf16 v[134:137], v[220:223], v[166:169], v[134:137]
	v_mfma_f32_16x16x32_bf16 v[130:133], v[228:231], v[166:169], v[130:133]
	v_mfma_f32_16x16x32_bf16 v[118:121], v[220:223], v[196:199], v[118:121]
	v_mfma_f32_16x16x32_bf16 v[114:117], v[228:231], v[196:199], v[114:117]
	v_mfma_f32_16x16x32_bf16 v[102:105], v[220:223], v[204:207], v[102:105]
	v_mfma_f32_16x16x32_bf16 v[98:101], v[228:231], v[204:207], v[98:101]
	v_mfma_f32_16x16x32_bf16 v[70:73], v[220:223], v[212:215], v[70:73]
	v_mfma_f32_16x16x32_bf16 v[66:69], v[228:231], v[212:215], v[66:69]
	v_mfma_f32_16x16x32_bf16 v[134:137], v[224:227], v[192:195], v[134:137]
	v_mfma_f32_16x16x32_bf16 v[130:133], v[232:235], v[192:195], v[130:133]
	v_mfma_f32_16x16x32_bf16 v[118:121], v[224:227], v[200:203], v[118:121]
	v_mfma_f32_16x16x32_bf16 v[114:117], v[232:235], v[200:203], v[114:117]
	v_mfma_f32_16x16x32_bf16 v[102:105], v[224:227], v[208:211], v[102:105]
	v_mfma_f32_16x16x32_bf16 v[98:101], v[232:235], v[208:211], v[98:101]
	v_mfma_f32_16x16x32_bf16 v[70:73], v[224:227], v[216:219], v[70:73]
	v_mfma_f32_16x16x32_bf16 v[66:69], v[232:235], v[216:219], v[66:69]
	s_mov_b32 m0, s87
	v_lshl_add_u64 v[236:237], v[240:241], 0, s[6:7]
	s_barrier
	ds_read_b128 v[166:169], v190 offset:49152
	ds_read_b128 v[192:195], v190 offset:50176
	ds_read_b128 v[196:199], v190 offset:51200
	ds_read_b128 v[200:203], v190 offset:52224
	ds_read_b128 v[204:207], v190 offset:53248
	ds_read_b128 v[208:211], v190 offset:54272
	ds_read_b128 v[212:215], v190 offset:55296
	ds_read_b128 v[216:219], v190 offset:56320
	global_load_lds_dwordx4 v[236:237], off
	v_lshl_add_u64 v[236:237], v[242:243], 0, s[6:7]
	s_mov_b32 m0, s88
	s_nop 0
	global_load_lds_dwordx4 v[236:237], off
	s_barrier
	s_waitcnt lgkmcnt(0)
	s_waitcnt lgkmcnt(0)
	v_mfma_f32_16x16x32_bf16 v[62:65], v[74:77], v[166:169], v[62:65]
	v_mfma_f32_16x16x32_bf16 v[58:61], v[82:85], v[166:169], v[58:61]
	v_mfma_f32_16x16x32_bf16 v[46:49], v[74:77], v[196:199], v[46:49]
	v_mfma_f32_16x16x32_bf16 v[42:45], v[82:85], v[196:199], v[42:45]
	v_mfma_f32_16x16x32_bf16 v[30:33], v[74:77], v[204:207], v[30:33]
	v_mfma_f32_16x16x32_bf16 v[26:29], v[82:85], v[204:207], v[26:29]
	v_mfma_f32_16x16x32_bf16 v[14:17], v[74:77], v[212:215], v[14:17]
	v_mfma_f32_16x16x32_bf16 v[10:13], v[82:85], v[212:215], v[10:13]
	v_mfma_f32_16x16x32_bf16 v[62:65], v[78:81], v[192:195], v[62:65]
	v_mfma_f32_16x16x32_bf16 v[58:61], v[86:89], v[192:195], v[58:61]
	v_mfma_f32_16x16x32_bf16 v[46:49], v[78:81], v[200:203], v[46:49]
	v_mfma_f32_16x16x32_bf16 v[42:45], v[86:89], v[200:203], v[42:45]
	v_mfma_f32_16x16x32_bf16 v[30:33], v[78:81], v[208:211], v[30:33]
	v_mfma_f32_16x16x32_bf16 v[26:29], v[86:89], v[208:211], v[26:29]
	v_mfma_f32_16x16x32_bf16 v[14:17], v[78:81], v[216:219], v[14:17]
	v_mfma_f32_16x16x32_bf16 v[10:13], v[86:89], v[216:219], v[10:13]
	s_barrier
	s_add_u32 s34, s34, 0x40080
	s_addc_u32 s35, s35, 0
	s_add_i32 s37, s38, s71
	v_lshl_add_u64 v[74:75], s[34:35], 0, v[152:153]
	s_mov_b32 m0, s37
	s_nop 0
	global_load_lds_dwordx4 v[74:75], off
	v_lshl_add_u64 v[74:75], s[34:35], 0, v[156:157]
	s_add_i32 m0, s37, 0x2000
	s_nop 0
	global_load_lds_dwordx4 v[74:75], off
	s_waitcnt vmcnt(6)
	s_barrier
	v_mfma_f32_16x16x32_bf16 v[54:57], v[220:223], v[166:169], v[54:57]
	v_mfma_f32_16x16x32_bf16 v[50:53], v[228:231], v[166:169], v[50:53]
	v_mfma_f32_16x16x32_bf16 v[38:41], v[220:223], v[196:199], v[38:41]
	v_mfma_f32_16x16x32_bf16 v[34:37], v[228:231], v[196:199], v[34:37]
	v_mfma_f32_16x16x32_bf16 v[22:25], v[220:223], v[204:207], v[22:25]
	v_mfma_f32_16x16x32_bf16 v[18:21], v[228:231], v[204:207], v[18:21]
	v_mfma_f32_16x16x32_bf16 v[6:9], v[220:223], v[212:215], v[6:9]
	v_mfma_f32_16x16x32_bf16 v[2:5], v[228:231], v[212:215], v[2:5]
	v_mfma_f32_16x16x32_bf16 v[54:57], v[224:227], v[192:195], v[54:57]
	v_mfma_f32_16x16x32_bf16 v[50:53], v[232:235], v[192:195], v[50:53]
	v_mfma_f32_16x16x32_bf16 v[38:41], v[224:227], v[200:203], v[38:41]
	v_mfma_f32_16x16x32_bf16 v[34:37], v[232:235], v[200:203], v[34:37]
	v_mfma_f32_16x16x32_bf16 v[22:25], v[224:227], v[208:211], v[22:25]
	v_mfma_f32_16x16x32_bf16 v[18:21], v[232:235], v[208:211], v[18:21]
	v_mfma_f32_16x16x32_bf16 v[6:9], v[224:227], v[216:219], v[6:9]
	v_mfma_f32_16x16x32_bf16 v[2:5], v[232:235], v[216:219], v[2:5]
	s_add_i32 s36, s36, 2
	s_add_u32 s4, s4, 0x100
	s_addc_u32 s5, s5, 0
	s_add_u32 s22, s22, 0x100
	s_addc_u32 s23, s23, 0
	s_cmp_gt_u32 s36, 13
	s_barrier
	s_cbranch_scc0 .LBB0_93
	s_ashr_i32 s11, s0, 2
	s_and_b32 s4, s0, -8
	s_cmp_lg_u32 s4, 8
	s_mov_b64 s[4:5], -1
	s_cbranch_scc0 .LBB0_96
	s_mul_hi_i32 s67, s11, 0x2100000
	s_mul_i32 s66, s11, 0x2100000
	s_lshl_b32 s20, s11, 10
	s_mov_b64 s[4:5], 0

.LBB0_658:
	ds_read_b128 v[138:141], v147
	ds_read_b128 v[186:189], v147 offset:1024
	ds_read_b128 v[190:193], v147 offset:2048
	ds_read_b128 v[194:197], v147 offset:3072
	s_add_u32 s46, s48, 0xfffc0080
	s_addc_u32 s47, s49, -1
	s_cmp_eq_u32 s39, 12
	s_cselect_b32 s57, s21, s47
	s_cselect_b32 s56, s22, s46
	s_cselect_b32 s51, s23, s37
	s_cselect_b32 s50, s35, s36
	v_lshl_add_u64 v[142:143], s[48:49], 0, v[130:131]
	s_add_i32 m0, s45, 0xc000
	ds_read_b128 v[198:201], v158
	ds_read_b128 v[202:205], v158 offset:1024
	ds_read_b128 v[206:209], v158 offset:2048
	ds_read_b128 v[210:213], v158 offset:3072
	ds_read_b128 v[214:217], v158 offset:4096
	ds_read_b128 v[218:221], v158 offset:5120
	ds_read_b128 v[222:225], v158 offset:6144
	ds_read_b128 v[226:229], v158 offset:7168
	global_load_lds_dwordx4 v[142:143], off
	v_lshl_add_u64 v[142:143], s[48:49], 0, v[132:133]
	s_add_i32 m0, s45, 0xe000
	s_nop 0
	global_load_lds_dwordx4 v[142:143], off
	s_waitcnt lgkmcnt(8)
	s_barrier
	s_waitcnt lgkmcnt(0)
	s_waitcnt lgkmcnt(0)
	v_mfma_f32_16x16x32_bf16 v[126:129], v[138:141], v[198:201], v[126:129]
	v_mfma_f32_16x16x32_bf16 v[122:125], v[190:193], v[198:201], v[122:125]
	v_mfma_f32_16x16x32_bf16 v[110:113], v[138:141], v[206:209], v[110:113]
	v_mfma_f32_16x16x32_bf16 v[106:109], v[190:193], v[206:209], v[106:109]
	v_mfma_f32_16x16x32_bf16 v[94:97], v[138:141], v[214:217], v[94:97]
	v_mfma_f32_16x16x32_bf16 v[90:93], v[190:193], v[214:217], v[90:93]
	v_mfma_f32_16x16x32_bf16 v[78:81], v[138:141], v[222:225], v[78:81]
	v_mfma_f32_16x16x32_bf16 v[74:77], v[190:193], v[222:225], v[74:77]
	v_mfma_f32_16x16x32_bf16 v[126:129], v[186:189], v[202:205], v[126:129]
	v_mfma_f32_16x16x32_bf16 v[122:125], v[194:197], v[202:205], v[122:125]
	v_mfma_f32_16x16x32_bf16 v[110:113], v[186:189], v[210:213], v[110:113]
	v_mfma_f32_16x16x32_bf16 v[106:109], v[194:197], v[210:213], v[106:109]
	v_mfma_f32_16x16x32_bf16 v[94:97], v[186:189], v[218:221], v[94:97]
	v_mfma_f32_16x16x32_bf16 v[90:93], v[194:197], v[218:221], v[90:93]
	v_mfma_f32_16x16x32_bf16 v[78:81], v[186:189], v[226:229], v[78:81]
	v_mfma_f32_16x16x32_bf16 v[74:77], v[194:197], v[226:229], v[74:77]
	s_barrier
	s_add_i32 s46, s67, s59
	v_lshl_add_u64 v[142:143], s[50:51], 0, v[152:153]
	s_mov_b32 m0, s46
	ds_read_b128 v[230:233], v159
	ds_read_b128 v[234:237], v159 offset:1024
	ds_read_b128 v[238:241], v159 offset:2048
	ds_read_b128 v[242:245], v159 offset:3072
	global_load_lds_dwordx4 v[142:143], off
	v_lshl_add_u64 v[168:169], s[50:51], 0, v[156:157]
	s_add_i32 m0, s46, 0x2000
	s_nop 0
	global_load_lds_dwordx4 v[168:169], off
	s_barrier
	s_waitcnt lgkmcnt(0)
	s_waitcnt lgkmcnt(0)
	v_mfma_f32_16x16x32_bf16 v[118:121], v[230:233], v[198:201], v[118:121]
	v_mfma_f32_16x16x32_bf16 v[114:117], v[238:241], v[198:201], v[114:117]
	v_mfma_f32_16x16x32_bf16 v[102:105], v[230:233], v[206:209], v[102:105]
	v_mfma_f32_16x16x32_bf16 v[98:101], v[238:241], v[206:209], v[98:101]
	v_mfma_f32_16x16x32_bf16 v[86:89], v[230:233], v[214:217], v[86:89]
	v_mfma_f32_16x16x32_bf16 v[82:85], v[238:241], v[214:217], v[82:85]
	v_mfma_f32_16x16x32_bf16 v[70:73], v[230:233], v[222:225], v[70:73]
	v_mfma_f32_16x16x32_bf16 v[66:69], v[238:241], v[222:225], v[66:69]
	v_mfma_f32_16x16x32_bf16 v[118:121], v[234:237], v[202:205], v[118:121]
	v_mfma_f32_16x16x32_bf16 v[114:117], v[242:245], v[202:205], v[114:117]
	v_mfma_f32_16x16x32_bf16 v[102:105], v[234:237], v[210:213], v[102:105]
	v_mfma_f32_16x16x32_bf16 v[98:101], v[242:245], v[210:213], v[98:101]
	v_mfma_f32_16x16x32_bf16 v[86:89], v[234:237], v[218:221], v[86:89]
	v_mfma_f32_16x16x32_bf16 v[82:85], v[242:245], v[218:221], v[82:85]
	v_mfma_f32_16x16x32_bf16 v[70:73], v[234:237], v[226:229], v[70:73]
	v_mfma_f32_16x16x32_bf16 v[66:69], v[242:245], v[226:229], v[66:69]
	s_mov_b32 m0, s45
	v_lshl_add_u64 v[246:247], s[56:57], 0, v[150:151]
	s_barrier
	ds_read_b128 v[198:201], v158 offset:16384
	ds_read_b128 v[202:205], v158 offset:17408
	ds_read_b128 v[206:209], v158 offset:18432
	ds_read_b128 v[210:213], v158 offset:19456
	ds_read_b128 v[214:217], v158 offset:20480
	ds_read_b128 v[218:221], v158 offset:21504
	ds_read_b128 v[222:225], v158 offset:22528
	ds_read_b128 v[226:229], v158 offset:23552
	global_load_lds_dwordx4 v[246:247], off
	v_lshl_add_u64 v[248:249], s[56:57], 0, v[154:155]
	s_mov_b32 m0, s60
	s_nop 0
	global_load_lds_dwordx4 v[248:249], off
	s_barrier
	s_waitcnt lgkmcnt(0)
	s_waitcnt lgkmcnt(0)
	v_mfma_f32_16x16x32_bf16 v[62:65], v[138:141], v[198:201], v[62:65]
	v_mfma_f32_16x16x32_bf16 v[58:61], v[190:193], v[198:201], v[58:61]
	v_mfma_f32_16x16x32_bf16 v[50:53], v[138:141], v[206:209], v[50:53]
	v_mfma_f32_16x16x32_bf16 v[42:45], v[190:193], v[206:209], v[42:45]
	v_mfma_f32_16x16x32_bf16 v[34:37], v[138:141], v[214:217], v[34:37]
	v_mfma_f32_16x16x32_bf16 v[26:29], v[190:193], v[214:217], v[26:29]
	v_mfma_f32_16x16x32_bf16 v[18:21], v[138:141], v[222:225], v[18:21]
	v_mfma_f32_16x16x32_bf16 v[10:13], v[190:193], v[222:225], v[10:13]
	v_mfma_f32_16x16x32_bf16 v[62:65], v[186:189], v[202:205], v[62:65]
	v_mfma_f32_16x16x32_bf16 v[58:61], v[194:197], v[202:205], v[58:61]
	v_mfma_f32_16x16x32_bf16 v[50:53], v[186:189], v[210:213], v[50:53]
	v_mfma_f32_16x16x32_bf16 v[42:45], v[194:197], v[210:213], v[42:45]
	v_mfma_f32_16x16x32_bf16 v[34:37], v[186:189], v[218:221], v[34:37]
	v_mfma_f32_16x16x32_bf16 v[26:29], v[194:197], v[218:221], v[26:29]
	v_mfma_f32_16x16x32_bf16 v[18:21], v[186:189], v[226:229], v[18:21]
	v_mfma_f32_16x16x32_bf16 v[10:13], v[194:197], v[226:229], v[10:13]
	s_barrier
	s_add_u32 s46, s50, 0x40000
	s_addc_u32 s47, s51, 0
	s_add_i32 s69, s68, s59
	v_lshl_add_u64 v[138:139], s[46:47], 0, v[152:153]
	s_mov_b32 m0, s69
	s_nop 0
	global_load_lds_dwordx4 v[138:139], off
	v_lshl_add_u64 v[138:139], s[46:47], 0, v[156:157]
	s_add_i32 m0, s69, 0x2000
	s_nop 0
	global_load_lds_dwordx4 v[138:139], off
	s_waitcnt vmcnt(6)
	s_barrier
	v_mfma_f32_16x16x32_bf16 v[54:57], v[230:233], v[198:201], v[54:57]
	v_mfma_f32_16x16x32_bf16 v[46:49], v[238:241], v[198:201], v[46:49]
	v_mfma_f32_16x16x32_bf16 v[38:41], v[230:233], v[206:209], v[38:41]
	v_mfma_f32_16x16x32_bf16 v[30:33], v[238:241], v[206:209], v[30:33]
	v_mfma_f32_16x16x32_bf16 v[22:25], v[230:233], v[214:217], v[22:25]
	v_mfma_f32_16x16x32_bf16 v[14:17], v[238:241], v[214:217], v[14:17]
	v_mfma_f32_16x16x32_bf16 v[6:9], v[230:233], v[222:225], v[6:9]
	v_mfma_f32_16x16x32_bf16 v[2:5], v[238:241], v[222:225], v[2:5]
	v_mfma_f32_16x16x32_bf16 v[54:57], v[234:237], v[202:205], v[54:57]
	v_mfma_f32_16x16x32_bf16 v[46:49], v[242:245], v[202:205], v[46:49]
	v_mfma_f32_16x16x32_bf16 v[38:41], v[234:237], v[210:213], v[38:41]
	v_mfma_f32_16x16x32_bf16 v[30:33], v[242:245], v[210:213], v[30:33]
	v_mfma_f32_16x16x32_bf16 v[22:25], v[234:237], v[218:221], v[22:25]
	v_mfma_f32_16x16x32_bf16 v[14:17], v[242:245], v[218:221], v[14:17]
	v_mfma_f32_16x16x32_bf16 v[6:9], v[234:237], v[226:229], v[6:9]
	v_mfma_f32_16x16x32_bf16 v[2:5], v[242:245], v[226:229], v[2:5]
	s_add_i32 s69, 0, 0x18000
	v_add_u32_e32 v185, s69, v145
	s_barrier
	ds_read_b128 v[138:141], v185
	ds_read_b128 v[186:189], v185 offset:1024
	ds_read_b128 v[190:193], v185 offset:2048
	ds_read_b128 v[194:197], v185 offset:3072
	s_add_u32 s46, s56, 0x40000
	s_addc_u32 s47, s57, 0
	s_mov_b32 m0, s61
	v_lshl_add_u64 v[230:231], s[46:47], 0, v[150:151]
	ds_read_b128 v[198:201], v158 offset:32768
	ds_read_b128 v[202:205], v158 offset:33792
	ds_read_b128 v[206:209], v158 offset:34816
	ds_read_b128 v[210:213], v158 offset:35840
	ds_read_b128 v[214:217], v158 offset:36864
	ds_read_b128 v[218:221], v158 offset:37888
	ds_read_b128 v[222:225], v158 offset:38912
	ds_read_b128 v[226:229], v158 offset:39936
	global_load_lds_dwordx4 v[230:231], off
	v_lshl_add_u64 v[230:231], s[46:47], 0, v[154:155]
	s_mov_b32 m0, s62
	s_nop 0
	global_load_lds_dwordx4 v[230:231], off
	s_waitcnt lgkmcnt(8)
	s_barrier
	s_waitcnt lgkmcnt(0)
	s_waitcnt lgkmcnt(0)
	v_mfma_f32_16x16x32_bf16 v[126:129], v[138:141], v[198:201], v[126:129]
	v_mfma_f32_16x16x32_bf16 v[122:125], v[190:193], v[198:201], v[122:125]
	v_mfma_f32_16x16x32_bf16 v[110:113], v[138:141], v[206:209], v[110:113]
	v_mfma_f32_16x16x32_bf16 v[106:109], v[190:193], v[206:209], v[106:109]
	v_mfma_f32_16x16x32_bf16 v[94:97], v[138:141], v[214:217], v[94:97]
	v_mfma_f32_16x16x32_bf16 v[90:93], v[190:193], v[214:217], v[90:93]
	v_mfma_f32_16x16x32_bf16 v[78:81], v[138:141], v[222:225], v[78:81]
	v_mfma_f32_16x16x32_bf16 v[74:77], v[190:193], v[222:225], v[74:77]
	v_mfma_f32_16x16x32_bf16 v[126:129], v[186:189], v[202:205], v[126:129]
	v_mfma_f32_16x16x32_bf16 v[122:125], v[194:197], v[202:205], v[122:125]
	v_mfma_f32_16x16x32_bf16 v[110:113], v[186:189], v[210:213], v[110:113]
	v_mfma_f32_16x16x32_bf16 v[106:109], v[194:197], v[210:213], v[106:109]
	v_mfma_f32_16x16x32_bf16 v[94:97], v[186:189], v[218:221], v[94:97]
	v_mfma_f32_16x16x32_bf16 v[90:93], v[194:197], v[218:221], v[90:93]
	v_mfma_f32_16x16x32_bf16 v[78:81], v[186:189], v[226:229], v[78:81]
	v_mfma_f32_16x16x32_bf16 v[74:77], v[194:197], v[226:229], v[74:77]
	s_barrier
	s_add_i32 s56, 0, 0x1c000
	s_add_i32 s46, s69, s59
	v_add_u32_e32 v185, s56, v145
	v_lshl_add_u64 v[142:143], v[142:143], 0, s[6:7]
	s_mov_b32 m0, s46
	ds_read_b128 v[230:233], v185
	ds_read_b128 v[234:237], v185 offset:1024
	ds_read_b128 v[238:241], v185 offset:2048
	ds_read_b128 v[242:245], v185 offset:3072
	global_load_lds_dwordx4 v[142:143], off
	v_lshl_add_u64 v[142:143], v[168:169], 0, s[6:7]
	s_add_i32 m0, s46, 0x2000
	s_nop 0
	global_load_lds_dwordx4 v[142:143], off
	s_barrier
	s_waitcnt lgkmcnt(0)
	s_waitcnt lgkmcnt(0)
	v_mfma_f32_16x16x32_bf16 v[118:121], v[230:233], v[198:201], v[118:121]
	v_mfma_f32_16x16x32_bf16 v[114:117], v[238:241], v[198:201], v[114:117]
	v_mfma_f32_16x16x32_bf16 v[102:105], v[230:233], v[206:209], v[102:105]
	v_mfma_f32_16x16x32_bf16 v[98:101], v[238:241], v[206:209], v[98:101]
	v_mfma_f32_16x16x32_bf16 v[86:89], v[230:233], v[214:217], v[86:89]
	v_mfma_f32_16x16x32_bf16 v[82:85], v[238:241], v[214:217], v[82:85]
	v_mfma_f32_16x16x32_bf16 v[70:73], v[230:233], v[222:225], v[70:73]
	v_mfma_f32_16x16x32_bf16 v[66:69], v[238:241], v[222:225], v[66:69]
	v_mfma_f32_16x16x32_bf16 v[118:121], v[234:237], v[202:205], v[118:121]
	v_mfma_f32_16x16x32_bf16 v[114:117], v[242:245], v[202:205], v[114:117]
	v_mfma_f32_16x16x32_bf16 v[102:105], v[234:237], v[210:213], v[102:105]
	v_mfma_f32_16x16x32_bf16 v[98:101], v[242:245], v[210:213], v[98:101]
	v_mfma_f32_16x16x32_bf16 v[86:89], v[234:237], v[218:221], v[86:89]
	v_mfma_f32_16x16x32_bf16 v[82:85], v[242:245], v[218:221], v[82:85]
	v_mfma_f32_16x16x32_bf16 v[70:73], v[234:237], v[226:229], v[70:73]
	v_mfma_f32_16x16x32_bf16 v[66:69], v[242:245], v[226:229], v[66:69]
	s_mov_b32 m0, s64
	v_lshl_add_u64 v[142:143], v[246:247], 0, s[6:7]
	s_barrier
	ds_read_b128 v[198:201], v158 offset:49152
	ds_read_b128 v[202:205], v158 offset:50176
	ds_read_b128 v[206:209], v158 offset:51200
	ds_read_b128 v[210:213], v158 offset:52224
	ds_read_b128 v[214:217], v158 offset:53248
	ds_read_b128 v[218:221], v158 offset:54272
	ds_read_b128 v[222:225], v158 offset:55296
	ds_read_b128 v[226:229], v158 offset:56320
	global_load_lds_dwordx4 v[142:143], off
	v_lshl_add_u64 v[142:143], v[248:249], 0, s[6:7]
	s_mov_b32 m0, s65
	s_nop 0
	global_load_lds_dwordx4 v[142:143], off
	s_barrier
	s_waitcnt lgkmcnt(0)
	s_waitcnt lgkmcnt(0)
	v_mfma_f32_16x16x32_bf16 v[62:65], v[138:141], v[198:201], v[62:65]
	v_mfma_f32_16x16x32_bf16 v[58:61], v[190:193], v[198:201], v[58:61]
	v_mfma_f32_16x16x32_bf16 v[50:53], v[138:141], v[206:209], v[50:53]
	v_mfma_f32_16x16x32_bf16 v[42:45], v[190:193], v[206:209], v[42:45]
	v_mfma_f32_16x16x32_bf16 v[34:37], v[138:141], v[214:217], v[34:37]
	v_mfma_f32_16x16x32_bf16 v[26:29], v[190:193], v[214:217], v[26:29]
	v_mfma_f32_16x16x32_bf16 v[18:21], v[138:141], v[222:225], v[18:21]
	v_mfma_f32_16x16x32_bf16 v[10:13], v[190:193], v[222:225], v[10:13]
	v_mfma_f32_16x16x32_bf16 v[62:65], v[186:189], v[202:205], v[62:65]
	v_mfma_f32_16x16x32_bf16 v[58:61], v[194:197], v[202:205], v[58:61]
	v_mfma_f32_16x16x32_bf16 v[50:53], v[186:189], v[210:213], v[50:53]
	v_mfma_f32_16x16x32_bf16 v[42:45], v[194:197], v[210:213], v[42:45]
	v_mfma_f32_16x16x32_bf16 v[34:37], v[186:189], v[218:221], v[34:37]
	v_mfma_f32_16x16x32_bf16 v[26:29], v[194:197], v[218:221], v[26:29]
	v_mfma_f32_16x16x32_bf16 v[18:21], v[186:189], v[226:229], v[18:21]
	v_mfma_f32_16x16x32_bf16 v[10:13], v[194:197], v[226:229], v[10:13]
	s_barrier
	s_add_u32 s46, s50, 0x40080
	s_addc_u32 s47, s51, 0
	s_add_i32 s50, s56, s59
	v_lshl_add_u64 v[138:139], s[46:47], 0, v[152:153]
	s_mov_b32 m0, s50
	s_nop 0
	global_load_lds_dwordx4 v[138:139], off
	v_lshl_add_u64 v[138:139], s[46:47], 0, v[156:157]
	s_add_i32 m0, s50, 0x2000
	s_nop 0
	global_load_lds_dwordx4 v[138:139], off
	s_waitcnt vmcnt(6)
	s_barrier
	v_mfma_f32_16x16x32_bf16 v[54:57], v[230:233], v[198:201], v[54:57]
	v_mfma_f32_16x16x32_bf16 v[46:49], v[238:241], v[198:201], v[46:49]
	v_mfma_f32_16x16x32_bf16 v[38:41], v[230:233], v[206:209], v[38:41]
	v_mfma_f32_16x16x32_bf16 v[30:33], v[238:241], v[206:209], v[30:33]
	v_mfma_f32_16x16x32_bf16 v[22:25], v[230:233], v[214:217], v[22:25]
	v_mfma_f32_16x16x32_bf16 v[14:17], v[238:241], v[214:217], v[14:17]
	v_mfma_f32_16x16x32_bf16 v[6:9], v[230:233], v[222:225], v[6:9]
	v_mfma_f32_16x16x32_bf16 v[2:5], v[238:241], v[222:225], v[2:5]
	v_mfma_f32_16x16x32_bf16 v[54:57], v[234:237], v[202:205], v[54:57]
	v_mfma_f32_16x16x32_bf16 v[46:49], v[242:245], v[202:205], v[46:49]
	v_mfma_f32_16x16x32_bf16 v[38:41], v[234:237], v[210:213], v[38:41]
	v_mfma_f32_16x16x32_bf16 v[30:33], v[242:245], v[210:213], v[30:33]
	v_mfma_f32_16x16x32_bf16 v[22:25], v[234:237], v[218:221], v[22:25]
	v_mfma_f32_16x16x32_bf16 v[14:17], v[242:245], v[218:221], v[14:17]
	v_mfma_f32_16x16x32_bf16 v[6:9], v[234:237], v[226:229], v[6:9]
	v_mfma_f32_16x16x32_bf16 v[2:5], v[242:245], v[226:229], v[2:5]
	s_add_i32 s39, s39, 2
	s_add_u32 s48, s48, 0x100
	s_addc_u32 s49, s49, 0
	s_add_u32 s36, s36, 0x100
	s_addc_u32 s37, s37, 0
	s_cmp_gt_u32 s39, 13
	s_barrier
	s_cbranch_scc0 .LBB0_658
	v_lshl_add_u32 v142, s44, 8, v144
	v_lshl_or_b32 v140, s20, 8, v146
	v_ashrrev_i32_e32 v143, 31, v142
	v_ashrrev_i32_e32 v141, 31, v140
	v_lshlrev_b64 v[138:139], 10, v[142:143]
	v_lshl_add_u64 v[138:139], v[138:139], 0, v[140:141]
	v_lshlrev_b64 v[138:139], 1, v[138:139]
	s_and_b64 vcc, exec, s[2:3]
	s_mov_b32 s20, s34
	s_mov_b32 s44, s38
	s_mov_b64 s[50:51], s[42:43]
	s_mov_b64 s[48:49], s[40:41]
	v_mov_b32_e32 v192, v138
	v_add_u32_e32 v193, 0x8000, v138
	v_add_u32_e32 v194, 0x10000, v138
	v_add_u32_e32 v195, 0x18000, v138
	v_add_u32_e32 v196, 0x40000, v138
	v_add_u32_e32 v197, 0x48000, v138
	v_add_u32_e32 v198, 0x50000, v138
	v_add_u32_e32 v199, 0x58000, v138
	global_load_dwordx4 v[200:203], v192, s[4:5]
	global_load_dwordx4 v[204:207], v192, s[4:5] offset:256
	global_load_dwordx4 v[208:211], v193, s[4:5]
	global_load_dwordx4 v[212:215], v193, s[4:5] offset:256
	global_load_dwordx4 v[216:219], v194, s[4:5]
	global_load_dwordx4 v[220:223], v194, s[4:5] offset:256
	global_load_dwordx4 v[224:227], v195, s[4:5]
	global_load_dwordx4 v[228:231], v195, s[4:5] offset:256
	s_waitcnt vmcnt(7)
	v_lshlrev_b32_e32 v143, 16, v200
	v_and_b32_e32 v185, 0xffff0000, v200
	v_lshlrev_b32_e32 v200, 16, v201
	v_and_b32_e32 v201, 0xffff0000, v201
	v_lshlrev_b32_e32 v191, 16, v203
	v_and_b32_e32 v203, 0xffff0000, v203
	v_lshlrev_b32_e32 v190, 16, v202
	v_and_b32_e32 v202, 0xffff0000, v202
	v_mul_f32_e32 v126, v126, v143
	v_mul_f32_e32 v127, v127, v185
	v_mul_f32_e32 v128, v128, v200
	v_mul_f32_e32 v129, v129, v201
	v_mul_f32_e32 v125, v125, v203
	v_mul_f32_e32 v143, v122, v190
	v_mul_f32_e32 v185, v123, v202
	v_mul_f32_e32 v200, v124, v191
	v_cvt_pk_bf16_f32 v122, v126, v127
	v_cvt_pk_bf16_f32 v123, v128, v129
	v_cvt_pk_bf16_f32 v124, v143, v185
	v_cvt_pk_bf16_f32 v125, v200, v125
	global_store_dwordx4 v192, v[122:125], s[18:19]
	s_nop 1
	global_load_dwordx4 v[200:203], v196, s[4:5]
	s_waitcnt vmcnt(8)
	v_lshlrev_b32_e32 v122, 16, v204
	v_and_b32_e32 v123, 0xffff0000, v204
	v_lshlrev_b32_e32 v124, 16, v205
	v_and_b32_e32 v125, 0xffff0000, v205
	v_lshlrev_b32_e32 v204, 16, v206
	v_and_b32_e32 v205, 0xffff0000, v206
	v_lshlrev_b32_e32 v206, 16, v207
	v_and_b32_e32 v207, 0xffff0000, v207
	v_mul_f32_e32 v117, v117, v207
	v_mul_f32_e32 v118, v118, v122
	v_mul_f32_e32 v119, v119, v123
	v_mul_f32_e32 v120, v120, v124
	v_mul_f32_e32 v121, v121, v125
	v_mul_f32_e32 v122, v114, v204
	v_mul_f32_e32 v123, v115, v205
	v_mul_f32_e32 v124, v116, v206
	v_cvt_pk_bf16_f32 v114, v118, v119
	v_cvt_pk_bf16_f32 v115, v120, v121
	v_cvt_pk_bf16_f32 v116, v122, v123
	v_cvt_pk_bf16_f32 v117, v124, v117
	global_store_dwordx4 v192, v[114:117], s[18:19] offset:256
	s_nop 1
	global_load_dwordx4 v[204:207], v196, s[4:5] offset:256
	s_waitcnt vmcnt(9)
	v_lshlrev_b32_e32 v118, 16, v208
	v_and_b32_e32 v208, 0xffff0000, v208
	v_lshlrev_b32_e32 v119, 16, v209
	v_and_b32_e32 v209, 0xffff0000, v209
	v_lshlrev_b32_e32 v121, 16, v211
	v_and_b32_e32 v211, 0xffff0000, v211
	v_lshlrev_b32_e32 v120, 16, v210
	v_and_b32_e32 v210, 0xffff0000, v210
	v_mul_f32_e32 v110, v110, v118
	v_mul_f32_e32 v111, v111, v208
	v_mul_f32_e32 v112, v112, v119
	v_mul_f32_e32 v113, v113, v209
	v_mul_f32_e32 v109, v109, v211
	v_mul_f32_e32 v208, v106, v120
	v_mul_f32_e32 v209, v107, v210
	v_mul_f32_e32 v210, v108, v121
	v_cvt_pk_bf16_f32 v106, v110, v111
	v_cvt_pk_bf16_f32 v107, v112, v113
	v_cvt_pk_bf16_f32 v108, v208, v209
	v_cvt_pk_bf16_f32 v109, v210, v109
	global_store_dwordx4 v193, v[106:109], s[18:19]
	s_nop 1
	global_load_dwordx4 v[208:211], v197, s[4:5]
	s_waitcnt vmcnt(10)
	v_lshlrev_b32_e32 v106, 16, v212
	v_and_b32_e32 v107, 0xffff0000, v212
	v_lshlrev_b32_e32 v108, 16, v213
	v_and_b32_e32 v109, 0xffff0000, v213
	v_lshlrev_b32_e32 v212, 16, v214
	v_and_b32_e32 v213, 0xffff0000, v214
	v_lshlrev_b32_e32 v214, 16, v215
	v_and_b32_e32 v215, 0xffff0000, v215
	v_mul_f32_e32 v101, v101, v215
	v_mul_f32_e32 v102, v102, v106
	v_mul_f32_e32 v103, v103, v107
	v_mul_f32_e32 v104, v104, v108
	v_mul_f32_e32 v105, v105, v109
	v_mul_f32_e32 v106, v98, v212
	v_mul_f32_e32 v107, v99, v213
	v_mul_f32_e32 v108, v100, v214
	v_cvt_pk_bf16_f32 v98, v102, v103
	v_cvt_pk_bf16_f32 v99, v104, v105
	v_cvt_pk_bf16_f32 v100, v106, v107
	v_cvt_pk_bf16_f32 v101, v108, v101
	global_store_dwordx4 v193, v[98:101], s[18:19] offset:256
	s_nop 1
	global_load_dwordx4 v[212:215], v197, s[4:5] offset:256
	s_waitcnt vmcnt(11)
	v_lshlrev_b32_e32 v102, 16, v216
	v_and_b32_e32 v216, 0xffff0000, v216
	v_lshlrev_b32_e32 v103, 16, v217
	v_and_b32_e32 v217, 0xffff0000, v217
	v_lshlrev_b32_e32 v105, 16, v219
	v_and_b32_e32 v219, 0xffff0000, v219
	v_lshlrev_b32_e32 v104, 16, v218
	v_and_b32_e32 v218, 0xffff0000, v218
	v_mul_f32_e32 v94, v94, v102
	v_mul_f32_e32 v95, v95, v216
	v_mul_f32_e32 v96, v96, v103
	v_mul_f32_e32 v97, v97, v217
	v_mul_f32_e32 v93, v93, v219
	v_mul_f32_e32 v216, v90, v104
	v_mul_f32_e32 v217, v91, v218
	v_mul_f32_e32 v218, v92, v105
	v_cvt_pk_bf16_f32 v90, v94, v95
	v_cvt_pk_bf16_f32 v91, v96, v97
	v_cvt_pk_bf16_f32 v92, v216, v217
	v_cvt_pk_bf16_f32 v93, v218, v93
	global_store_dwordx4 v194, v[90:93], s[18:19]
	s_nop 1
	global_load_dwordx4 v[216:219], v198, s[4:5]
	s_waitcnt vmcnt(12)
	v_lshlrev_b32_e32 v90, 16, v220
	v_and_b32_e32 v91, 0xffff0000, v220
	v_lshlrev_b32_e32 v92, 16, v221
	v_and_b32_e32 v93, 0xffff0000, v221
	v_lshlrev_b32_e32 v220, 16, v222
	v_and_b32_e32 v221, 0xffff0000, v222
	v_lshlrev_b32_e32 v222, 16, v223
	v_and_b32_e32 v223, 0xffff0000, v223
	v_mul_f32_e32 v85, v85, v223
	v_mul_f32_e32 v86, v86, v90
	v_mul_f32_e32 v87, v87, v91
	v_mul_f32_e32 v88, v88, v92
	v_mul_f32_e32 v89, v89, v93
	v_mul_f32_e32 v90, v82, v220
	v_mul_f32_e32 v91, v83, v221
	v_mul_f32_e32 v92, v84, v222
	v_cvt_pk_bf16_f32 v82, v86, v87
	v_cvt_pk_bf16_f32 v83, v88, v89
	v_cvt_pk_bf16_f32 v84, v90, v91
	v_cvt_pk_bf16_f32 v85, v92, v85
	global_store_dwordx4 v194, v[82:85], s[18:19] offset:256
	s_nop 1
	global_load_dwordx4 v[220:223], v198, s[4:5] offset:256
	s_waitcnt vmcnt(13)
	v_lshlrev_b32_e32 v86, 16, v224
	v_and_b32_e32 v224, 0xffff0000, v224
	v_lshlrev_b32_e32 v87, 16, v225
	v_and_b32_e32 v225, 0xffff0000, v225
	v_lshlrev_b32_e32 v89, 16, v227
	v_and_b32_e32 v227, 0xffff0000, v227
	v_lshlrev_b32_e32 v88, 16, v226
	v_and_b32_e32 v226, 0xffff0000, v226
	v_mul_f32_e32 v78, v78, v86
	v_mul_f32_e32 v79, v79, v224
	v_mul_f32_e32 v80, v80, v87
	v_mul_f32_e32 v81, v81, v225
	v_mul_f32_e32 v77, v77, v227
	v_mul_f32_e32 v224, v74, v88
	v_mul_f32_e32 v225, v75, v226
	v_mul_f32_e32 v226, v76, v89
	v_cvt_pk_bf16_f32 v74, v78, v79
	v_cvt_pk_bf16_f32 v75, v80, v81
	v_cvt_pk_bf16_f32 v76, v224, v225
	v_cvt_pk_bf16_f32 v77, v226, v77
	global_store_dwordx4 v195, v[74:77], s[18:19]
	s_nop 1
	global_load_dwordx4 v[224:227], v199, s[4:5]
	s_waitcnt vmcnt(14)
	v_lshlrev_b32_e32 v74, 16, v228
	v_and_b32_e32 v75, 0xffff0000, v228
	v_lshlrev_b32_e32 v76, 16, v229
	v_and_b32_e32 v77, 0xffff0000, v229
	v_lshlrev_b32_e32 v228, 16, v230
	v_and_b32_e32 v229, 0xffff0000, v230
	v_lshlrev_b32_e32 v230, 16, v231
	v_and_b32_e32 v231, 0xffff0000, v231
	v_mul_f32_e32 v69, v69, v231
	v_mul_f32_e32 v70, v70, v74
	v_mul_f32_e32 v71, v71, v75
	v_mul_f32_e32 v72, v72, v76
	v_mul_f32_e32 v73, v73, v77
	v_mul_f32_e32 v74, v66, v228
	v_mul_f32_e32 v75, v67, v229
	v_mul_f32_e32 v76, v68, v230
	v_cvt_pk_bf16_f32 v66, v70, v71
	v_cvt_pk_bf16_f32 v67, v72, v73
	v_cvt_pk_bf16_f32 v68, v74, v75
	v_cvt_pk_bf16_f32 v69, v76, v69
	global_store_dwordx4 v195, v[66:69], s[18:19] offset:256
	s_nop 1
	global_load_dwordx4 v[228:231], v199, s[4:5] offset:256
	s_waitcnt vmcnt(14)
	v_lshlrev_b32_e32 v70, 16, v200
	v_and_b32_e32 v200, 0xffff0000, v200
	v_lshlrev_b32_e32 v71, 16, v201
	v_and_b32_e32 v201, 0xffff0000, v201
	v_lshlrev_b32_e32 v73, 16, v203
	v_and_b32_e32 v203, 0xffff0000, v203
	v_lshlrev_b32_e32 v72, 16, v202
	v_and_b32_e32 v202, 0xffff0000, v202
	v_mul_f32_e32 v62, v62, v70
	v_mul_f32_e32 v63, v63, v200
	v_mul_f32_e32 v64, v64, v71
	v_mul_f32_e32 v65, v65, v201
	v_mul_f32_e32 v61, v61, v203
	v_mul_f32_e32 v200, v58, v72
	v_mul_f32_e32 v201, v59, v202
	v_mul_f32_e32 v202, v60, v73
	v_cvt_pk_bf16_f32 v58, v62, v63
	v_cvt_pk_bf16_f32 v59, v64, v65
	v_cvt_pk_bf16_f32 v60, v200, v201
	v_cvt_pk_bf16_f32 v61, v202, v61
	global_store_dwordx4 v196, v[58:61], s[18:19]
	s_nop 1
	s_waitcnt vmcnt(13)
	v_lshlrev_b32_e32 v58, 16, v204
	v_and_b32_e32 v59, 0xffff0000, v204
	v_lshlrev_b32_e32 v60, 16, v205
	v_and_b32_e32 v61, 0xffff0000, v205
	v_lshlrev_b32_e32 v204, 16, v206
	v_and_b32_e32 v205, 0xffff0000, v206
	v_lshlrev_b32_e32 v206, 16, v207
	v_and_b32_e32 v207, 0xffff0000, v207
	v_mul_f32_e32 v49, v49, v207
	v_mul_f32_e32 v54, v54, v58
	v_mul_f32_e32 v55, v55, v59
	v_mul_f32_e32 v56, v56, v60
	v_mul_f32_e32 v57, v57, v61
	v_mul_f32_e32 v58, v46, v204
	v_mul_f32_e32 v59, v47, v205
	v_mul_f32_e32 v60, v48, v206
	v_cvt_pk_bf16_f32 v46, v54, v55
	v_cvt_pk_bf16_f32 v47, v56, v57
	v_cvt_pk_bf16_f32 v48, v58, v59
	v_cvt_pk_bf16_f32 v49, v60, v49
	global_store_dwordx4 v196, v[46:49], s[18:19] offset:256
	s_nop 1
	s_waitcnt vmcnt(12)
	v_lshlrev_b32_e32 v54, 16, v208
	v_and_b32_e32 v208, 0xffff0000, v208
	v_lshlrev_b32_e32 v55, 16, v209
	v_and_b32_e32 v209, 0xffff0000, v209
	v_lshlrev_b32_e32 v56, 16, v210
	v_and_b32_e32 v210, 0xffff0000, v210
	v_lshlrev_b32_e32 v57, 16, v211
	v_and_b32_e32 v211, 0xffff0000, v211
	v_mul_f32_e32 v208, v51, v208
	v_mul_f32_e32 v209, v53, v209
	v_mul_f32_e32 v210, v43, v210
	v_mul_f32_e32 v45, v45, v211
	v_mul_f32_e32 v50, v50, v54
	v_mul_f32_e32 v51, v52, v55
	v_mul_f32_e32 v52, v42, v56
	v_mul_f32_e32 v53, v44, v57
	v_cvt_pk_bf16_f32 v42, v50, v208
	v_cvt_pk_bf16_f32 v43, v51, v209
	v_cvt_pk_bf16_f32 v44, v52, v210
	v_cvt_pk_bf16_f32 v45, v53, v45
	global_store_dwordx4 v197, v[42:45], s[18:19]
	s_nop 1
	s_waitcnt vmcnt(11)
	v_lshlrev_b32_e32 v42, 16, v212
	v_and_b32_e32 v43, 0xffff0000, v212
	v_lshlrev_b32_e32 v44, 16, v213
	v_and_b32_e32 v45, 0xffff0000, v213
	v_lshlrev_b32_e32 v212, 16, v214
	v_and_b32_e32 v213, 0xffff0000, v214
	v_lshlrev_b32_e32 v214, 16, v215
	v_and_b32_e32 v215, 0xffff0000, v215
	v_mul_f32_e32 v33, v33, v215
	v_mul_f32_e32 v38, v38, v42
	v_mul_f32_e32 v39, v39, v43
	v_mul_f32_e32 v40, v40, v44
	v_mul_f32_e32 v41, v41, v45
	v_mul_f32_e32 v42, v30, v212
	v_mul_f32_e32 v43, v31, v213
	v_mul_f32_e32 v44, v32, v214
	v_cvt_pk_bf16_f32 v30, v38, v39
	v_cvt_pk_bf16_f32 v31, v40, v41
	v_cvt_pk_bf16_f32 v32, v42, v43
	v_cvt_pk_bf16_f32 v33, v44, v33
	global_store_dwordx4 v197, v[30:33], s[18:19] offset:256
	s_nop 1
	s_waitcnt vmcnt(10)
	v_lshlrev_b32_e32 v38, 16, v216
	v_and_b32_e32 v216, 0xffff0000, v216
	v_lshlrev_b32_e32 v39, 16, v217
	v_and_b32_e32 v217, 0xffff0000, v217
	v_lshlrev_b32_e32 v40, 16, v218
	v_and_b32_e32 v218, 0xffff0000, v218
	v_lshlrev_b32_e32 v41, 16, v219
	v_and_b32_e32 v219, 0xffff0000, v219
	v_mul_f32_e32 v216, v35, v216
	v_mul_f32_e32 v217, v37, v217
	v_mul_f32_e32 v218, v27, v218
	v_mul_f32_e32 v29, v29, v219
	v_mul_f32_e32 v34, v34, v38
	v_mul_f32_e32 v35, v36, v39
	v_mul_f32_e32 v36, v26, v40
	v_mul_f32_e32 v37, v28, v41
	v_cvt_pk_bf16_f32 v26, v34, v216
	v_cvt_pk_bf16_f32 v27, v35, v217
	v_cvt_pk_bf16_f32 v28, v36, v218
	v_cvt_pk_bf16_f32 v29, v37, v29
	global_store_dwordx4 v198, v[26:29], s[18:19]
	s_nop 1
	s_waitcnt vmcnt(9)
	v_lshlrev_b32_e32 v26, 16, v220
	v_and_b32_e32 v27, 0xffff0000, v220
	v_lshlrev_b32_e32 v28, 16, v221
	v_and_b32_e32 v29, 0xffff0000, v221
	v_lshlrev_b32_e32 v220, 16, v222
	v_and_b32_e32 v221, 0xffff0000, v222
	v_lshlrev_b32_e32 v222, 16, v223
	v_and_b32_e32 v223, 0xffff0000, v223
	v_mul_f32_e32 v17, v17, v223
	v_mul_f32_e32 v22, v22, v26
	v_mul_f32_e32 v23, v23, v27
	v_mul_f32_e32 v24, v24, v28
	v_mul_f32_e32 v25, v25, v29
	v_mul_f32_e32 v26, v14, v220
	v_mul_f32_e32 v27, v15, v221
	v_mul_f32_e32 v28, v16, v222
	v_cvt_pk_bf16_f32 v14, v22, v23
	v_cvt_pk_bf16_f32 v15, v24, v25
	v_cvt_pk_bf16_f32 v16, v26, v27
	v_cvt_pk_bf16_f32 v17, v28, v17
	global_store_dwordx4 v198, v[14:17], s[18:19] offset:256
	s_nop 1
	s_waitcnt vmcnt(8)
	v_lshlrev_b32_e32 v22, 16, v224
	v_and_b32_e32 v224, 0xffff0000, v224
	v_lshlrev_b32_e32 v23, 16, v225
	v_and_b32_e32 v225, 0xffff0000, v225
	v_lshlrev_b32_e32 v24, 16, v226
	v_and_b32_e32 v226, 0xffff0000, v226
	v_lshlrev_b32_e32 v25, 16, v227
	v_and_b32_e32 v227, 0xffff0000, v227
	v_mul_f32_e32 v224, v19, v224
	v_mul_f32_e32 v225, v21, v225
	v_mul_f32_e32 v226, v11, v226
	v_mul_f32_e32 v13, v13, v227
	v_mul_f32_e32 v18, v18, v22
	v_mul_f32_e32 v19, v20, v23
	v_mul_f32_e32 v20, v10, v24
	v_mul_f32_e32 v21, v12, v25
	v_cvt_pk_bf16_f32 v10, v18, v224
	v_cvt_pk_bf16_f32 v11, v19, v225
	v_cvt_pk_bf16_f32 v12, v20, v226
	v_cvt_pk_bf16_f32 v13, v21, v13
	global_store_dwordx4 v199, v[10:13], s[18:19]
	s_nop 1
	s_waitcnt vmcnt(7)
	v_lshlrev_b32_e32 v10, 16, v228
	v_and_b32_e32 v11, 0xffff0000, v228
	v_lshlrev_b32_e32 v12, 16, v229
	v_and_b32_e32 v13, 0xffff0000, v229
	v_lshlrev_b32_e32 v228, 16, v230
	v_and_b32_e32 v229, 0xffff0000, v230
	v_lshlrev_b32_e32 v230, 16, v231
	v_and_b32_e32 v231, 0xffff0000, v231
	v_mul_f32_e32 v5, v5, v231
	v_mul_f32_e32 v6, v6, v10
	v_mul_f32_e32 v7, v7, v11
	v_mul_f32_e32 v8, v8, v12
	v_mul_f32_e32 v9, v9, v13
	v_mul_f32_e32 v10, v2, v228
	v_mul_f32_e32 v11, v3, v229
	v_mul_f32_e32 v12, v4, v230
	v_cvt_pk_bf16_f32 v2, v6, v7
	v_cvt_pk_bf16_f32 v3, v8, v9
	v_cvt_pk_bf16_f32 v4, v10, v11
	v_cvt_pk_bf16_f32 v5, v12, v5
	global_store_dwordx4 v199, v[2:5], s[18:19] offset:256
	s_nop 1
	s_cbranch_vccz .LBB0_651
	s_waitcnt vmcnt(0)
	s_cmpk_gt_u32 s25, 0xff
	s_cbranch_scc1 .LBB0_662
	s_barrier

.LBB0_690:
	ds_read_b128 v[138:141], v147
	ds_read_b128 v[186:189], v147 offset:1024
	ds_read_b128 v[190:193], v147 offset:2048
	ds_read_b128 v[194:197], v147 offset:3072
	s_add_u32 s48, s44, 0xfffc0080
	s_addc_u32 s49, s45, -1
	s_cmp_eq_u32 s47, 12
	s_cselect_b32 s51, s21, s49
	s_cselect_b32 s50, s22, s48
	s_cselect_b32 s49, s23, s46
	s_cselect_b32 s48, s35, s37
	v_lshl_add_u64 v[142:143], s[44:45], 0, v[130:131]
	s_add_i32 m0, s43, 0xc000
	ds_read_b128 v[198:201], v158
	ds_read_b128 v[202:205], v158 offset:1024
	ds_read_b128 v[206:209], v158 offset:2048
	ds_read_b128 v[210:213], v158 offset:3072
	ds_read_b128 v[214:217], v158 offset:4096
	ds_read_b128 v[218:221], v158 offset:5120
	ds_read_b128 v[222:225], v158 offset:6144
	ds_read_b128 v[226:229], v158 offset:7168
	global_load_lds_dwordx4 v[142:143], off
	v_lshl_add_u64 v[142:143], s[44:45], 0, v[132:133]
	s_add_i32 m0, s43, 0xe000
	s_nop 0
	global_load_lds_dwordx4 v[142:143], off
	s_waitcnt lgkmcnt(8)
	s_barrier
	s_waitcnt lgkmcnt(0)
	s_waitcnt lgkmcnt(0)
	v_mfma_f32_16x16x32_bf16 v[126:129], v[138:141], v[198:201], v[126:129]
	v_mfma_f32_16x16x32_bf16 v[122:125], v[190:193], v[198:201], v[122:125]
	v_mfma_f32_16x16x32_bf16 v[110:113], v[138:141], v[206:209], v[110:113]
	v_mfma_f32_16x16x32_bf16 v[106:109], v[190:193], v[206:209], v[106:109]
	v_mfma_f32_16x16x32_bf16 v[94:97], v[138:141], v[214:217], v[94:97]
	v_mfma_f32_16x16x32_bf16 v[90:93], v[190:193], v[214:217], v[90:93]
	v_mfma_f32_16x16x32_bf16 v[78:81], v[138:141], v[222:225], v[78:81]
	v_mfma_f32_16x16x32_bf16 v[74:77], v[190:193], v[222:225], v[74:77]
	v_mfma_f32_16x16x32_bf16 v[126:129], v[186:189], v[202:205], v[126:129]
	v_mfma_f32_16x16x32_bf16 v[122:125], v[194:197], v[202:205], v[122:125]
	v_mfma_f32_16x16x32_bf16 v[110:113], v[186:189], v[210:213], v[110:113]
	v_mfma_f32_16x16x32_bf16 v[106:109], v[194:197], v[210:213], v[106:109]
	v_mfma_f32_16x16x32_bf16 v[94:97], v[186:189], v[218:221], v[94:97]
	v_mfma_f32_16x16x32_bf16 v[90:93], v[194:197], v[218:221], v[90:93]
	v_mfma_f32_16x16x32_bf16 v[78:81], v[186:189], v[226:229], v[78:81]
	v_mfma_f32_16x16x32_bf16 v[74:77], v[194:197], v[226:229], v[74:77]
	s_barrier
	s_add_i32 s67, s65, s57
	v_lshl_add_u64 v[142:143], s[48:49], 0, v[152:153]
	s_mov_b32 m0, s67
	ds_read_b128 v[230:233], v159
	ds_read_b128 v[234:237], v159 offset:1024
	ds_read_b128 v[238:241], v159 offset:2048
	ds_read_b128 v[242:245], v159 offset:3072
	global_load_lds_dwordx4 v[142:143], off
	v_lshl_add_u64 v[168:169], s[48:49], 0, v[156:157]
	s_add_i32 m0, s67, 0x2000
	s_nop 0
	global_load_lds_dwordx4 v[168:169], off
	s_barrier
	s_waitcnt lgkmcnt(0)
	s_waitcnt lgkmcnt(0)
	v_mfma_f32_16x16x32_bf16 v[118:121], v[230:233], v[198:201], v[118:121]
	v_mfma_f32_16x16x32_bf16 v[114:117], v[238:241], v[198:201], v[114:117]
	v_mfma_f32_16x16x32_bf16 v[102:105], v[230:233], v[206:209], v[102:105]
	v_mfma_f32_16x16x32_bf16 v[98:101], v[238:241], v[206:209], v[98:101]
	v_mfma_f32_16x16x32_bf16 v[86:89], v[230:233], v[214:217], v[86:89]
	v_mfma_f32_16x16x32_bf16 v[82:85], v[238:241], v[214:217], v[82:85]
	v_mfma_f32_16x16x32_bf16 v[70:73], v[230:233], v[222:225], v[70:73]
	v_mfma_f32_16x16x32_bf16 v[66:69], v[238:241], v[222:225], v[66:69]
	v_mfma_f32_16x16x32_bf16 v[118:121], v[234:237], v[202:205], v[118:121]
	v_mfma_f32_16x16x32_bf16 v[114:117], v[242:245], v[202:205], v[114:117]
	v_mfma_f32_16x16x32_bf16 v[102:105], v[234:237], v[210:213], v[102:105]
	v_mfma_f32_16x16x32_bf16 v[98:101], v[242:245], v[210:213], v[98:101]
	v_mfma_f32_16x16x32_bf16 v[86:89], v[234:237], v[218:221], v[86:89]
	v_mfma_f32_16x16x32_bf16 v[82:85], v[242:245], v[218:221], v[82:85]
	v_mfma_f32_16x16x32_bf16 v[70:73], v[234:237], v[226:229], v[70:73]
	v_mfma_f32_16x16x32_bf16 v[66:69], v[242:245], v[226:229], v[66:69]
	s_mov_b32 m0, s43
	v_lshl_add_u64 v[246:247], s[50:51], 0, v[150:151]
	s_barrier
	ds_read_b128 v[198:201], v158 offset:16384
	ds_read_b128 v[202:205], v158 offset:17408
	ds_read_b128 v[206:209], v158 offset:18432
	ds_read_b128 v[210:213], v158 offset:19456
	ds_read_b128 v[214:217], v158 offset:20480
	ds_read_b128 v[218:221], v158 offset:21504
	ds_read_b128 v[222:225], v158 offset:22528
	ds_read_b128 v[226:229], v158 offset:23552
	global_load_lds_dwordx4 v[246:247], off
	v_lshl_add_u64 v[248:249], s[50:51], 0, v[154:155]
	s_mov_b32 m0, s58
	s_nop 0
	global_load_lds_dwordx4 v[248:249], off
	s_barrier
	s_waitcnt lgkmcnt(0)
	s_waitcnt lgkmcnt(0)
	v_mfma_f32_16x16x32_bf16 v[62:65], v[138:141], v[198:201], v[62:65]
	v_mfma_f32_16x16x32_bf16 v[58:61], v[190:193], v[198:201], v[58:61]
	v_mfma_f32_16x16x32_bf16 v[50:53], v[138:141], v[206:209], v[50:53]
	v_mfma_f32_16x16x32_bf16 v[42:45], v[190:193], v[206:209], v[42:45]
	v_mfma_f32_16x16x32_bf16 v[34:37], v[138:141], v[214:217], v[34:37]
	v_mfma_f32_16x16x32_bf16 v[26:29], v[190:193], v[214:217], v[26:29]
	v_mfma_f32_16x16x32_bf16 v[18:21], v[138:141], v[222:225], v[18:21]
	v_mfma_f32_16x16x32_bf16 v[10:13], v[190:193], v[222:225], v[10:13]
	v_mfma_f32_16x16x32_bf16 v[62:65], v[186:189], v[202:205], v[62:65]
	v_mfma_f32_16x16x32_bf16 v[58:61], v[194:197], v[202:205], v[58:61]
	v_mfma_f32_16x16x32_bf16 v[50:53], v[186:189], v[210:213], v[50:53]
	v_mfma_f32_16x16x32_bf16 v[42:45], v[194:197], v[210:213], v[42:45]
	v_mfma_f32_16x16x32_bf16 v[34:37], v[186:189], v[218:221], v[34:37]
	v_mfma_f32_16x16x32_bf16 v[26:29], v[194:197], v[218:221], v[26:29]
	v_mfma_f32_16x16x32_bf16 v[18:21], v[186:189], v[226:229], v[18:21]
	v_mfma_f32_16x16x32_bf16 v[10:13], v[194:197], v[226:229], v[10:13]
	s_barrier
	s_add_u32 s68, s48, 0x40000
	s_addc_u32 s69, s49, 0
	s_add_i32 s67, s66, s57
	v_lshl_add_u64 v[138:139], s[68:69], 0, v[152:153]
	s_mov_b32 m0, s67
	s_nop 0
	global_load_lds_dwordx4 v[138:139], off
	v_lshl_add_u64 v[138:139], s[68:69], 0, v[156:157]
	s_add_i32 m0, s67, 0x2000
	s_nop 0
	global_load_lds_dwordx4 v[138:139], off
	s_waitcnt vmcnt(6)
	s_barrier
	v_mfma_f32_16x16x32_bf16 v[54:57], v[230:233], v[198:201], v[54:57]
	v_mfma_f32_16x16x32_bf16 v[46:49], v[238:241], v[198:201], v[46:49]
	v_mfma_f32_16x16x32_bf16 v[38:41], v[230:233], v[206:209], v[38:41]
	v_mfma_f32_16x16x32_bf16 v[30:33], v[238:241], v[206:209], v[30:33]
	v_mfma_f32_16x16x32_bf16 v[22:25], v[230:233], v[214:217], v[22:25]
	v_mfma_f32_16x16x32_bf16 v[14:17], v[238:241], v[214:217], v[14:17]
	v_mfma_f32_16x16x32_bf16 v[6:9], v[230:233], v[222:225], v[6:9]
	v_mfma_f32_16x16x32_bf16 v[2:5], v[238:241], v[222:225], v[2:5]
	v_mfma_f32_16x16x32_bf16 v[54:57], v[234:237], v[202:205], v[54:57]
	v_mfma_f32_16x16x32_bf16 v[46:49], v[242:245], v[202:205], v[46:49]
	v_mfma_f32_16x16x32_bf16 v[38:41], v[234:237], v[210:213], v[38:41]
	v_mfma_f32_16x16x32_bf16 v[30:33], v[242:245], v[210:213], v[30:33]
	v_mfma_f32_16x16x32_bf16 v[22:25], v[234:237], v[218:221], v[22:25]
	v_mfma_f32_16x16x32_bf16 v[14:17], v[242:245], v[218:221], v[14:17]
	v_mfma_f32_16x16x32_bf16 v[6:9], v[234:237], v[226:229], v[6:9]
	v_mfma_f32_16x16x32_bf16 v[2:5], v[242:245], v[226:229], v[2:5]
	s_add_i32 s67, 0, 0x18000
	v_add_u32_e32 v185, s67, v145
	s_barrier
	ds_read_b128 v[138:141], v185
	ds_read_b128 v[186:189], v185 offset:1024
	ds_read_b128 v[190:193], v185 offset:2048
	ds_read_b128 v[194:197], v185 offset:3072
	s_add_u32 s50, s50, 0x40000
	s_addc_u32 s51, s51, 0
	s_mov_b32 m0, s59
	v_lshl_add_u64 v[230:231], s[50:51], 0, v[150:151]
	ds_read_b128 v[198:201], v158 offset:32768
	ds_read_b128 v[202:205], v158 offset:33792
	ds_read_b128 v[206:209], v158 offset:34816
	ds_read_b128 v[210:213], v158 offset:35840
	ds_read_b128 v[214:217], v158 offset:36864
	ds_read_b128 v[218:221], v158 offset:37888
	ds_read_b128 v[222:225], v158 offset:38912
	ds_read_b128 v[226:229], v158 offset:39936
	global_load_lds_dwordx4 v[230:231], off
	v_lshl_add_u64 v[230:231], s[50:51], 0, v[154:155]
	s_mov_b32 m0, s60
	s_nop 0
	global_load_lds_dwordx4 v[230:231], off
	s_waitcnt lgkmcnt(8)
	s_barrier
	s_waitcnt lgkmcnt(0)
	s_waitcnt lgkmcnt(0)
	v_mfma_f32_16x16x32_bf16 v[126:129], v[138:141], v[198:201], v[126:129]
	v_mfma_f32_16x16x32_bf16 v[122:125], v[190:193], v[198:201], v[122:125]
	v_mfma_f32_16x16x32_bf16 v[110:113], v[138:141], v[206:209], v[110:113]
	v_mfma_f32_16x16x32_bf16 v[106:109], v[190:193], v[206:209], v[106:109]
	v_mfma_f32_16x16x32_bf16 v[94:97], v[138:141], v[214:217], v[94:97]
	v_mfma_f32_16x16x32_bf16 v[90:93], v[190:193], v[214:217], v[90:93]
	v_mfma_f32_16x16x32_bf16 v[78:81], v[138:141], v[222:225], v[78:81]
	v_mfma_f32_16x16x32_bf16 v[74:77], v[190:193], v[222:225], v[74:77]
	v_mfma_f32_16x16x32_bf16 v[126:129], v[186:189], v[202:205], v[126:129]
	v_mfma_f32_16x16x32_bf16 v[122:125], v[194:197], v[202:205], v[122:125]
	v_mfma_f32_16x16x32_bf16 v[110:113], v[186:189], v[210:213], v[110:113]
	v_mfma_f32_16x16x32_bf16 v[106:109], v[194:197], v[210:213], v[106:109]
	v_mfma_f32_16x16x32_bf16 v[94:97], v[186:189], v[218:221], v[94:97]
	v_mfma_f32_16x16x32_bf16 v[90:93], v[194:197], v[218:221], v[90:93]
	v_mfma_f32_16x16x32_bf16 v[78:81], v[186:189], v[226:229], v[78:81]
	v_mfma_f32_16x16x32_bf16 v[74:77], v[194:197], v[226:229], v[74:77]
	s_barrier
	s_add_i32 s50, 0, 0x1c000
	s_add_i32 s51, s67, s57
	v_add_u32_e32 v185, s50, v145
	v_lshl_add_u64 v[142:143], v[142:143], 0, s[6:7]
	s_mov_b32 m0, s51
	ds_read_b128 v[230:233], v185
	ds_read_b128 v[234:237], v185 offset:1024
	ds_read_b128 v[238:241], v185 offset:2048
	ds_read_b128 v[242:245], v185 offset:3072
	global_load_lds_dwordx4 v[142:143], off
	v_lshl_add_u64 v[142:143], v[168:169], 0, s[6:7]
	s_add_i32 m0, s51, 0x2000
	s_nop 0
	global_load_lds_dwordx4 v[142:143], off
	s_barrier
	s_waitcnt lgkmcnt(0)
	s_waitcnt lgkmcnt(0)
	v_mfma_f32_16x16x32_bf16 v[118:121], v[230:233], v[198:201], v[118:121]
	v_mfma_f32_16x16x32_bf16 v[114:117], v[238:241], v[198:201], v[114:117]
	v_mfma_f32_16x16x32_bf16 v[102:105], v[230:233], v[206:209], v[102:105]
	v_mfma_f32_16x16x32_bf16 v[98:101], v[238:241], v[206:209], v[98:101]
	v_mfma_f32_16x16x32_bf16 v[86:89], v[230:233], v[214:217], v[86:89]
	v_mfma_f32_16x16x32_bf16 v[82:85], v[238:241], v[214:217], v[82:85]
	v_mfma_f32_16x16x32_bf16 v[70:73], v[230:233], v[222:225], v[70:73]
	v_mfma_f32_16x16x32_bf16 v[66:69], v[238:241], v[222:225], v[66:69]
	v_mfma_f32_16x16x32_bf16 v[118:121], v[234:237], v[202:205], v[118:121]
	v_mfma_f32_16x16x32_bf16 v[114:117], v[242:245], v[202:205], v[114:117]
	v_mfma_f32_16x16x32_bf16 v[102:105], v[234:237], v[210:213], v[102:105]
	v_mfma_f32_16x16x32_bf16 v[98:101], v[242:245], v[210:213], v[98:101]
	v_mfma_f32_16x16x32_bf16 v[86:89], v[234:237], v[218:221], v[86:89]
	v_mfma_f32_16x16x32_bf16 v[82:85], v[242:245], v[218:221], v[82:85]
	v_mfma_f32_16x16x32_bf16 v[70:73], v[234:237], v[226:229], v[70:73]
	v_mfma_f32_16x16x32_bf16 v[66:69], v[242:245], v[226:229], v[66:69]
	s_mov_b32 m0, s62
	v_lshl_add_u64 v[142:143], v[246:247], 0, s[6:7]
	s_barrier
	ds_read_b128 v[198:201], v158 offset:49152
	ds_read_b128 v[202:205], v158 offset:50176
	ds_read_b128 v[206:209], v158 offset:51200
	ds_read_b128 v[210:213], v158 offset:52224
	ds_read_b128 v[214:217], v158 offset:53248
	ds_read_b128 v[218:221], v158 offset:54272
	ds_read_b128 v[222:225], v158 offset:55296
	ds_read_b128 v[226:229], v158 offset:56320
	global_load_lds_dwordx4 v[142:143], off
	v_lshl_add_u64 v[142:143], v[248:249], 0, s[6:7]
	s_mov_b32 m0, s63
	s_nop 0
	global_load_lds_dwordx4 v[142:143], off
	s_barrier
	s_waitcnt lgkmcnt(0)
	s_waitcnt lgkmcnt(0)
	v_mfma_f32_16x16x32_bf16 v[62:65], v[138:141], v[198:201], v[62:65]
	v_mfma_f32_16x16x32_bf16 v[58:61], v[190:193], v[198:201], v[58:61]
	v_mfma_f32_16x16x32_bf16 v[50:53], v[138:141], v[206:209], v[50:53]
	v_mfma_f32_16x16x32_bf16 v[42:45], v[190:193], v[206:209], v[42:45]
	v_mfma_f32_16x16x32_bf16 v[34:37], v[138:141], v[214:217], v[34:37]
	v_mfma_f32_16x16x32_bf16 v[26:29], v[190:193], v[214:217], v[26:29]
	v_mfma_f32_16x16x32_bf16 v[18:21], v[138:141], v[222:225], v[18:21]
	v_mfma_f32_16x16x32_bf16 v[10:13], v[190:193], v[222:225], v[10:13]
	v_mfma_f32_16x16x32_bf16 v[62:65], v[186:189], v[202:205], v[62:65]
	v_mfma_f32_16x16x32_bf16 v[58:61], v[194:197], v[202:205], v[58:61]
	v_mfma_f32_16x16x32_bf16 v[50:53], v[186:189], v[210:213], v[50:53]
	v_mfma_f32_16x16x32_bf16 v[42:45], v[194:197], v[210:213], v[42:45]
	v_mfma_f32_16x16x32_bf16 v[34:37], v[186:189], v[218:221], v[34:37]
	v_mfma_f32_16x16x32_bf16 v[26:29], v[194:197], v[218:221], v[26:29]
	v_mfma_f32_16x16x32_bf16 v[18:21], v[186:189], v[226:229], v[18:21]
	v_mfma_f32_16x16x32_bf16 v[10:13], v[194:197], v[226:229], v[10:13]
	s_barrier
	s_add_u32 s48, s48, 0x40080
	s_addc_u32 s49, s49, 0
	s_add_i32 s50, s50, s57
	v_lshl_add_u64 v[138:139], s[48:49], 0, v[152:153]
	s_mov_b32 m0, s50
	s_nop 0
	global_load_lds_dwordx4 v[138:139], off
	v_lshl_add_u64 v[138:139], s[48:49], 0, v[156:157]
	s_add_i32 m0, s50, 0x2000
	s_nop 0
	global_load_lds_dwordx4 v[138:139], off
	s_waitcnt vmcnt(6)
	s_barrier
	v_mfma_f32_16x16x32_bf16 v[54:57], v[230:233], v[198:201], v[54:57]
	v_mfma_f32_16x16x32_bf16 v[46:49], v[238:241], v[198:201], v[46:49]
	v_mfma_f32_16x16x32_bf16 v[38:41], v[230:233], v[206:209], v[38:41]
	v_mfma_f32_16x16x32_bf16 v[30:33], v[238:241], v[206:209], v[30:33]
	v_mfma_f32_16x16x32_bf16 v[22:25], v[230:233], v[214:217], v[22:25]
	v_mfma_f32_16x16x32_bf16 v[14:17], v[238:241], v[214:217], v[14:17]
	v_mfma_f32_16x16x32_bf16 v[6:9], v[230:233], v[222:225], v[6:9]
	v_mfma_f32_16x16x32_bf16 v[2:5], v[238:241], v[222:225], v[2:5]
	v_mfma_f32_16x16x32_bf16 v[54:57], v[234:237], v[202:205], v[54:57]
	v_mfma_f32_16x16x32_bf16 v[46:49], v[242:245], v[202:205], v[46:49]
	v_mfma_f32_16x16x32_bf16 v[38:41], v[234:237], v[210:213], v[38:41]
	v_mfma_f32_16x16x32_bf16 v[30:33], v[242:245], v[210:213], v[30:33]
	v_mfma_f32_16x16x32_bf16 v[22:25], v[234:237], v[218:221], v[22:25]
	v_mfma_f32_16x16x32_bf16 v[14:17], v[242:245], v[218:221], v[14:17]
	v_mfma_f32_16x16x32_bf16 v[6:9], v[234:237], v[226:229], v[6:9]
	v_mfma_f32_16x16x32_bf16 v[2:5], v[242:245], v[226:229], v[2:5]
	s_add_i32 s47, s47, 2
	s_add_u32 s44, s44, 0x100
	s_addc_u32 s45, s45, 0
	s_add_u32 s37, s37, 0x100
	s_addc_u32 s46, s46, 0
	s_cmp_gt_u32 s47, 13
	s_barrier
	s_cbranch_scc0 .LBB0_690
	v_lshl_add_u32 v142, s42, 8, v144
	v_lshl_or_b32 v140, s20, 8, v146
	v_ashrrev_i32_e32 v143, 31, v142
	v_ashrrev_i32_e32 v141, 31, v140
	v_lshlrev_b64 v[138:139], 10, v[142:143]
	v_lshl_add_u64 v[138:139], v[138:139], 0, v[140:141]
	v_lshlrev_b64 v[138:139], 1, v[138:139]
	s_and_b64 vcc, exec, s[2:3]
	s_mov_b32 s20, s34
	s_mov_b32 s42, s36
	s_mov_b64 s[48:49], s[40:41]
	s_mov_b64 s[44:45], s[38:39]
	v_mov_b32_e32 v192, v138
	v_add_u32_e32 v193, 0x8000, v138
	v_add_u32_e32 v194, 0x10000, v138
	v_add_u32_e32 v195, 0x18000, v138
	v_add_u32_e32 v196, 0x40000, v138
	v_add_u32_e32 v197, 0x48000, v138
	v_add_u32_e32 v198, 0x50000, v138
	v_add_u32_e32 v199, 0x58000, v138
	global_load_dwordx4 v[200:203], v192, s[4:5]
	global_load_dwordx4 v[204:207], v192, s[4:5] offset:256
	global_load_dwordx4 v[208:211], v193, s[4:5]
	global_load_dwordx4 v[212:215], v193, s[4:5] offset:256
	global_load_dwordx4 v[216:219], v194, s[4:5]
	global_load_dwordx4 v[220:223], v194, s[4:5] offset:256
	global_load_dwordx4 v[224:227], v195, s[4:5]
	global_load_dwordx4 v[228:231], v195, s[4:5] offset:256
	s_waitcnt vmcnt(7)
	v_lshlrev_b32_e32 v143, 16, v200
	v_and_b32_e32 v185, 0xffff0000, v200
	v_lshlrev_b32_e32 v200, 16, v201
	v_and_b32_e32 v201, 0xffff0000, v201
	v_lshlrev_b32_e32 v191, 16, v203
	v_and_b32_e32 v203, 0xffff0000, v203
	v_lshlrev_b32_e32 v190, 16, v202
	v_and_b32_e32 v202, 0xffff0000, v202
	v_mul_f32_e32 v126, v126, v143
	v_mul_f32_e32 v127, v127, v185
	v_mul_f32_e32 v128, v128, v200
	v_mul_f32_e32 v129, v129, v201
	v_mul_f32_e32 v125, v125, v203
	v_mul_f32_e32 v143, v122, v190
	v_mul_f32_e32 v185, v123, v202
	v_mul_f32_e32 v200, v124, v191
	v_cvt_pk_bf16_f32 v122, v126, v127
	v_cvt_pk_bf16_f32 v123, v128, v129
	v_cvt_pk_bf16_f32 v124, v143, v185
	v_cvt_pk_bf16_f32 v125, v200, v125
	global_store_dwordx4 v192, v[122:125], s[18:19]
	s_nop 1
	global_load_dwordx4 v[200:203], v196, s[4:5]
	s_waitcnt vmcnt(8)
	v_lshlrev_b32_e32 v122, 16, v204
	v_and_b32_e32 v123, 0xffff0000, v204
	v_lshlrev_b32_e32 v124, 16, v205
	v_and_b32_e32 v125, 0xffff0000, v205
	v_lshlrev_b32_e32 v204, 16, v206
	v_and_b32_e32 v205, 0xffff0000, v206
	v_lshlrev_b32_e32 v206, 16, v207
	v_and_b32_e32 v207, 0xffff0000, v207
	v_mul_f32_e32 v117, v117, v207
	v_mul_f32_e32 v118, v118, v122
	v_mul_f32_e32 v119, v119, v123
	v_mul_f32_e32 v120, v120, v124
	v_mul_f32_e32 v121, v121, v125
	v_mul_f32_e32 v122, v114, v204
	v_mul_f32_e32 v123, v115, v205
	v_mul_f32_e32 v124, v116, v206
	v_cvt_pk_bf16_f32 v114, v118, v119
	v_cvt_pk_bf16_f32 v115, v120, v121
	v_cvt_pk_bf16_f32 v116, v122, v123
	v_cvt_pk_bf16_f32 v117, v124, v117
	global_store_dwordx4 v192, v[114:117], s[18:19] offset:256
	s_nop 1
	global_load_dwordx4 v[204:207], v196, s[4:5] offset:256
	s_waitcnt vmcnt(9)
	v_lshlrev_b32_e32 v118, 16, v208
	v_and_b32_e32 v208, 0xffff0000, v208
	v_lshlrev_b32_e32 v119, 16, v209
	v_and_b32_e32 v209, 0xffff0000, v209
	v_lshlrev_b32_e32 v121, 16, v211
	v_and_b32_e32 v211, 0xffff0000, v211
	v_lshlrev_b32_e32 v120, 16, v210
	v_and_b32_e32 v210, 0xffff0000, v210
	v_mul_f32_e32 v110, v110, v118
	v_mul_f32_e32 v111, v111, v208
	v_mul_f32_e32 v112, v112, v119
	v_mul_f32_e32 v113, v113, v209
	v_mul_f32_e32 v109, v109, v211
	v_mul_f32_e32 v208, v106, v120
	v_mul_f32_e32 v209, v107, v210
	v_mul_f32_e32 v210, v108, v121
	v_cvt_pk_bf16_f32 v106, v110, v111
	v_cvt_pk_bf16_f32 v107, v112, v113
	v_cvt_pk_bf16_f32 v108, v208, v209
	v_cvt_pk_bf16_f32 v109, v210, v109
	global_store_dwordx4 v193, v[106:109], s[18:19]
	s_nop 1
	global_load_dwordx4 v[208:211], v197, s[4:5]
	s_waitcnt vmcnt(10)
	v_lshlrev_b32_e32 v106, 16, v212
	v_and_b32_e32 v107, 0xffff0000, v212
	v_lshlrev_b32_e32 v108, 16, v213
	v_and_b32_e32 v109, 0xffff0000, v213
	v_lshlrev_b32_e32 v212, 16, v214
	v_and_b32_e32 v213, 0xffff0000, v214
	v_lshlrev_b32_e32 v214, 16, v215
	v_and_b32_e32 v215, 0xffff0000, v215
	v_mul_f32_e32 v101, v101, v215
	v_mul_f32_e32 v102, v102, v106
	v_mul_f32_e32 v103, v103, v107
	v_mul_f32_e32 v104, v104, v108
	v_mul_f32_e32 v105, v105, v109
	v_mul_f32_e32 v106, v98, v212
	v_mul_f32_e32 v107, v99, v213
	v_mul_f32_e32 v108, v100, v214
	v_cvt_pk_bf16_f32 v98, v102, v103
	v_cvt_pk_bf16_f32 v99, v104, v105
	v_cvt_pk_bf16_f32 v100, v106, v107
	v_cvt_pk_bf16_f32 v101, v108, v101
	global_store_dwordx4 v193, v[98:101], s[18:19] offset:256
	s_nop 1
	global_load_dwordx4 v[212:215], v197, s[4:5] offset:256
	s_waitcnt vmcnt(11)
	v_lshlrev_b32_e32 v102, 16, v216
	v_and_b32_e32 v216, 0xffff0000, v216
	v_lshlrev_b32_e32 v103, 16, v217
	v_and_b32_e32 v217, 0xffff0000, v217
	v_lshlrev_b32_e32 v105, 16, v219
	v_and_b32_e32 v219, 0xffff0000, v219
	v_lshlrev_b32_e32 v104, 16, v218
	v_and_b32_e32 v218, 0xffff0000, v218
	v_mul_f32_e32 v94, v94, v102
	v_mul_f32_e32 v95, v95, v216
	v_mul_f32_e32 v96, v96, v103
	v_mul_f32_e32 v97, v97, v217
	v_mul_f32_e32 v93, v93, v219
	v_mul_f32_e32 v216, v90, v104
	v_mul_f32_e32 v217, v91, v218
	v_mul_f32_e32 v218, v92, v105
	v_cvt_pk_bf16_f32 v90, v94, v95
	v_cvt_pk_bf16_f32 v91, v96, v97
	v_cvt_pk_bf16_f32 v92, v216, v217
	v_cvt_pk_bf16_f32 v93, v218, v93
	global_store_dwordx4 v194, v[90:93], s[18:19]
	s_nop 1
	global_load_dwordx4 v[216:219], v198, s[4:5]
	s_waitcnt vmcnt(12)
	v_lshlrev_b32_e32 v90, 16, v220
	v_and_b32_e32 v91, 0xffff0000, v220
	v_lshlrev_b32_e32 v92, 16, v221
	v_and_b32_e32 v93, 0xffff0000, v221
	v_lshlrev_b32_e32 v220, 16, v222
	v_and_b32_e32 v221, 0xffff0000, v222
	v_lshlrev_b32_e32 v222, 16, v223
	v_and_b32_e32 v223, 0xffff0000, v223
	v_mul_f32_e32 v85, v85, v223
	v_mul_f32_e32 v86, v86, v90
	v_mul_f32_e32 v87, v87, v91
	v_mul_f32_e32 v88, v88, v92
	v_mul_f32_e32 v89, v89, v93
	v_mul_f32_e32 v90, v82, v220
	v_mul_f32_e32 v91, v83, v221
	v_mul_f32_e32 v92, v84, v222
	v_cvt_pk_bf16_f32 v82, v86, v87
	v_cvt_pk_bf16_f32 v83, v88, v89
	v_cvt_pk_bf16_f32 v84, v90, v91
	v_cvt_pk_bf16_f32 v85, v92, v85
	global_store_dwordx4 v194, v[82:85], s[18:19] offset:256
	s_nop 1
	global_load_dwordx4 v[220:223], v198, s[4:5] offset:256
	s_waitcnt vmcnt(13)
	v_lshlrev_b32_e32 v86, 16, v224
	v_and_b32_e32 v224, 0xffff0000, v224
	v_lshlrev_b32_e32 v87, 16, v225
	v_and_b32_e32 v225, 0xffff0000, v225
	v_lshlrev_b32_e32 v89, 16, v227
	v_and_b32_e32 v227, 0xffff0000, v227
	v_lshlrev_b32_e32 v88, 16, v226
	v_and_b32_e32 v226, 0xffff0000, v226
	v_mul_f32_e32 v78, v78, v86
	v_mul_f32_e32 v79, v79, v224
	v_mul_f32_e32 v80, v80, v87
	v_mul_f32_e32 v81, v81, v225
	v_mul_f32_e32 v77, v77, v227
	v_mul_f32_e32 v224, v74, v88
	v_mul_f32_e32 v225, v75, v226
	v_mul_f32_e32 v226, v76, v89
	v_cvt_pk_bf16_f32 v74, v78, v79
	v_cvt_pk_bf16_f32 v75, v80, v81
	v_cvt_pk_bf16_f32 v76, v224, v225
	v_cvt_pk_bf16_f32 v77, v226, v77
	global_store_dwordx4 v195, v[74:77], s[18:19]
	s_nop 1
	global_load_dwordx4 v[224:227], v199, s[4:5]
	s_waitcnt vmcnt(14)
	v_lshlrev_b32_e32 v74, 16, v228
	v_and_b32_e32 v75, 0xffff0000, v228
	v_lshlrev_b32_e32 v76, 16, v229
	v_and_b32_e32 v77, 0xffff0000, v229
	v_lshlrev_b32_e32 v228, 16, v230
	v_and_b32_e32 v229, 0xffff0000, v230
	v_lshlrev_b32_e32 v230, 16, v231
	v_and_b32_e32 v231, 0xffff0000, v231
	v_mul_f32_e32 v69, v69, v231
	v_mul_f32_e32 v70, v70, v74
	v_mul_f32_e32 v71, v71, v75
	v_mul_f32_e32 v72, v72, v76
	v_mul_f32_e32 v73, v73, v77
	v_mul_f32_e32 v74, v66, v228
	v_mul_f32_e32 v75, v67, v229
	v_mul_f32_e32 v76, v68, v230
	v_cvt_pk_bf16_f32 v66, v70, v71
	v_cvt_pk_bf16_f32 v67, v72, v73
	v_cvt_pk_bf16_f32 v68, v74, v75
	v_cvt_pk_bf16_f32 v69, v76, v69
	global_store_dwordx4 v195, v[66:69], s[18:19] offset:256
	s_nop 1
	global_load_dwordx4 v[228:231], v199, s[4:5] offset:256
	s_waitcnt vmcnt(14)
	v_lshlrev_b32_e32 v70, 16, v200
	v_and_b32_e32 v200, 0xffff0000, v200
	v_lshlrev_b32_e32 v71, 16, v201
	v_and_b32_e32 v201, 0xffff0000, v201
	v_lshlrev_b32_e32 v73, 16, v203
	v_and_b32_e32 v203, 0xffff0000, v203
	v_lshlrev_b32_e32 v72, 16, v202
	v_and_b32_e32 v202, 0xffff0000, v202
	v_mul_f32_e32 v62, v62, v70
	v_mul_f32_e32 v63, v63, v200
	v_mul_f32_e32 v64, v64, v71
	v_mul_f32_e32 v65, v65, v201
	v_mul_f32_e32 v61, v61, v203
	v_mul_f32_e32 v200, v58, v72
	v_mul_f32_e32 v201, v59, v202
	v_mul_f32_e32 v202, v60, v73
	v_cvt_pk_bf16_f32 v58, v62, v63
	v_cvt_pk_bf16_f32 v59, v64, v65
	v_cvt_pk_bf16_f32 v60, v200, v201
	v_cvt_pk_bf16_f32 v61, v202, v61
	global_store_dwordx4 v196, v[58:61], s[18:19]
	s_nop 1
	s_waitcnt vmcnt(13)
	v_lshlrev_b32_e32 v58, 16, v204
	v_and_b32_e32 v59, 0xffff0000, v204
	v_lshlrev_b32_e32 v60, 16, v205
	v_and_b32_e32 v61, 0xffff0000, v205
	v_lshlrev_b32_e32 v204, 16, v206
	v_and_b32_e32 v205, 0xffff0000, v206
	v_lshlrev_b32_e32 v206, 16, v207
	v_and_b32_e32 v207, 0xffff0000, v207
	v_mul_f32_e32 v49, v49, v207
	v_mul_f32_e32 v54, v54, v58
	v_mul_f32_e32 v55, v55, v59
	v_mul_f32_e32 v56, v56, v60
	v_mul_f32_e32 v57, v57, v61
	v_mul_f32_e32 v58, v46, v204
	v_mul_f32_e32 v59, v47, v205
	v_mul_f32_e32 v60, v48, v206
	v_cvt_pk_bf16_f32 v46, v54, v55
	v_cvt_pk_bf16_f32 v47, v56, v57
	v_cvt_pk_bf16_f32 v48, v58, v59
	v_cvt_pk_bf16_f32 v49, v60, v49
	global_store_dwordx4 v196, v[46:49], s[18:19] offset:256
	s_nop 1
	s_waitcnt vmcnt(12)
	v_lshlrev_b32_e32 v54, 16, v208
	v_and_b32_e32 v208, 0xffff0000, v208
	v_lshlrev_b32_e32 v55, 16, v209
	v_and_b32_e32 v209, 0xffff0000, v209
	v_lshlrev_b32_e32 v56, 16, v210
	v_and_b32_e32 v210, 0xffff0000, v210
	v_lshlrev_b32_e32 v57, 16, v211
	v_and_b32_e32 v211, 0xffff0000, v211
	v_mul_f32_e32 v208, v51, v208
	v_mul_f32_e32 v209, v53, v209
	v_mul_f32_e32 v210, v43, v210
	v_mul_f32_e32 v45, v45, v211
	v_mul_f32_e32 v50, v50, v54
	v_mul_f32_e32 v51, v52, v55
	v_mul_f32_e32 v52, v42, v56
	v_mul_f32_e32 v53, v44, v57
	v_cvt_pk_bf16_f32 v42, v50, v208
	v_cvt_pk_bf16_f32 v43, v51, v209
	v_cvt_pk_bf16_f32 v44, v52, v210
	v_cvt_pk_bf16_f32 v45, v53, v45
	global_store_dwordx4 v197, v[42:45], s[18:19]
	s_nop 1
	s_waitcnt vmcnt(11)
	v_lshlrev_b32_e32 v42, 16, v212
	v_and_b32_e32 v43, 0xffff0000, v212
	v_lshlrev_b32_e32 v44, 16, v213
	v_and_b32_e32 v45, 0xffff0000, v213
	v_lshlrev_b32_e32 v212, 16, v214
	v_and_b32_e32 v213, 0xffff0000, v214
	v_lshlrev_b32_e32 v214, 16, v215
	v_and_b32_e32 v215, 0xffff0000, v215
	v_mul_f32_e32 v33, v33, v215
	v_mul_f32_e32 v38, v38, v42
	v_mul_f32_e32 v39, v39, v43
	v_mul_f32_e32 v40, v40, v44
	v_mul_f32_e32 v41, v41, v45
	v_mul_f32_e32 v42, v30, v212
	v_mul_f32_e32 v43, v31, v213
	v_mul_f32_e32 v44, v32, v214
	v_cvt_pk_bf16_f32 v30, v38, v39
	v_cvt_pk_bf16_f32 v31, v40, v41
	v_cvt_pk_bf16_f32 v32, v42, v43
	v_cvt_pk_bf16_f32 v33, v44, v33
	global_store_dwordx4 v197, v[30:33], s[18:19] offset:256
	s_nop 1
	s_waitcnt vmcnt(10)
	v_lshlrev_b32_e32 v38, 16, v216
	v_and_b32_e32 v216, 0xffff0000, v216
	v_lshlrev_b32_e32 v39, 16, v217
	v_and_b32_e32 v217, 0xffff0000, v217
	v_lshlrev_b32_e32 v40, 16, v218
	v_and_b32_e32 v218, 0xffff0000, v218
	v_lshlrev_b32_e32 v41, 16, v219
	v_and_b32_e32 v219, 0xffff0000, v219
	v_mul_f32_e32 v216, v35, v216
	v_mul_f32_e32 v217, v37, v217
	v_mul_f32_e32 v218, v27, v218
	v_mul_f32_e32 v29, v29, v219
	v_mul_f32_e32 v34, v34, v38
	v_mul_f32_e32 v35, v36, v39
	v_mul_f32_e32 v36, v26, v40
	v_mul_f32_e32 v37, v28, v41
	v_cvt_pk_bf16_f32 v26, v34, v216
	v_cvt_pk_bf16_f32 v27, v35, v217
	v_cvt_pk_bf16_f32 v28, v36, v218
	v_cvt_pk_bf16_f32 v29, v37, v29
	global_store_dwordx4 v198, v[26:29], s[18:19]
	s_nop 1
	s_waitcnt vmcnt(9)
	v_lshlrev_b32_e32 v26, 16, v220
	v_and_b32_e32 v27, 0xffff0000, v220
	v_lshlrev_b32_e32 v28, 16, v221
	v_and_b32_e32 v29, 0xffff0000, v221
	v_lshlrev_b32_e32 v220, 16, v222
	v_and_b32_e32 v221, 0xffff0000, v222
	v_lshlrev_b32_e32 v222, 16, v223
	v_and_b32_e32 v223, 0xffff0000, v223
	v_mul_f32_e32 v17, v17, v223
	v_mul_f32_e32 v22, v22, v26
	v_mul_f32_e32 v23, v23, v27
	v_mul_f32_e32 v24, v24, v28
	v_mul_f32_e32 v25, v25, v29
	v_mul_f32_e32 v26, v14, v220
	v_mul_f32_e32 v27, v15, v221
	v_mul_f32_e32 v28, v16, v222
	v_cvt_pk_bf16_f32 v14, v22, v23
	v_cvt_pk_bf16_f32 v15, v24, v25
	v_cvt_pk_bf16_f32 v16, v26, v27
	v_cvt_pk_bf16_f32 v17, v28, v17
	global_store_dwordx4 v198, v[14:17], s[18:19] offset:256
	s_nop 1
	s_waitcnt vmcnt(8)
	v_lshlrev_b32_e32 v22, 16, v224
	v_and_b32_e32 v224, 0xffff0000, v224
	v_lshlrev_b32_e32 v23, 16, v225
	v_and_b32_e32 v225, 0xffff0000, v225
	v_lshlrev_b32_e32 v24, 16, v226
	v_and_b32_e32 v226, 0xffff0000, v226
	v_lshlrev_b32_e32 v25, 16, v227
	v_and_b32_e32 v227, 0xffff0000, v227
	v_mul_f32_e32 v224, v19, v224
	v_mul_f32_e32 v225, v21, v225
	v_mul_f32_e32 v226, v11, v226
	v_mul_f32_e32 v13, v13, v227
	v_mul_f32_e32 v18, v18, v22
	v_mul_f32_e32 v19, v20, v23
	v_mul_f32_e32 v20, v10, v24
	v_mul_f32_e32 v21, v12, v25
	v_cvt_pk_bf16_f32 v10, v18, v224
	v_cvt_pk_bf16_f32 v11, v19, v225
	v_cvt_pk_bf16_f32 v12, v20, v226
	v_cvt_pk_bf16_f32 v13, v21, v13
	global_store_dwordx4 v199, v[10:13], s[18:19]
	s_nop 1
	s_waitcnt vmcnt(7)
	v_lshlrev_b32_e32 v10, 16, v228
	v_and_b32_e32 v11, 0xffff0000, v228
	v_lshlrev_b32_e32 v12, 16, v229
	v_and_b32_e32 v13, 0xffff0000, v229
	v_lshlrev_b32_e32 v228, 16, v230
	v_and_b32_e32 v229, 0xffff0000, v230
	v_lshlrev_b32_e32 v230, 16, v231
	v_and_b32_e32 v231, 0xffff0000, v231
	v_mul_f32_e32 v5, v5, v231
	v_mul_f32_e32 v6, v6, v10
	v_mul_f32_e32 v7, v7, v11
	v_mul_f32_e32 v8, v8, v12
	v_mul_f32_e32 v9, v9, v13
	v_mul_f32_e32 v10, v2, v228
	v_mul_f32_e32 v11, v3, v229
	v_mul_f32_e32 v12, v4, v230
	v_cvt_pk_bf16_f32 v2, v6, v7
	v_cvt_pk_bf16_f32 v3, v8, v9
	v_cvt_pk_bf16_f32 v4, v10, v11
	v_cvt_pk_bf16_f32 v5, v12, v5
	global_store_dwordx4 v199, v[2:5], s[18:19] offset:256
	s_nop 1
	s_cbranch_vccz .LBB0_683
	s_waitcnt vmcnt(0)
	s_cmpk_gt_u32 s25, 0xff
	s_cbranch_scc1 .LBB0_694
	s_barrier

.LBB0_762:
	ds_read_b128 v[138:141], v147
	ds_read_b128 v[186:189], v147 offset:1024
	ds_read_b128 v[190:193], v147 offset:2048
	ds_read_b128 v[194:197], v147 offset:3072
	s_add_u32 s58, s56, 0xfffc0080
	s_addc_u32 s59, s57, -1
	s_cmp_eq_u32 s47, 12
	s_cselect_b32 s61, s21, s59
	s_cselect_b32 s60, s22, s58
	s_cselect_b32 s59, s23, s46
	s_cselect_b32 s58, s41, s43
	v_lshl_add_u64 v[142:143], s[56:57], 0, v[130:131]
	s_add_i32 m0, s51, 0xc000
	ds_read_b128 v[198:201], v158
	ds_read_b128 v[202:205], v158 offset:1024
	ds_read_b128 v[206:209], v158 offset:2048
	ds_read_b128 v[210:213], v158 offset:3072
	ds_read_b128 v[214:217], v158 offset:4096
	ds_read_b128 v[218:221], v158 offset:5120
	ds_read_b128 v[222:225], v158 offset:6144
	ds_read_b128 v[226:229], v158 offset:7168
	global_load_lds_dwordx4 v[142:143], off
	v_lshl_add_u64 v[142:143], s[56:57], 0, v[132:133]
	s_add_i32 m0, s51, 0xe000
	s_nop 0
	global_load_lds_dwordx4 v[142:143], off
	s_waitcnt lgkmcnt(8)
	s_barrier
	s_waitcnt lgkmcnt(0)
	s_waitcnt lgkmcnt(0)
	v_mfma_f32_16x16x32_bf16 v[126:129], v[138:141], v[198:201], v[126:129]
	v_mfma_f32_16x16x32_bf16 v[122:125], v[190:193], v[198:201], v[122:125]
	v_mfma_f32_16x16x32_bf16 v[110:113], v[138:141], v[206:209], v[110:113]
	v_mfma_f32_16x16x32_bf16 v[106:109], v[190:193], v[206:209], v[106:109]
	v_mfma_f32_16x16x32_bf16 v[94:97], v[138:141], v[214:217], v[94:97]
	v_mfma_f32_16x16x32_bf16 v[90:93], v[190:193], v[214:217], v[90:93]
	v_mfma_f32_16x16x32_bf16 v[78:81], v[138:141], v[222:225], v[78:81]
	v_mfma_f32_16x16x32_bf16 v[74:77], v[190:193], v[222:225], v[74:77]
	v_mfma_f32_16x16x32_bf16 v[126:129], v[186:189], v[202:205], v[126:129]
	v_mfma_f32_16x16x32_bf16 v[122:125], v[194:197], v[202:205], v[122:125]
	v_mfma_f32_16x16x32_bf16 v[110:113], v[186:189], v[210:213], v[110:113]
	v_mfma_f32_16x16x32_bf16 v[106:109], v[194:197], v[210:213], v[106:109]
	v_mfma_f32_16x16x32_bf16 v[94:97], v[186:189], v[218:221], v[94:97]
	v_mfma_f32_16x16x32_bf16 v[90:93], v[194:197], v[218:221], v[90:93]
	v_mfma_f32_16x16x32_bf16 v[78:81], v[186:189], v[226:229], v[78:81]
	v_mfma_f32_16x16x32_bf16 v[74:77], v[194:197], v[226:229], v[74:77]
	s_barrier
	s_add_i32 s74, s72, s64
	v_lshl_add_u64 v[142:143], s[58:59], 0, v[152:153]
	s_mov_b32 m0, s74
	ds_read_b128 v[230:233], v159
	ds_read_b128 v[234:237], v159 offset:1024
	ds_read_b128 v[238:241], v159 offset:2048
	ds_read_b128 v[242:245], v159 offset:3072
	global_load_lds_dwordx4 v[142:143], off
	v_lshl_add_u64 v[246:247], s[58:59], 0, v[156:157]
	s_add_i32 m0, s74, 0x2000
	s_nop 0
	global_load_lds_dwordx4 v[246:247], off
	s_barrier
	s_waitcnt lgkmcnt(0)
	s_waitcnt lgkmcnt(0)
	v_mfma_f32_16x16x32_bf16 v[118:121], v[230:233], v[198:201], v[118:121]
	v_mfma_f32_16x16x32_bf16 v[114:117], v[238:241], v[198:201], v[114:117]
	v_mfma_f32_16x16x32_bf16 v[102:105], v[230:233], v[206:209], v[102:105]
	v_mfma_f32_16x16x32_bf16 v[98:101], v[238:241], v[206:209], v[98:101]
	v_mfma_f32_16x16x32_bf16 v[86:89], v[230:233], v[214:217], v[86:89]
	v_mfma_f32_16x16x32_bf16 v[82:85], v[238:241], v[214:217], v[82:85]
	v_mfma_f32_16x16x32_bf16 v[70:73], v[230:233], v[222:225], v[70:73]
	v_mfma_f32_16x16x32_bf16 v[66:69], v[238:241], v[222:225], v[66:69]
	v_mfma_f32_16x16x32_bf16 v[118:121], v[234:237], v[202:205], v[118:121]
	v_mfma_f32_16x16x32_bf16 v[114:117], v[242:245], v[202:205], v[114:117]
	v_mfma_f32_16x16x32_bf16 v[102:105], v[234:237], v[210:213], v[102:105]
	v_mfma_f32_16x16x32_bf16 v[98:101], v[242:245], v[210:213], v[98:101]
	v_mfma_f32_16x16x32_bf16 v[86:89], v[234:237], v[218:221], v[86:89]
	v_mfma_f32_16x16x32_bf16 v[82:85], v[242:245], v[218:221], v[82:85]
	v_mfma_f32_16x16x32_bf16 v[70:73], v[234:237], v[226:229], v[70:73]
	v_mfma_f32_16x16x32_bf16 v[66:69], v[242:245], v[226:229], v[66:69]
	s_mov_b32 m0, s51
	v_lshl_add_u64 v[248:249], s[60:61], 0, v[150:151]
	s_barrier
	ds_read_b128 v[198:201], v158 offset:16384
	ds_read_b128 v[202:205], v158 offset:17408
	ds_read_b128 v[206:209], v158 offset:18432
	ds_read_b128 v[210:213], v158 offset:19456
	ds_read_b128 v[214:217], v158 offset:20480
	ds_read_b128 v[218:221], v158 offset:21504
	ds_read_b128 v[222:225], v158 offset:22528
	ds_read_b128 v[226:229], v158 offset:23552
	global_load_lds_dwordx4 v[248:249], off
	v_lshl_add_u64 v[250:251], s[60:61], 0, v[154:155]
	s_mov_b32 m0, s65
	s_nop 0
	global_load_lds_dwordx4 v[250:251], off
	s_barrier
	s_waitcnt lgkmcnt(0)
	s_waitcnt lgkmcnt(0)
	v_mfma_f32_16x16x32_bf16 v[62:65], v[138:141], v[198:201], v[62:65]
	v_mfma_f32_16x16x32_bf16 v[58:61], v[190:193], v[198:201], v[58:61]
	v_mfma_f32_16x16x32_bf16 v[46:49], v[138:141], v[206:209], v[46:49]
	v_mfma_f32_16x16x32_bf16 v[42:45], v[190:193], v[206:209], v[42:45]
	v_mfma_f32_16x16x32_bf16 v[30:33], v[138:141], v[214:217], v[30:33]
	v_mfma_f32_16x16x32_bf16 v[26:29], v[190:193], v[214:217], v[26:29]
	v_mfma_f32_16x16x32_bf16 v[14:17], v[138:141], v[222:225], v[14:17]
	v_mfma_f32_16x16x32_bf16 v[10:13], v[190:193], v[222:225], v[10:13]
	v_mfma_f32_16x16x32_bf16 v[62:65], v[186:189], v[202:205], v[62:65]
	v_mfma_f32_16x16x32_bf16 v[58:61], v[194:197], v[202:205], v[58:61]
	v_mfma_f32_16x16x32_bf16 v[46:49], v[186:189], v[210:213], v[46:49]
	v_mfma_f32_16x16x32_bf16 v[42:45], v[194:197], v[210:213], v[42:45]
	v_mfma_f32_16x16x32_bf16 v[30:33], v[186:189], v[218:221], v[30:33]
	v_mfma_f32_16x16x32_bf16 v[26:29], v[194:197], v[218:221], v[26:29]
	v_mfma_f32_16x16x32_bf16 v[14:17], v[186:189], v[226:229], v[14:17]
	v_mfma_f32_16x16x32_bf16 v[10:13], v[194:197], v[226:229], v[10:13]
	s_barrier
	s_add_u32 s74, s58, 0x40000
	s_addc_u32 s75, s59, 0
	s_add_i32 s76, s73, s64
	v_lshl_add_u64 v[138:139], s[74:75], 0, v[152:153]
	s_mov_b32 m0, s76
	s_nop 0
	global_load_lds_dwordx4 v[138:139], off
	v_lshl_add_u64 v[138:139], s[74:75], 0, v[156:157]
	s_add_i32 m0, s76, 0x2000
	s_nop 0
	global_load_lds_dwordx4 v[138:139], off
	s_waitcnt vmcnt(6)
	s_barrier
	v_mfma_f32_16x16x32_bf16 v[54:57], v[230:233], v[198:201], v[54:57]
	v_mfma_f32_16x16x32_bf16 v[50:53], v[238:241], v[198:201], v[50:53]
	v_mfma_f32_16x16x32_bf16 v[38:41], v[230:233], v[206:209], v[38:41]
	v_mfma_f32_16x16x32_bf16 v[34:37], v[238:241], v[206:209], v[34:37]
	v_mfma_f32_16x16x32_bf16 v[22:25], v[230:233], v[214:217], v[22:25]
	v_mfma_f32_16x16x32_bf16 v[18:21], v[238:241], v[214:217], v[18:21]
	v_mfma_f32_16x16x32_bf16 v[6:9], v[230:233], v[222:225], v[6:9]
	v_mfma_f32_16x16x32_bf16 v[2:5], v[238:241], v[222:225], v[2:5]
	v_mfma_f32_16x16x32_bf16 v[54:57], v[234:237], v[202:205], v[54:57]
	v_mfma_f32_16x16x32_bf16 v[50:53], v[242:245], v[202:205], v[50:53]
	v_mfma_f32_16x16x32_bf16 v[38:41], v[234:237], v[210:213], v[38:41]
	v_mfma_f32_16x16x32_bf16 v[34:37], v[242:245], v[210:213], v[34:37]
	v_mfma_f32_16x16x32_bf16 v[22:25], v[234:237], v[218:221], v[22:25]
	v_mfma_f32_16x16x32_bf16 v[18:21], v[242:245], v[218:221], v[18:21]
	v_mfma_f32_16x16x32_bf16 v[6:9], v[234:237], v[226:229], v[6:9]
	v_mfma_f32_16x16x32_bf16 v[2:5], v[242:245], v[226:229], v[2:5]
	s_add_i32 s74, 0, 0x18000
	v_add_u32_e32 v169, s74, v145
	s_barrier
	ds_read_b128 v[138:141], v169
	ds_read_b128 v[186:189], v169 offset:1024
	ds_read_b128 v[190:193], v169 offset:2048
	ds_read_b128 v[194:197], v169 offset:3072
	s_add_u32 s60, s60, 0x40000
	s_addc_u32 s61, s61, 0
	s_mov_b32 m0, s66
	v_lshl_add_u64 v[230:231], s[60:61], 0, v[150:151]
	ds_read_b128 v[198:201], v158 offset:32768
	ds_read_b128 v[202:205], v158 offset:33792
	ds_read_b128 v[206:209], v158 offset:34816
	ds_read_b128 v[210:213], v158 offset:35840
	ds_read_b128 v[214:217], v158 offset:36864
	ds_read_b128 v[218:221], v158 offset:37888
	ds_read_b128 v[222:225], v158 offset:38912
	ds_read_b128 v[226:229], v158 offset:39936
	global_load_lds_dwordx4 v[230:231], off
	v_lshl_add_u64 v[230:231], s[60:61], 0, v[154:155]
	s_mov_b32 m0, s67
	s_nop 0
	global_load_lds_dwordx4 v[230:231], off
	s_waitcnt lgkmcnt(8)
	s_barrier
	s_waitcnt lgkmcnt(0)
	s_waitcnt lgkmcnt(0)
	v_mfma_f32_16x16x32_bf16 v[126:129], v[138:141], v[198:201], v[126:129]
	v_mfma_f32_16x16x32_bf16 v[122:125], v[190:193], v[198:201], v[122:125]
	v_mfma_f32_16x16x32_bf16 v[110:113], v[138:141], v[206:209], v[110:113]
	v_mfma_f32_16x16x32_bf16 v[106:109], v[190:193], v[206:209], v[106:109]
	v_mfma_f32_16x16x32_bf16 v[94:97], v[138:141], v[214:217], v[94:97]
	v_mfma_f32_16x16x32_bf16 v[90:93], v[190:193], v[214:217], v[90:93]
	v_mfma_f32_16x16x32_bf16 v[78:81], v[138:141], v[222:225], v[78:81]
	v_mfma_f32_16x16x32_bf16 v[74:77], v[190:193], v[222:225], v[74:77]
	v_mfma_f32_16x16x32_bf16 v[126:129], v[186:189], v[202:205], v[126:129]
	v_mfma_f32_16x16x32_bf16 v[122:125], v[194:197], v[202:205], v[122:125]
	v_mfma_f32_16x16x32_bf16 v[110:113], v[186:189], v[210:213], v[110:113]
	v_mfma_f32_16x16x32_bf16 v[106:109], v[194:197], v[210:213], v[106:109]
	v_mfma_f32_16x16x32_bf16 v[94:97], v[186:189], v[218:221], v[94:97]
	v_mfma_f32_16x16x32_bf16 v[90:93], v[194:197], v[218:221], v[90:93]
	v_mfma_f32_16x16x32_bf16 v[78:81], v[186:189], v[226:229], v[78:81]
	v_mfma_f32_16x16x32_bf16 v[74:77], v[194:197], v[226:229], v[74:77]
	s_barrier
	s_add_i32 s60, 0, 0x1c000
	s_add_i32 s61, s74, s64
	v_add_u32_e32 v169, s60, v145
	v_lshl_add_u64 v[142:143], v[142:143], 0, s[12:13]
	s_mov_b32 m0, s61
	ds_read_b128 v[230:233], v169
	ds_read_b128 v[234:237], v169 offset:1024
	ds_read_b128 v[238:241], v169 offset:2048
	ds_read_b128 v[242:245], v169 offset:3072
	global_load_lds_dwordx4 v[142:143], off
	v_lshl_add_u64 v[142:143], v[246:247], 0, s[12:13]
	s_add_i32 m0, s61, 0x2000
	s_nop 0
	global_load_lds_dwordx4 v[142:143], off
	s_barrier
	s_waitcnt lgkmcnt(0)
	s_waitcnt lgkmcnt(0)
	v_mfma_f32_16x16x32_bf16 v[118:121], v[230:233], v[198:201], v[118:121]
	v_mfma_f32_16x16x32_bf16 v[114:117], v[238:241], v[198:201], v[114:117]
	v_mfma_f32_16x16x32_bf16 v[102:105], v[230:233], v[206:209], v[102:105]
	v_mfma_f32_16x16x32_bf16 v[98:101], v[238:241], v[206:209], v[98:101]
	v_mfma_f32_16x16x32_bf16 v[86:89], v[230:233], v[214:217], v[86:89]
	v_mfma_f32_16x16x32_bf16 v[82:85], v[238:241], v[214:217], v[82:85]
	v_mfma_f32_16x16x32_bf16 v[70:73], v[230:233], v[222:225], v[70:73]
	v_mfma_f32_16x16x32_bf16 v[66:69], v[238:241], v[222:225], v[66:69]
	v_mfma_f32_16x16x32_bf16 v[118:121], v[234:237], v[202:205], v[118:121]
	v_mfma_f32_16x16x32_bf16 v[114:117], v[242:245], v[202:205], v[114:117]
	v_mfma_f32_16x16x32_bf16 v[102:105], v[234:237], v[210:213], v[102:105]
	v_mfma_f32_16x16x32_bf16 v[98:101], v[242:245], v[210:213], v[98:101]
	v_mfma_f32_16x16x32_bf16 v[86:89], v[234:237], v[218:221], v[86:89]
	v_mfma_f32_16x16x32_bf16 v[82:85], v[242:245], v[218:221], v[82:85]
	v_mfma_f32_16x16x32_bf16 v[70:73], v[234:237], v[226:229], v[70:73]
	v_mfma_f32_16x16x32_bf16 v[66:69], v[242:245], v[226:229], v[66:69]
	s_mov_b32 m0, s69
	v_lshl_add_u64 v[142:143], v[248:249], 0, s[12:13]
	s_barrier
	ds_read_b128 v[198:201], v158 offset:49152
	ds_read_b128 v[202:205], v158 offset:50176
	ds_read_b128 v[206:209], v158 offset:51200
	ds_read_b128 v[210:213], v158 offset:52224
	ds_read_b128 v[214:217], v158 offset:53248
	ds_read_b128 v[218:221], v158 offset:54272
	ds_read_b128 v[222:225], v158 offset:55296
	ds_read_b128 v[226:229], v158 offset:56320
	global_load_lds_dwordx4 v[142:143], off
	v_lshl_add_u64 v[142:143], v[250:251], 0, s[12:13]
	s_mov_b32 m0, s70
	s_nop 0
	global_load_lds_dwordx4 v[142:143], off
	s_barrier
	s_waitcnt lgkmcnt(0)
	s_waitcnt lgkmcnt(0)
	v_mfma_f32_16x16x32_bf16 v[62:65], v[138:141], v[198:201], v[62:65]
	v_mfma_f32_16x16x32_bf16 v[58:61], v[190:193], v[198:201], v[58:61]
	v_mfma_f32_16x16x32_bf16 v[46:49], v[138:141], v[206:209], v[46:49]
	v_mfma_f32_16x16x32_bf16 v[42:45], v[190:193], v[206:209], v[42:45]
	v_mfma_f32_16x16x32_bf16 v[30:33], v[138:141], v[214:217], v[30:33]
	v_mfma_f32_16x16x32_bf16 v[26:29], v[190:193], v[214:217], v[26:29]
	v_mfma_f32_16x16x32_bf16 v[14:17], v[138:141], v[222:225], v[14:17]
	v_mfma_f32_16x16x32_bf16 v[10:13], v[190:193], v[222:225], v[10:13]
	v_mfma_f32_16x16x32_bf16 v[62:65], v[186:189], v[202:205], v[62:65]
	v_mfma_f32_16x16x32_bf16 v[58:61], v[194:197], v[202:205], v[58:61]
	v_mfma_f32_16x16x32_bf16 v[46:49], v[186:189], v[210:213], v[46:49]
	v_mfma_f32_16x16x32_bf16 v[42:45], v[194:197], v[210:213], v[42:45]
	v_mfma_f32_16x16x32_bf16 v[30:33], v[186:189], v[218:221], v[30:33]
	v_mfma_f32_16x16x32_bf16 v[26:29], v[194:197], v[218:221], v[26:29]
	v_mfma_f32_16x16x32_bf16 v[14:17], v[186:189], v[226:229], v[14:17]
	v_mfma_f32_16x16x32_bf16 v[10:13], v[194:197], v[226:229], v[10:13]
	s_barrier
	s_add_u32 s58, s58, 0x40080
	s_addc_u32 s59, s59, 0
	s_add_i32 s60, s60, s64
	v_lshl_add_u64 v[138:139], s[58:59], 0, v[152:153]
	s_mov_b32 m0, s60
	s_nop 0
	global_load_lds_dwordx4 v[138:139], off
	v_lshl_add_u64 v[138:139], s[58:59], 0, v[156:157]
	s_add_i32 m0, s60, 0x2000
	s_nop 0
	global_load_lds_dwordx4 v[138:139], off
	s_waitcnt vmcnt(6)
	s_barrier
	v_mfma_f32_16x16x32_bf16 v[54:57], v[230:233], v[198:201], v[54:57]
	v_mfma_f32_16x16x32_bf16 v[50:53], v[238:241], v[198:201], v[50:53]
	v_mfma_f32_16x16x32_bf16 v[38:41], v[230:233], v[206:209], v[38:41]
	v_mfma_f32_16x16x32_bf16 v[34:37], v[238:241], v[206:209], v[34:37]
	v_mfma_f32_16x16x32_bf16 v[22:25], v[230:233], v[214:217], v[22:25]
	v_mfma_f32_16x16x32_bf16 v[18:21], v[238:241], v[214:217], v[18:21]
	v_mfma_f32_16x16x32_bf16 v[6:9], v[230:233], v[222:225], v[6:9]
	v_mfma_f32_16x16x32_bf16 v[2:5], v[238:241], v[222:225], v[2:5]
	v_mfma_f32_16x16x32_bf16 v[54:57], v[234:237], v[202:205], v[54:57]
	v_mfma_f32_16x16x32_bf16 v[50:53], v[242:245], v[202:205], v[50:53]
	v_mfma_f32_16x16x32_bf16 v[38:41], v[234:237], v[210:213], v[38:41]
	v_mfma_f32_16x16x32_bf16 v[34:37], v[242:245], v[210:213], v[34:37]
	v_mfma_f32_16x16x32_bf16 v[22:25], v[234:237], v[218:221], v[22:25]
	v_mfma_f32_16x16x32_bf16 v[18:21], v[242:245], v[218:221], v[18:21]
	v_mfma_f32_16x16x32_bf16 v[6:9], v[234:237], v[226:229], v[6:9]
	v_mfma_f32_16x16x32_bf16 v[2:5], v[242:245], v[226:229], v[2:5]
	s_add_i32 s47, s47, 2
	s_add_u32 s56, s56, 0x100
	s_addc_u32 s57, s57, 0
	s_add_u32 s43, s43, 0x100
	s_addc_u32 s46, s46, 0
	s_cmp_gt_u32 s47, 13
	s_barrier
	s_cbranch_scc0 .LBB0_762
	v_lshl_add_u32 v142, s50, 8, v144
	v_lshl_or_b32 v140, s20, 8, v146
	v_ashrrev_i32_e32 v143, 31, v142
	v_ashrrev_i32_e32 v141, 31, v140
	v_lshlrev_b64 v[138:139], 10, v[142:143]
	v_lshl_add_u64 v[138:139], v[138:139], 0, v[140:141]
	v_lshlrev_b64 v[138:139], 1, v[138:139]
	v_readlane_b32 s74, v254, 46
	s_and_b64 vcc, exec, s[2:3]
	s_mov_b32 s20, s40
	s_mov_b32 s50, s42
	s_mov_b64 s[58:59], s[48:49]
	s_mov_b64 s[56:57], s[44:45]
	v_readlane_b32 s75, v254, 47
	v_mov_b32_e32 v203, v138
	v_add_u32_e32 v204, 0x8000, v138
	v_add_u32_e32 v205, 0x10000, v138
	v_add_u32_e32 v206, 0x18000, v138
	v_add_u32_e32 v207, 0x40000, v138
	v_add_u32_e32 v208, 0x48000, v138
	v_add_u32_e32 v209, 0x50000, v138
	v_add_u32_e32 v210, 0x58000, v138
	global_load_dwordx4 v[212:215], v203, s[18:19]
	global_load_dwordx4 v[216:219], v203, s[0:1]
	global_load_dwordx4 v[220:223], v203, s[18:19] offset:256
	global_load_dwordx4 v[224:227], v203, s[0:1] offset:256
	global_load_dwordx4 v[228:231], v204, s[18:19]
	global_load_dwordx4 v[232:235], v204, s[0:1]
	global_load_dwordx4 v[236:239], v204, s[18:19] offset:256
	global_load_dwordx4 v[240:243], v204, s[0:1] offset:256
	global_load_dwordx4 v[244:247], v205, s[18:19]
	global_load_dwordx4 v[248:251], v205, s[0:1]
	s_waitcnt vmcnt(8)
	v_lshlrev_b32_e32 v143, 16, v212
	v_lshlrev_b32_e32 v169, 16, v216
	v_and_b32_e32 v185, 0xffff0000, v212
	v_and_b32_e32 v212, 0xffff0000, v216
	v_lshlrev_b32_e32 v216, 16, v213
	v_lshlrev_b32_e32 v198, 16, v217
	v_and_b32_e32 v213, 0xffff0000, v213
	v_and_b32_e32 v217, 0xffff0000, v217
	v_lshlrev_b32_e32 v199, 16, v214
	v_lshlrev_b32_e32 v200, 16, v218
	v_and_b32_e32 v214, 0xffff0000, v214
	v_and_b32_e32 v218, 0xffff0000, v218
	v_lshlrev_b32_e32 v201, 16, v215
	v_lshlrev_b32_e32 v202, 16, v219
	v_and_b32_e32 v215, 0xffff0000, v215
	v_and_b32_e32 v219, 0xffff0000, v219
	v_fmac_f32_e32 v213, v129, v217
	v_fmac_f32_e32 v214, v123, v218
	v_fmac_f32_e32 v215, v125, v219
	v_fmac_f32_e32 v143, v126, v169
	v_fmac_f32_e32 v185, v127, v212
	v_fmac_f32_e32 v216, v128, v198
	v_fmac_f32_e32 v199, v122, v200
	v_fmac_f32_e32 v201, v124, v202
	v_cvt_pk_bf16_f32 v122, v143, v185
	v_cvt_pk_bf16_f32 v123, v216, v213
	v_cvt_pk_bf16_f32 v124, v199, v214
	v_cvt_pk_bf16_f32 v125, v201, v215
	global_store_dwordx4 v203, v[122:125], s[26:27]
	s_nop 1
	global_load_dwordx4 v[212:215], v205, s[18:19] offset:256
	global_load_dwordx4 v[216:219], v205, s[0:1] offset:256
	s_waitcnt vmcnt(9)
	v_lshlrev_b32_e32 v122, 16, v220
	v_lshlrev_b32_e32 v123, 16, v224
	v_and_b32_e32 v124, 0xffff0000, v220
	v_and_b32_e32 v125, 0xffff0000, v224
	v_lshlrev_b32_e32 v220, 16, v221
	v_lshlrev_b32_e32 v143, 16, v225
	v_and_b32_e32 v221, 0xffff0000, v221
	v_and_b32_e32 v169, 0xffff0000, v225
	v_lshlrev_b32_e32 v185, 16, v222
	v_lshlrev_b32_e32 v224, 16, v226
	v_and_b32_e32 v222, 0xffff0000, v222
	v_and_b32_e32 v225, 0xffff0000, v226
	v_lshlrev_b32_e32 v226, 16, v223
	v_lshlrev_b32_e32 v198, 16, v227
	v_and_b32_e32 v223, 0xffff0000, v223
	v_and_b32_e32 v227, 0xffff0000, v227
	v_fmac_f32_e32 v122, v118, v123
	v_fmac_f32_e32 v124, v119, v125
	v_fmac_f32_e32 v220, v120, v143
	v_fmac_f32_e32 v221, v121, v169
	v_fmac_f32_e32 v185, v114, v224
	v_fmac_f32_e32 v222, v115, v225
	v_fmac_f32_e32 v226, v116, v198
	v_fmac_f32_e32 v223, v117, v227
	v_cvt_pk_bf16_f32 v114, v122, v124
	v_cvt_pk_bf16_f32 v115, v220, v221
	v_cvt_pk_bf16_f32 v116, v185, v222
	v_cvt_pk_bf16_f32 v117, v226, v223
	global_store_dwordx4 v203, v[114:117], s[26:27] offset:256
	s_nop 1
	global_load_dwordx4 v[220:223], v206, s[18:19]
	global_load_dwordx4 v[224:227], v206, s[0:1]
	s_waitcnt vmcnt(10)
	v_lshlrev_b32_e32 v122, 16, v228
	v_lshlrev_b32_e32 v123, 16, v232
	v_and_b32_e32 v228, 0xffff0000, v228
	v_and_b32_e32 v232, 0xffff0000, v232
	v_lshlrev_b32_e32 v124, 16, v229
	v_lshlrev_b32_e32 v125, 16, v233
	v_and_b32_e32 v229, 0xffff0000, v229
	v_and_b32_e32 v233, 0xffff0000, v233
	v_lshlrev_b32_e32 v126, 16, v230
	v_lshlrev_b32_e32 v127, 16, v234
	v_and_b32_e32 v230, 0xffff0000, v230
	v_and_b32_e32 v234, 0xffff0000, v234
	v_lshlrev_b32_e32 v128, 16, v231
	v_lshlrev_b32_e32 v129, 16, v235
	v_and_b32_e32 v231, 0xffff0000, v231
	v_and_b32_e32 v235, 0xffff0000, v235
	v_fmac_f32_e32 v228, v111, v232
	v_fmac_f32_e32 v229, v113, v233
	v_fmac_f32_e32 v230, v107, v234
	v_fmac_f32_e32 v231, v109, v235
	v_fmac_f32_e32 v122, v110, v123
	v_fmac_f32_e32 v124, v112, v125
	v_fmac_f32_e32 v126, v106, v127
	v_fmac_f32_e32 v128, v108, v129
	v_cvt_pk_bf16_f32 v106, v122, v228
	v_cvt_pk_bf16_f32 v107, v124, v229
	v_cvt_pk_bf16_f32 v108, v126, v230
	v_cvt_pk_bf16_f32 v109, v128, v231
	global_store_dwordx4 v204, v[106:109], s[26:27]
	s_nop 1
	global_load_dwordx4 v[228:231], v206, s[18:19] offset:256
	global_load_dwordx4 v[232:235], v206, s[0:1] offset:256
	s_waitcnt vmcnt(11)
	v_lshlrev_b32_e32 v106, 16, v236
	v_lshlrev_b32_e32 v107, 16, v240
	v_and_b32_e32 v108, 0xffff0000, v236
	v_and_b32_e32 v109, 0xffff0000, v240
	v_lshlrev_b32_e32 v236, 16, v237
	v_lshlrev_b32_e32 v240, 16, v241
	v_and_b32_e32 v237, 0xffff0000, v237
	v_and_b32_e32 v241, 0xffff0000, v241
	v_lshlrev_b32_e32 v126, 16, v238
	v_lshlrev_b32_e32 v127, 16, v242
	v_and_b32_e32 v238, 0xffff0000, v238
	v_and_b32_e32 v242, 0xffff0000, v242
	v_lshlrev_b32_e32 v128, 16, v239
	v_lshlrev_b32_e32 v129, 16, v243
	v_and_b32_e32 v239, 0xffff0000, v239
	v_and_b32_e32 v243, 0xffff0000, v243
	v_fmac_f32_e32 v106, v102, v107
	v_fmac_f32_e32 v108, v103, v109
	v_fmac_f32_e32 v236, v104, v240
	v_fmac_f32_e32 v237, v105, v241
	v_fmac_f32_e32 v126, v98, v127
	v_fmac_f32_e32 v238, v99, v242
	v_fmac_f32_e32 v128, v100, v129
	v_fmac_f32_e32 v239, v101, v243
	v_cvt_pk_bf16_f32 v98, v106, v108
	v_cvt_pk_bf16_f32 v99, v236, v237
	v_cvt_pk_bf16_f32 v100, v126, v238
	v_cvt_pk_bf16_f32 v101, v128, v239
	global_store_dwordx4 v204, v[98:101], s[26:27] offset:256
	s_nop 1
	global_load_dwordx4 v[236:239], v207, s[18:19]
	global_load_dwordx4 v[240:243], v207, s[0:1]
	s_waitcnt vmcnt(12)
	v_lshlrev_b32_e32 v106, 16, v244
	v_lshlrev_b32_e32 v107, 16, v248
	v_and_b32_e32 v244, 0xffff0000, v244
	v_and_b32_e32 v248, 0xffff0000, v248
	v_lshlrev_b32_e32 v108, 16, v245
	v_lshlrev_b32_e32 v109, 16, v249
	v_and_b32_e32 v245, 0xffff0000, v245
	v_and_b32_e32 v249, 0xffff0000, v249
	v_lshlrev_b32_e32 v110, 16, v246
	v_lshlrev_b32_e32 v111, 16, v250
	v_and_b32_e32 v246, 0xffff0000, v246
	v_and_b32_e32 v250, 0xffff0000, v250
	v_lshlrev_b32_e32 v112, 16, v247
	v_lshlrev_b32_e32 v113, 16, v251
	v_and_b32_e32 v247, 0xffff0000, v247
	v_and_b32_e32 v251, 0xffff0000, v251
	v_fmac_f32_e32 v244, v95, v248
	v_fmac_f32_e32 v245, v97, v249
	v_fmac_f32_e32 v246, v91, v250
	v_fmac_f32_e32 v247, v93, v251
	v_fmac_f32_e32 v106, v94, v107
	v_fmac_f32_e32 v108, v96, v109
	v_fmac_f32_e32 v110, v90, v111
	v_fmac_f32_e32 v112, v92, v113
	v_cvt_pk_bf16_f32 v90, v106, v244
	v_cvt_pk_bf16_f32 v91, v108, v245
	v_cvt_pk_bf16_f32 v92, v110, v246
	v_cvt_pk_bf16_f32 v93, v112, v247
	global_store_dwordx4 v205, v[90:93], s[26:27]
	s_nop 1
	global_load_dwordx4 v[244:247], v207, s[18:19] offset:256
	global_load_dwordx4 v[248:251], v207, s[0:1] offset:256
	s_waitcnt vmcnt(12)
	v_lshlrev_b32_e32 v90, 16, v212
	v_lshlrev_b32_e32 v91, 16, v216
	v_and_b32_e32 v92, 0xffff0000, v212
	v_and_b32_e32 v93, 0xffff0000, v216
	v_lshlrev_b32_e32 v212, 16, v213
	v_lshlrev_b32_e32 v216, 16, v217
	v_and_b32_e32 v213, 0xffff0000, v213
	v_and_b32_e32 v217, 0xffff0000, v217
	v_lshlrev_b32_e32 v110, 16, v214
	v_lshlrev_b32_e32 v111, 16, v218
	v_and_b32_e32 v214, 0xffff0000, v214
	v_and_b32_e32 v218, 0xffff0000, v218
	v_lshlrev_b32_e32 v112, 16, v215
	v_lshlrev_b32_e32 v113, 16, v219
	v_and_b32_e32 v215, 0xffff0000, v215
	v_and_b32_e32 v219, 0xffff0000, v219
	v_fmac_f32_e32 v90, v86, v91
	v_fmac_f32_e32 v92, v87, v93
	v_fmac_f32_e32 v212, v88, v216
	v_fmac_f32_e32 v213, v89, v217
	v_fmac_f32_e32 v110, v82, v111
	v_fmac_f32_e32 v214, v83, v218
	v_fmac_f32_e32 v112, v84, v113
	v_fmac_f32_e32 v215, v85, v219
	v_cvt_pk_bf16_f32 v82, v90, v92
	v_cvt_pk_bf16_f32 v83, v212, v213
	v_cvt_pk_bf16_f32 v84, v110, v214
	v_cvt_pk_bf16_f32 v85, v112, v215
	global_store_dwordx4 v205, v[82:85], s[26:27] offset:256
	s_nop 1
	global_load_dwordx4 v[212:215], v208, s[18:19]
	global_load_dwordx4 v[216:219], v208, s[0:1]
	s_waitcnt vmcnt(12)
	v_lshlrev_b32_e32 v90, 16, v220
	v_lshlrev_b32_e32 v91, 16, v224
	v_and_b32_e32 v220, 0xffff0000, v220
	v_and_b32_e32 v224, 0xffff0000, v224
	v_lshlrev_b32_e32 v92, 16, v221
	v_lshlrev_b32_e32 v93, 16, v225
	v_and_b32_e32 v221, 0xffff0000, v221
	v_and_b32_e32 v225, 0xffff0000, v225
	v_lshlrev_b32_e32 v94, 16, v222
	v_lshlrev_b32_e32 v95, 16, v226
	v_and_b32_e32 v222, 0xffff0000, v222
	v_and_b32_e32 v226, 0xffff0000, v226
	v_lshlrev_b32_e32 v96, 16, v223
	v_lshlrev_b32_e32 v97, 16, v227
	v_and_b32_e32 v223, 0xffff0000, v223
	v_and_b32_e32 v227, 0xffff0000, v227
	v_fmac_f32_e32 v220, v79, v224
	v_fmac_f32_e32 v221, v81, v225
	v_fmac_f32_e32 v222, v75, v226
	v_fmac_f32_e32 v223, v77, v227
	v_fmac_f32_e32 v90, v78, v91
	v_fmac_f32_e32 v92, v80, v93
	v_fmac_f32_e32 v94, v74, v95
	v_fmac_f32_e32 v96, v76, v97
	v_cvt_pk_bf16_f32 v74, v90, v220
	v_cvt_pk_bf16_f32 v75, v92, v221
	v_cvt_pk_bf16_f32 v76, v94, v222
	v_cvt_pk_bf16_f32 v77, v96, v223
	global_store_dwordx4 v206, v[74:77], s[26:27]
	s_nop 1
	global_load_dwordx4 v[220:223], v208, s[18:19] offset:256
	global_load_dwordx4 v[224:227], v208, s[0:1] offset:256
	s_waitcnt vmcnt(12)
	v_lshlrev_b32_e32 v74, 16, v228
	v_lshlrev_b32_e32 v75, 16, v232
	v_and_b32_e32 v76, 0xffff0000, v228
	v_and_b32_e32 v77, 0xffff0000, v232
	v_lshlrev_b32_e32 v228, 16, v229
	v_lshlrev_b32_e32 v232, 16, v233
	v_and_b32_e32 v229, 0xffff0000, v229
	v_and_b32_e32 v233, 0xffff0000, v233
	v_lshlrev_b32_e32 v94, 16, v230
	v_lshlrev_b32_e32 v95, 16, v234
	v_and_b32_e32 v230, 0xffff0000, v230
	v_and_b32_e32 v234, 0xffff0000, v234
	v_lshlrev_b32_e32 v96, 16, v231
	v_lshlrev_b32_e32 v97, 16, v235
	v_and_b32_e32 v231, 0xffff0000, v231
	v_and_b32_e32 v235, 0xffff0000, v235
	v_fmac_f32_e32 v74, v70, v75
	v_fmac_f32_e32 v76, v71, v77
	v_fmac_f32_e32 v228, v72, v232
	v_fmac_f32_e32 v229, v73, v233
	v_fmac_f32_e32 v94, v66, v95
	v_fmac_f32_e32 v230, v67, v234
	v_fmac_f32_e32 v96, v68, v97
	v_fmac_f32_e32 v231, v69, v235
	v_cvt_pk_bf16_f32 v66, v74, v76
	v_cvt_pk_bf16_f32 v67, v228, v229
	v_cvt_pk_bf16_f32 v68, v94, v230
	v_cvt_pk_bf16_f32 v69, v96, v231
	global_store_dwordx4 v206, v[66:69], s[26:27] offset:256
	s_nop 1
	global_load_dwordx4 v[228:231], v209, s[18:19]
	global_load_dwordx4 v[232:235], v209, s[0:1]
	s_waitcnt vmcnt(12)
	v_lshlrev_b32_e32 v74, 16, v236
	v_lshlrev_b32_e32 v75, 16, v240
	v_and_b32_e32 v236, 0xffff0000, v236
	v_and_b32_e32 v240, 0xffff0000, v240
	v_lshlrev_b32_e32 v76, 16, v237
	v_lshlrev_b32_e32 v77, 16, v241
	v_and_b32_e32 v237, 0xffff0000, v237
	v_and_b32_e32 v241, 0xffff0000, v241
	v_lshlrev_b32_e32 v78, 16, v238
	v_lshlrev_b32_e32 v79, 16, v242
	v_and_b32_e32 v238, 0xffff0000, v238
	v_and_b32_e32 v242, 0xffff0000, v242
	v_lshlrev_b32_e32 v80, 16, v239
	v_lshlrev_b32_e32 v81, 16, v243
	v_and_b32_e32 v239, 0xffff0000, v239
	v_and_b32_e32 v243, 0xffff0000, v243
	v_fmac_f32_e32 v236, v63, v240
	v_fmac_f32_e32 v237, v65, v241
	v_fmac_f32_e32 v238, v59, v242
	v_fmac_f32_e32 v239, v61, v243
	v_fmac_f32_e32 v74, v62, v75
	v_fmac_f32_e32 v76, v64, v77
	v_fmac_f32_e32 v78, v58, v79
	v_fmac_f32_e32 v80, v60, v81
	v_cvt_pk_bf16_f32 v58, v74, v236
	v_cvt_pk_bf16_f32 v59, v76, v237
	v_cvt_pk_bf16_f32 v60, v78, v238
	v_cvt_pk_bf16_f32 v61, v80, v239
	global_store_dwordx4 v207, v[58:61], s[26:27]
	s_nop 1
	global_load_dwordx4 v[236:239], v209, s[18:19] offset:256
	global_load_dwordx4 v[240:243], v209, s[0:1] offset:256
	s_waitcnt vmcnt(12)
	v_lshlrev_b32_e32 v58, 16, v244
	v_lshlrev_b32_e32 v59, 16, v248
	v_and_b32_e32 v60, 0xffff0000, v244
	v_and_b32_e32 v61, 0xffff0000, v248
	v_lshlrev_b32_e32 v244, 16, v245
	v_lshlrev_b32_e32 v248, 16, v249
	v_and_b32_e32 v245, 0xffff0000, v245
	v_and_b32_e32 v249, 0xffff0000, v249
	v_lshlrev_b32_e32 v78, 16, v246
	v_lshlrev_b32_e32 v79, 16, v250
	v_and_b32_e32 v246, 0xffff0000, v246
	v_and_b32_e32 v250, 0xffff0000, v250
	v_lshlrev_b32_e32 v80, 16, v247
	v_lshlrev_b32_e32 v81, 16, v251
	v_and_b32_e32 v247, 0xffff0000, v247
	v_and_b32_e32 v251, 0xffff0000, v251
	v_fmac_f32_e32 v58, v54, v59
	v_fmac_f32_e32 v60, v55, v61
	v_fmac_f32_e32 v244, v56, v248
	v_fmac_f32_e32 v245, v57, v249
	v_fmac_f32_e32 v78, v50, v79
	v_fmac_f32_e32 v246, v51, v250
	v_fmac_f32_e32 v80, v52, v81
	v_fmac_f32_e32 v247, v53, v251
	v_cvt_pk_bf16_f32 v50, v58, v60
	v_cvt_pk_bf16_f32 v51, v244, v245
	v_cvt_pk_bf16_f32 v52, v78, v246
	v_cvt_pk_bf16_f32 v53, v80, v247
	global_store_dwordx4 v207, v[50:53], s[26:27] offset:256
	s_nop 1
	global_load_dwordx4 v[244:247], v210, s[18:19]
	global_load_dwordx4 v[248:251], v210, s[0:1]
	s_waitcnt vmcnt(12)
	v_lshlrev_b32_e32 v58, 16, v212
	v_lshlrev_b32_e32 v59, 16, v216
	v_and_b32_e32 v212, 0xffff0000, v212
	v_and_b32_e32 v216, 0xffff0000, v216
	v_lshlrev_b32_e32 v60, 16, v213
	v_lshlrev_b32_e32 v61, 16, v217
	v_and_b32_e32 v213, 0xffff0000, v213
	v_and_b32_e32 v217, 0xffff0000, v217
	v_lshlrev_b32_e32 v62, 16, v214
	v_lshlrev_b32_e32 v63, 16, v218
	v_and_b32_e32 v214, 0xffff0000, v214
	v_and_b32_e32 v218, 0xffff0000, v218
	v_lshlrev_b32_e32 v64, 16, v215
	v_lshlrev_b32_e32 v65, 16, v219
	v_and_b32_e32 v215, 0xffff0000, v215
	v_and_b32_e32 v219, 0xffff0000, v219
	v_fmac_f32_e32 v212, v47, v216
	v_fmac_f32_e32 v213, v49, v217
	v_fmac_f32_e32 v214, v43, v218
	v_fmac_f32_e32 v215, v45, v219
	v_fmac_f32_e32 v58, v46, v59
	v_fmac_f32_e32 v60, v48, v61
	v_fmac_f32_e32 v62, v42, v63
	v_fmac_f32_e32 v64, v44, v65
	v_cvt_pk_bf16_f32 v42, v58, v212
	v_cvt_pk_bf16_f32 v43, v60, v213
	v_cvt_pk_bf16_f32 v44, v62, v214
	v_cvt_pk_bf16_f32 v45, v64, v215
	global_store_dwordx4 v208, v[42:45], s[26:27]
	s_nop 1
	global_load_dwordx4 v[212:215], v210, s[18:19] offset:256
	global_load_dwordx4 v[216:219], v210, s[0:1] offset:256
	s_waitcnt vmcnt(12)
	v_lshlrev_b32_e32 v42, 16, v220
	v_lshlrev_b32_e32 v43, 16, v224
	v_and_b32_e32 v44, 0xffff0000, v220
	v_and_b32_e32 v45, 0xffff0000, v224
	v_lshlrev_b32_e32 v220, 16, v221
	v_lshlrev_b32_e32 v224, 16, v225
	v_and_b32_e32 v221, 0xffff0000, v221
	v_and_b32_e32 v225, 0xffff0000, v225
	v_lshlrev_b32_e32 v62, 16, v222
	v_lshlrev_b32_e32 v63, 16, v226
	v_and_b32_e32 v222, 0xffff0000, v222
	v_and_b32_e32 v226, 0xffff0000, v226
	v_lshlrev_b32_e32 v64, 16, v223
	v_lshlrev_b32_e32 v65, 16, v227
	v_and_b32_e32 v223, 0xffff0000, v223
	v_and_b32_e32 v227, 0xffff0000, v227
	v_fmac_f32_e32 v42, v38, v43
	v_fmac_f32_e32 v44, v39, v45
	v_fmac_f32_e32 v220, v40, v224
	v_fmac_f32_e32 v221, v41, v225
	v_fmac_f32_e32 v62, v34, v63
	v_fmac_f32_e32 v222, v35, v226
	v_fmac_f32_e32 v64, v36, v65
	v_fmac_f32_e32 v223, v37, v227
	v_cvt_pk_bf16_f32 v34, v42, v44
	v_cvt_pk_bf16_f32 v35, v220, v221
	v_cvt_pk_bf16_f32 v36, v62, v222
	v_cvt_pk_bf16_f32 v37, v64, v223
	global_store_dwordx4 v208, v[34:37], s[26:27] offset:256
	s_nop 1
	s_waitcnt vmcnt(10)
	v_lshlrev_b32_e32 v42, 16, v228
	v_lshlrev_b32_e32 v43, 16, v232
	v_and_b32_e32 v228, 0xffff0000, v228
	v_and_b32_e32 v232, 0xffff0000, v232
	v_lshlrev_b32_e32 v44, 16, v229
	v_lshlrev_b32_e32 v45, 16, v233
	v_and_b32_e32 v229, 0xffff0000, v229
	v_and_b32_e32 v233, 0xffff0000, v233
	v_lshlrev_b32_e32 v46, 16, v230
	v_lshlrev_b32_e32 v47, 16, v234
	v_and_b32_e32 v230, 0xffff0000, v230
	v_and_b32_e32 v234, 0xffff0000, v234
	v_lshlrev_b32_e32 v48, 16, v231
	v_lshlrev_b32_e32 v49, 16, v235
	v_and_b32_e32 v231, 0xffff0000, v231
	v_and_b32_e32 v235, 0xffff0000, v235
	v_fmac_f32_e32 v228, v31, v232
	v_fmac_f32_e32 v229, v33, v233
	v_fmac_f32_e32 v230, v27, v234
	v_fmac_f32_e32 v231, v29, v235
	v_fmac_f32_e32 v42, v30, v43
	v_fmac_f32_e32 v44, v32, v45
	v_fmac_f32_e32 v46, v26, v47
	v_fmac_f32_e32 v48, v28, v49
	v_cvt_pk_bf16_f32 v26, v42, v228
	v_cvt_pk_bf16_f32 v27, v44, v229
	v_cvt_pk_bf16_f32 v28, v46, v230
	v_cvt_pk_bf16_f32 v29, v48, v231
	global_store_dwordx4 v209, v[26:29], s[26:27]
	s_nop 1
	s_waitcnt vmcnt(8)
	v_lshlrev_b32_e32 v26, 16, v236
	v_lshlrev_b32_e32 v27, 16, v240
	v_and_b32_e32 v28, 0xffff0000, v236
	v_and_b32_e32 v29, 0xffff0000, v240
	v_lshlrev_b32_e32 v236, 16, v237
	v_lshlrev_b32_e32 v240, 16, v241
	v_and_b32_e32 v237, 0xffff0000, v237
	v_and_b32_e32 v241, 0xffff0000, v241
	v_lshlrev_b32_e32 v46, 16, v238
	v_lshlrev_b32_e32 v47, 16, v242
	v_and_b32_e32 v238, 0xffff0000, v238
	v_and_b32_e32 v242, 0xffff0000, v242
	v_lshlrev_b32_e32 v48, 16, v239
	v_lshlrev_b32_e32 v49, 16, v243
	v_and_b32_e32 v239, 0xffff0000, v239
	v_and_b32_e32 v243, 0xffff0000, v243
	v_fmac_f32_e32 v26, v22, v27
	v_fmac_f32_e32 v28, v23, v29
	v_fmac_f32_e32 v236, v24, v240
	v_fmac_f32_e32 v237, v25, v241
	v_fmac_f32_e32 v46, v18, v47
	v_fmac_f32_e32 v238, v19, v242
	v_fmac_f32_e32 v48, v20, v49
	v_fmac_f32_e32 v239, v21, v243
	v_cvt_pk_bf16_f32 v18, v26, v28
	v_cvt_pk_bf16_f32 v19, v236, v237
	v_cvt_pk_bf16_f32 v20, v46, v238
	v_cvt_pk_bf16_f32 v21, v48, v239
	global_store_dwordx4 v209, v[18:21], s[26:27] offset:256
	s_nop 1
	s_waitcnt vmcnt(6)
	v_lshlrev_b32_e32 v26, 16, v244
	v_lshlrev_b32_e32 v27, 16, v248
	v_and_b32_e32 v244, 0xffff0000, v244
	v_and_b32_e32 v248, 0xffff0000, v248
	v_lshlrev_b32_e32 v28, 16, v245
	v_lshlrev_b32_e32 v29, 16, v249
	v_and_b32_e32 v245, 0xffff0000, v245
	v_and_b32_e32 v249, 0xffff0000, v249
	v_lshlrev_b32_e32 v30, 16, v246
	v_lshlrev_b32_e32 v31, 16, v250
	v_and_b32_e32 v246, 0xffff0000, v246
	v_and_b32_e32 v250, 0xffff0000, v250
	v_lshlrev_b32_e32 v32, 16, v247
	v_lshlrev_b32_e32 v33, 16, v251
	v_and_b32_e32 v247, 0xffff0000, v247
	v_and_b32_e32 v251, 0xffff0000, v251
	v_fmac_f32_e32 v244, v15, v248
	v_fmac_f32_e32 v245, v17, v249
	v_fmac_f32_e32 v246, v11, v250
	v_fmac_f32_e32 v247, v13, v251
	v_fmac_f32_e32 v26, v14, v27
	v_fmac_f32_e32 v28, v16, v29
	v_fmac_f32_e32 v30, v10, v31
	v_fmac_f32_e32 v32, v12, v33
	v_cvt_pk_bf16_f32 v10, v26, v244
	v_cvt_pk_bf16_f32 v11, v28, v245
	v_cvt_pk_bf16_f32 v12, v30, v246
	v_cvt_pk_bf16_f32 v13, v32, v247
	global_store_dwordx4 v210, v[10:13], s[26:27]
	s_nop 1
	s_waitcnt vmcnt(4)
	v_lshlrev_b32_e32 v24, 16, v214
	v_lshlrev_b32_e32 v10, 16, v212
	v_lshlrev_b32_e32 v11, 16, v216
	v_and_b32_e32 v12, 0xffff0000, v212
	v_and_b32_e32 v13, 0xffff0000, v216
	v_lshlrev_b32_e32 v212, 16, v213
	v_lshlrev_b32_e32 v216, 16, v217
	v_and_b32_e32 v213, 0xffff0000, v213
	v_and_b32_e32 v217, 0xffff0000, v217
	v_lshlrev_b32_e32 v25, 16, v218
	v_and_b32_e32 v214, 0xffff0000, v214
	v_and_b32_e32 v218, 0xffff0000, v218
	v_lshlrev_b32_e32 v26, 16, v215
	v_lshlrev_b32_e32 v27, 16, v219
	v_and_b32_e32 v215, 0xffff0000, v215
	v_and_b32_e32 v219, 0xffff0000, v219
	v_fmac_f32_e32 v10, v6, v11
	v_fmac_f32_e32 v12, v7, v13
	v_fmac_f32_e32 v212, v8, v216
	v_fmac_f32_e32 v213, v9, v217
	v_fmac_f32_e32 v24, v2, v25
	v_fmac_f32_e32 v214, v3, v218
	v_fmac_f32_e32 v26, v4, v27
	v_fmac_f32_e32 v215, v5, v219
	v_cvt_pk_bf16_f32 v2, v10, v12
	v_cvt_pk_bf16_f32 v3, v212, v213
	v_cvt_pk_bf16_f32 v4, v24, v214
	v_cvt_pk_bf16_f32 v5, v26, v215
	global_store_dwordx4 v210, v[2:5], s[26:27] offset:256
	s_nop 1
	s_cbranch_vccz .LBB0_755
	s_waitcnt vmcnt(0)
	s_cmpk_gt_u32 s24, 0xff
	s_cbranch_scc1 .LBB0_766
	s_barrier

.LBB0_845:
	ds_read_b128 v[138:141], v147
	ds_read_b128 v[186:189], v147 offset:1024
	ds_read_b128 v[190:193], v147 offset:2048
	ds_read_b128 v[194:197], v147 offset:3072
	s_add_u32 s60, s58, 0xfffc0080
	s_addc_u32 s61, s59, -1
	s_cmp_eq_u32 s47, 12
	s_cselect_b32 s63, s21, s61
	s_cselect_b32 s62, s22, s60
	s_cselect_b32 s61, s23, s46
	s_cselect_b32 s60, s43, s45
	v_lshl_add_u64 v[142:143], s[58:59], 0, v[130:131]
	s_add_i32 m0, s57, 0xc000
	ds_read_b128 v[198:201], v158
	ds_read_b128 v[202:205], v158 offset:1024
	ds_read_b128 v[206:209], v158 offset:2048
	ds_read_b128 v[210:213], v158 offset:3072
	ds_read_b128 v[214:217], v158 offset:4096
	ds_read_b128 v[218:221], v158 offset:5120
	ds_read_b128 v[222:225], v158 offset:6144
	ds_read_b128 v[226:229], v158 offset:7168
	global_load_lds_dwordx4 v[142:143], off
	v_lshl_add_u64 v[142:143], s[58:59], 0, v[132:133]
	s_add_i32 m0, s57, 0xe000
	s_nop 0
	global_load_lds_dwordx4 v[142:143], off
	s_waitcnt lgkmcnt(8)
	s_barrier
	s_waitcnt lgkmcnt(0)
	s_waitcnt lgkmcnt(0)
	v_mfma_f32_16x16x32_bf16 v[126:129], v[138:141], v[198:201], v[126:129]
	v_mfma_f32_16x16x32_bf16 v[122:125], v[190:193], v[198:201], v[122:125]
	v_mfma_f32_16x16x32_bf16 v[110:113], v[138:141], v[206:209], v[110:113]
	v_mfma_f32_16x16x32_bf16 v[106:109], v[190:193], v[206:209], v[106:109]
	v_mfma_f32_16x16x32_bf16 v[94:97], v[138:141], v[214:217], v[94:97]
	v_mfma_f32_16x16x32_bf16 v[90:93], v[190:193], v[214:217], v[90:93]
	v_mfma_f32_16x16x32_bf16 v[78:81], v[138:141], v[222:225], v[78:81]
	v_mfma_f32_16x16x32_bf16 v[74:77], v[190:193], v[222:225], v[74:77]
	v_mfma_f32_16x16x32_bf16 v[126:129], v[186:189], v[202:205], v[126:129]
	v_mfma_f32_16x16x32_bf16 v[122:125], v[194:197], v[202:205], v[122:125]
	v_mfma_f32_16x16x32_bf16 v[110:113], v[186:189], v[210:213], v[110:113]
	v_mfma_f32_16x16x32_bf16 v[106:109], v[194:197], v[210:213], v[106:109]
	v_mfma_f32_16x16x32_bf16 v[94:97], v[186:189], v[218:221], v[94:97]
	v_mfma_f32_16x16x32_bf16 v[90:93], v[194:197], v[218:221], v[90:93]
	v_mfma_f32_16x16x32_bf16 v[78:81], v[186:189], v[226:229], v[78:81]
	v_mfma_f32_16x16x32_bf16 v[74:77], v[194:197], v[226:229], v[74:77]
	s_barrier
	s_add_i32 s76, s74, s66
	v_lshl_add_u64 v[142:143], s[60:61], 0, v[152:153]
	s_mov_b32 m0, s76
	ds_read_b128 v[230:233], v159
	ds_read_b128 v[234:237], v159 offset:1024
	ds_read_b128 v[238:241], v159 offset:2048
	ds_read_b128 v[242:245], v159 offset:3072
	global_load_lds_dwordx4 v[142:143], off
	v_lshl_add_u64 v[246:247], s[60:61], 0, v[156:157]
	s_add_i32 m0, s76, 0x2000
	s_nop 0
	global_load_lds_dwordx4 v[246:247], off
	s_barrier
	s_waitcnt lgkmcnt(0)
	s_waitcnt lgkmcnt(0)
	v_mfma_f32_16x16x32_bf16 v[118:121], v[230:233], v[198:201], v[118:121]
	v_mfma_f32_16x16x32_bf16 v[114:117], v[238:241], v[198:201], v[114:117]
	v_mfma_f32_16x16x32_bf16 v[102:105], v[230:233], v[206:209], v[102:105]
	v_mfma_f32_16x16x32_bf16 v[98:101], v[238:241], v[206:209], v[98:101]
	v_mfma_f32_16x16x32_bf16 v[86:89], v[230:233], v[214:217], v[86:89]
	v_mfma_f32_16x16x32_bf16 v[82:85], v[238:241], v[214:217], v[82:85]
	v_mfma_f32_16x16x32_bf16 v[70:73], v[230:233], v[222:225], v[70:73]
	v_mfma_f32_16x16x32_bf16 v[66:69], v[238:241], v[222:225], v[66:69]
	v_mfma_f32_16x16x32_bf16 v[118:121], v[234:237], v[202:205], v[118:121]
	v_mfma_f32_16x16x32_bf16 v[114:117], v[242:245], v[202:205], v[114:117]
	v_mfma_f32_16x16x32_bf16 v[102:105], v[234:237], v[210:213], v[102:105]
	v_mfma_f32_16x16x32_bf16 v[98:101], v[242:245], v[210:213], v[98:101]
	v_mfma_f32_16x16x32_bf16 v[86:89], v[234:237], v[218:221], v[86:89]
	v_mfma_f32_16x16x32_bf16 v[82:85], v[242:245], v[218:221], v[82:85]
	v_mfma_f32_16x16x32_bf16 v[70:73], v[234:237], v[226:229], v[70:73]
	v_mfma_f32_16x16x32_bf16 v[66:69], v[242:245], v[226:229], v[66:69]
	s_mov_b32 m0, s57
	v_lshl_add_u64 v[248:249], s[62:63], 0, v[150:151]
	s_barrier
	ds_read_b128 v[198:201], v158 offset:16384
	ds_read_b128 v[202:205], v158 offset:17408
	ds_read_b128 v[206:209], v158 offset:18432
	ds_read_b128 v[210:213], v158 offset:19456
	ds_read_b128 v[214:217], v158 offset:20480
	ds_read_b128 v[218:221], v158 offset:21504
	ds_read_b128 v[222:225], v158 offset:22528
	ds_read_b128 v[226:229], v158 offset:23552
	global_load_lds_dwordx4 v[248:249], off
	v_lshl_add_u64 v[250:251], s[62:63], 0, v[154:155]
	s_mov_b32 m0, s67
	s_nop 0
	global_load_lds_dwordx4 v[250:251], off
	s_barrier
	s_waitcnt lgkmcnt(0)
	s_waitcnt lgkmcnt(0)
	v_mfma_f32_16x16x32_bf16 v[62:65], v[138:141], v[198:201], v[62:65]
	v_mfma_f32_16x16x32_bf16 v[58:61], v[190:193], v[198:201], v[58:61]
	v_mfma_f32_16x16x32_bf16 v[46:49], v[138:141], v[206:209], v[46:49]
	v_mfma_f32_16x16x32_bf16 v[42:45], v[190:193], v[206:209], v[42:45]
	v_mfma_f32_16x16x32_bf16 v[30:33], v[138:141], v[214:217], v[30:33]
	v_mfma_f32_16x16x32_bf16 v[26:29], v[190:193], v[214:217], v[26:29]
	v_mfma_f32_16x16x32_bf16 v[14:17], v[138:141], v[222:225], v[14:17]
	v_mfma_f32_16x16x32_bf16 v[10:13], v[190:193], v[222:225], v[10:13]
	v_mfma_f32_16x16x32_bf16 v[62:65], v[186:189], v[202:205], v[62:65]
	v_mfma_f32_16x16x32_bf16 v[58:61], v[194:197], v[202:205], v[58:61]
	v_mfma_f32_16x16x32_bf16 v[46:49], v[186:189], v[210:213], v[46:49]
	v_mfma_f32_16x16x32_bf16 v[42:45], v[194:197], v[210:213], v[42:45]
	v_mfma_f32_16x16x32_bf16 v[30:33], v[186:189], v[218:221], v[30:33]
	v_mfma_f32_16x16x32_bf16 v[26:29], v[194:197], v[218:221], v[26:29]
	v_mfma_f32_16x16x32_bf16 v[14:17], v[186:189], v[226:229], v[14:17]
	v_mfma_f32_16x16x32_bf16 v[10:13], v[194:197], v[226:229], v[10:13]
	s_barrier
	s_add_u32 s76, s60, 0x40000
	s_addc_u32 s77, s61, 0
	s_add_i32 s78, s75, s66
	v_lshl_add_u64 v[138:139], s[76:77], 0, v[152:153]
	s_mov_b32 m0, s78
	s_nop 0
	global_load_lds_dwordx4 v[138:139], off
	v_lshl_add_u64 v[138:139], s[76:77], 0, v[156:157]
	s_add_i32 m0, s78, 0x2000
	s_nop 0
	global_load_lds_dwordx4 v[138:139], off
	s_waitcnt vmcnt(6)
	s_barrier
	v_mfma_f32_16x16x32_bf16 v[54:57], v[230:233], v[198:201], v[54:57]
	v_mfma_f32_16x16x32_bf16 v[50:53], v[238:241], v[198:201], v[50:53]
	v_mfma_f32_16x16x32_bf16 v[38:41], v[230:233], v[206:209], v[38:41]
	v_mfma_f32_16x16x32_bf16 v[34:37], v[238:241], v[206:209], v[34:37]
	v_mfma_f32_16x16x32_bf16 v[22:25], v[230:233], v[214:217], v[22:25]
	v_mfma_f32_16x16x32_bf16 v[18:21], v[238:241], v[214:217], v[18:21]
	v_mfma_f32_16x16x32_bf16 v[6:9], v[230:233], v[222:225], v[6:9]
	v_mfma_f32_16x16x32_bf16 v[2:5], v[238:241], v[222:225], v[2:5]
	v_mfma_f32_16x16x32_bf16 v[54:57], v[234:237], v[202:205], v[54:57]
	v_mfma_f32_16x16x32_bf16 v[50:53], v[242:245], v[202:205], v[50:53]
	v_mfma_f32_16x16x32_bf16 v[38:41], v[234:237], v[210:213], v[38:41]
	v_mfma_f32_16x16x32_bf16 v[34:37], v[242:245], v[210:213], v[34:37]
	v_mfma_f32_16x16x32_bf16 v[22:25], v[234:237], v[218:221], v[22:25]
	v_mfma_f32_16x16x32_bf16 v[18:21], v[242:245], v[218:221], v[18:21]
	v_mfma_f32_16x16x32_bf16 v[6:9], v[234:237], v[226:229], v[6:9]
	v_mfma_f32_16x16x32_bf16 v[2:5], v[242:245], v[226:229], v[2:5]
	s_add_i32 s76, 0, 0x18000
	v_add_u32_e32 v169, s76, v145
	s_barrier
	ds_read_b128 v[138:141], v169
	ds_read_b128 v[186:189], v169 offset:1024
	ds_read_b128 v[190:193], v169 offset:2048
	ds_read_b128 v[194:197], v169 offset:3072
	s_add_u32 s62, s62, 0x40000
	s_addc_u32 s63, s63, 0
	s_mov_b32 m0, s68
	v_lshl_add_u64 v[230:231], s[62:63], 0, v[150:151]
	ds_read_b128 v[198:201], v158 offset:32768
	ds_read_b128 v[202:205], v158 offset:33792
	ds_read_b128 v[206:209], v158 offset:34816
	ds_read_b128 v[210:213], v158 offset:35840
	ds_read_b128 v[214:217], v158 offset:36864
	ds_read_b128 v[218:221], v158 offset:37888
	ds_read_b128 v[222:225], v158 offset:38912
	ds_read_b128 v[226:229], v158 offset:39936
	global_load_lds_dwordx4 v[230:231], off
	v_lshl_add_u64 v[230:231], s[62:63], 0, v[154:155]
	s_mov_b32 m0, s69
	s_nop 0
	global_load_lds_dwordx4 v[230:231], off
	s_waitcnt lgkmcnt(8)
	s_barrier
	s_waitcnt lgkmcnt(0)
	s_waitcnt lgkmcnt(0)
	v_mfma_f32_16x16x32_bf16 v[126:129], v[138:141], v[198:201], v[126:129]
	v_mfma_f32_16x16x32_bf16 v[122:125], v[190:193], v[198:201], v[122:125]
	v_mfma_f32_16x16x32_bf16 v[110:113], v[138:141], v[206:209], v[110:113]
	v_mfma_f32_16x16x32_bf16 v[106:109], v[190:193], v[206:209], v[106:109]
	v_mfma_f32_16x16x32_bf16 v[94:97], v[138:141], v[214:217], v[94:97]
	v_mfma_f32_16x16x32_bf16 v[90:93], v[190:193], v[214:217], v[90:93]
	v_mfma_f32_16x16x32_bf16 v[78:81], v[138:141], v[222:225], v[78:81]
	v_mfma_f32_16x16x32_bf16 v[74:77], v[190:193], v[222:225], v[74:77]
	v_mfma_f32_16x16x32_bf16 v[126:129], v[186:189], v[202:205], v[126:129]
	v_mfma_f32_16x16x32_bf16 v[122:125], v[194:197], v[202:205], v[122:125]
	v_mfma_f32_16x16x32_bf16 v[110:113], v[186:189], v[210:213], v[110:113]
	v_mfma_f32_16x16x32_bf16 v[106:109], v[194:197], v[210:213], v[106:109]
	v_mfma_f32_16x16x32_bf16 v[94:97], v[186:189], v[218:221], v[94:97]
	v_mfma_f32_16x16x32_bf16 v[90:93], v[194:197], v[218:221], v[90:93]
	v_mfma_f32_16x16x32_bf16 v[78:81], v[186:189], v[226:229], v[78:81]
	v_mfma_f32_16x16x32_bf16 v[74:77], v[194:197], v[226:229], v[74:77]
	s_barrier
	s_add_i32 s62, 0, 0x1c000
	s_add_i32 s63, s76, s66
	v_add_u32_e32 v169, s62, v145
	v_lshl_add_u64 v[142:143], v[142:143], 0, s[4:5]
	s_mov_b32 m0, s63
	ds_read_b128 v[230:233], v169
	ds_read_b128 v[234:237], v169 offset:1024
	ds_read_b128 v[238:241], v169 offset:2048
	ds_read_b128 v[242:245], v169 offset:3072
	global_load_lds_dwordx4 v[142:143], off
	v_lshl_add_u64 v[142:143], v[246:247], 0, s[4:5]
	s_add_i32 m0, s63, 0x2000
	s_nop 0
	global_load_lds_dwordx4 v[142:143], off
	s_barrier
	s_waitcnt lgkmcnt(0)
	s_waitcnt lgkmcnt(0)
	v_mfma_f32_16x16x32_bf16 v[118:121], v[230:233], v[198:201], v[118:121]
	v_mfma_f32_16x16x32_bf16 v[114:117], v[238:241], v[198:201], v[114:117]
	v_mfma_f32_16x16x32_bf16 v[102:105], v[230:233], v[206:209], v[102:105]
	v_mfma_f32_16x16x32_bf16 v[98:101], v[238:241], v[206:209], v[98:101]
	v_mfma_f32_16x16x32_bf16 v[86:89], v[230:233], v[214:217], v[86:89]
	v_mfma_f32_16x16x32_bf16 v[82:85], v[238:241], v[214:217], v[82:85]
	v_mfma_f32_16x16x32_bf16 v[70:73], v[230:233], v[222:225], v[70:73]
	v_mfma_f32_16x16x32_bf16 v[66:69], v[238:241], v[222:225], v[66:69]
	v_mfma_f32_16x16x32_bf16 v[118:121], v[234:237], v[202:205], v[118:121]
	v_mfma_f32_16x16x32_bf16 v[114:117], v[242:245], v[202:205], v[114:117]
	v_mfma_f32_16x16x32_bf16 v[102:105], v[234:237], v[210:213], v[102:105]
	v_mfma_f32_16x16x32_bf16 v[98:101], v[242:245], v[210:213], v[98:101]
	v_mfma_f32_16x16x32_bf16 v[86:89], v[234:237], v[218:221], v[86:89]
	v_mfma_f32_16x16x32_bf16 v[82:85], v[242:245], v[218:221], v[82:85]
	v_mfma_f32_16x16x32_bf16 v[70:73], v[234:237], v[226:229], v[70:73]
	v_mfma_f32_16x16x32_bf16 v[66:69], v[242:245], v[226:229], v[66:69]
	s_mov_b32 m0, s71
	v_lshl_add_u64 v[142:143], v[248:249], 0, s[4:5]
	s_barrier
	ds_read_b128 v[198:201], v158 offset:49152
	ds_read_b128 v[202:205], v158 offset:50176
	ds_read_b128 v[206:209], v158 offset:51200
	ds_read_b128 v[210:213], v158 offset:52224
	ds_read_b128 v[214:217], v158 offset:53248
	ds_read_b128 v[218:221], v158 offset:54272
	ds_read_b128 v[222:225], v158 offset:55296
	ds_read_b128 v[226:229], v158 offset:56320
	global_load_lds_dwordx4 v[142:143], off
	v_lshl_add_u64 v[142:143], v[250:251], 0, s[4:5]
	s_mov_b32 m0, s72
	s_nop 0
	global_load_lds_dwordx4 v[142:143], off
	s_barrier
	s_waitcnt lgkmcnt(0)
	s_waitcnt lgkmcnt(0)
	v_mfma_f32_16x16x32_bf16 v[62:65], v[138:141], v[198:201], v[62:65]
	v_mfma_f32_16x16x32_bf16 v[58:61], v[190:193], v[198:201], v[58:61]
	v_mfma_f32_16x16x32_bf16 v[46:49], v[138:141], v[206:209], v[46:49]
	v_mfma_f32_16x16x32_bf16 v[42:45], v[190:193], v[206:209], v[42:45]
	v_mfma_f32_16x16x32_bf16 v[30:33], v[138:141], v[214:217], v[30:33]
	v_mfma_f32_16x16x32_bf16 v[26:29], v[190:193], v[214:217], v[26:29]
	v_mfma_f32_16x16x32_bf16 v[14:17], v[138:141], v[222:225], v[14:17]
	v_mfma_f32_16x16x32_bf16 v[10:13], v[190:193], v[222:225], v[10:13]
	v_mfma_f32_16x16x32_bf16 v[62:65], v[186:189], v[202:205], v[62:65]
	v_mfma_f32_16x16x32_bf16 v[58:61], v[194:197], v[202:205], v[58:61]
	v_mfma_f32_16x16x32_bf16 v[46:49], v[186:189], v[210:213], v[46:49]
	v_mfma_f32_16x16x32_bf16 v[42:45], v[194:197], v[210:213], v[42:45]
	v_mfma_f32_16x16x32_bf16 v[30:33], v[186:189], v[218:221], v[30:33]
	v_mfma_f32_16x16x32_bf16 v[26:29], v[194:197], v[218:221], v[26:29]
	v_mfma_f32_16x16x32_bf16 v[14:17], v[186:189], v[226:229], v[14:17]
	v_mfma_f32_16x16x32_bf16 v[10:13], v[194:197], v[226:229], v[10:13]
	s_barrier
	s_add_u32 s60, s60, 0x40080
	s_addc_u32 s61, s61, 0
	s_add_i32 s62, s62, s66
	v_lshl_add_u64 v[138:139], s[60:61], 0, v[152:153]
	s_mov_b32 m0, s62
	s_nop 0
	global_load_lds_dwordx4 v[138:139], off
	v_lshl_add_u64 v[138:139], s[60:61], 0, v[156:157]
	s_add_i32 m0, s62, 0x2000
	s_nop 0
	global_load_lds_dwordx4 v[138:139], off
	s_waitcnt vmcnt(6)
	s_barrier
	v_mfma_f32_16x16x32_bf16 v[54:57], v[230:233], v[198:201], v[54:57]
	v_mfma_f32_16x16x32_bf16 v[50:53], v[238:241], v[198:201], v[50:53]
	v_mfma_f32_16x16x32_bf16 v[38:41], v[230:233], v[206:209], v[38:41]
	v_mfma_f32_16x16x32_bf16 v[34:37], v[238:241], v[206:209], v[34:37]
	v_mfma_f32_16x16x32_bf16 v[22:25], v[230:233], v[214:217], v[22:25]
	v_mfma_f32_16x16x32_bf16 v[18:21], v[238:241], v[214:217], v[18:21]
	v_mfma_f32_16x16x32_bf16 v[6:9], v[230:233], v[222:225], v[6:9]
	v_mfma_f32_16x16x32_bf16 v[2:5], v[238:241], v[222:225], v[2:5]
	v_mfma_f32_16x16x32_bf16 v[54:57], v[234:237], v[202:205], v[54:57]
	v_mfma_f32_16x16x32_bf16 v[50:53], v[242:245], v[202:205], v[50:53]
	v_mfma_f32_16x16x32_bf16 v[38:41], v[234:237], v[210:213], v[38:41]
	v_mfma_f32_16x16x32_bf16 v[34:37], v[242:245], v[210:213], v[34:37]
	v_mfma_f32_16x16x32_bf16 v[22:25], v[234:237], v[218:221], v[22:25]
	v_mfma_f32_16x16x32_bf16 v[18:21], v[242:245], v[218:221], v[18:21]
	v_mfma_f32_16x16x32_bf16 v[6:9], v[234:237], v[226:229], v[6:9]
	v_mfma_f32_16x16x32_bf16 v[2:5], v[242:245], v[226:229], v[2:5]
	s_add_i32 s47, s47, 2
	s_add_u32 s58, s58, 0x100
	s_addc_u32 s59, s59, 0
	s_add_u32 s45, s45, 0x100
	s_addc_u32 s46, s46, 0
	s_cmp_gt_u32 s47, 13
	s_barrier
	s_cbranch_scc0 .LBB0_845
	v_lshl_add_u32 v142, s56, 8, v144
	v_lshl_or_b32 v140, s20, 8, v146
	v_ashrrev_i32_e32 v143, 31, v142
	v_ashrrev_i32_e32 v141, 31, v140
	v_lshlrev_b64 v[138:139], 10, v[142:143]
	v_lshl_add_u64 v[138:139], v[138:139], 0, v[140:141]
	v_lshl_add_u64 v[194:195], v[138:139], 2, s[52:53]
	global_load_dwordx4 v[186:189], v[194:195], off
	global_load_dwordx4 v[190:193], v[194:195], off offset:16
	v_lshl_add_u64 v[196:197], v[138:139], 1, s[8:9]
	s_and_b64 vcc, exec, s[2:3]
	s_mov_b32 s20, s42
	s_mov_b32 s56, s44
	s_mov_b64 s[60:61], s[50:51]
	s_mov_b64 s[58:59], s[48:49]
	s_waitcnt vmcnt(0)
	v_pk_add_f32 v[126:127], v[126:127], v[186:187]
	v_pk_add_f32 v[186:187], v[124:125], v[192:193]
	v_pk_add_f32 v[124:125], v[122:123], v[190:191]
	v_pk_add_f32 v[128:129], v[128:129], v[188:189]
	v_cvt_pk_bf16_f32 v122, v126, v127
	s_nop 0
	v_cvt_pk_bf16_f32 v123, v128, v129
	v_cvt_pk_bf16_f32 v124, v124, v125
	v_cvt_pk_bf16_f32 v125, v186, v187
	global_store_dwordx4 v[196:197], v[122:125], off
	global_load_dwordx4 v[122:125], v[194:195], off offset:512
	s_nop 0
	global_load_dwordx4 v[126:129], v[194:195], off offset:528
	v_or_b32_e32 v186, 16, v142
	v_ashrrev_i32_e32 v187, 31, v186
	v_lshlrev_b64 v[186:187], 10, v[186:187]
	v_lshl_add_u64 v[186:187], v[186:187], 0, v[140:141]
	v_lshl_add_u64 v[188:189], v[186:187], 2, s[52:53]
	s_waitcnt vmcnt(0)
	v_pk_add_f32 v[118:119], v[118:119], v[122:123]
	v_pk_add_f32 v[122:123], v[116:117], v[128:129]
	v_pk_add_f32 v[116:117], v[114:115], v[126:127]
	v_pk_add_f32 v[120:121], v[120:121], v[124:125]
	v_cvt_pk_bf16_f32 v114, v118, v119
	s_nop 0
	v_cvt_pk_bf16_f32 v115, v120, v121
	v_cvt_pk_bf16_f32 v116, v116, v117
	v_cvt_pk_bf16_f32 v117, v122, v123
	global_store_dwordx4 v[196:197], v[114:117], off offset:256
	global_load_dwordx4 v[114:117], v[188:189], off
	s_nop 0
	global_load_dwordx4 v[118:121], v[188:189], off offset:16
	v_lshl_add_u64 v[122:123], v[186:187], 1, s[8:9]
	s_waitcnt vmcnt(0)
	v_pk_add_f32 v[110:111], v[110:111], v[114:115]
	v_pk_add_f32 v[114:115], v[108:109], v[120:121]
	v_pk_add_f32 v[108:109], v[106:107], v[118:119]
	v_pk_add_f32 v[112:113], v[112:113], v[116:117]
	v_cvt_pk_bf16_f32 v106, v110, v111
	s_nop 0
	v_cvt_pk_bf16_f32 v107, v112, v113
	v_cvt_pk_bf16_f32 v108, v108, v109
	v_cvt_pk_bf16_f32 v109, v114, v115
	global_store_dwordx4 v[122:123], v[106:109], off
	global_load_dwordx4 v[106:109], v[188:189], off offset:512
	s_nop 0
	global_load_dwordx4 v[110:113], v[188:189], off offset:528
	v_or_b32_e32 v114, 32, v142
	v_ashrrev_i32_e32 v115, 31, v114
	v_lshlrev_b64 v[114:115], 10, v[114:115]
	v_lshl_add_u64 v[114:115], v[114:115], 0, v[140:141]
	v_lshl_add_u64 v[116:117], v[114:115], 2, s[52:53]
	s_waitcnt vmcnt(0)
	v_pk_add_f32 v[102:103], v[102:103], v[106:107]
	v_pk_add_f32 v[106:107], v[100:101], v[112:113]
	v_pk_add_f32 v[100:101], v[98:99], v[110:111]
	v_pk_add_f32 v[104:105], v[104:105], v[108:109]
	v_cvt_pk_bf16_f32 v98, v102, v103
	s_nop 0
	v_cvt_pk_bf16_f32 v99, v104, v105
	v_cvt_pk_bf16_f32 v100, v100, v101
	v_cvt_pk_bf16_f32 v101, v106, v107
	global_store_dwordx4 v[122:123], v[98:101], off offset:256
	global_load_dwordx4 v[98:101], v[116:117], off
	s_nop 0
	global_load_dwordx4 v[102:105], v[116:117], off offset:16
	v_lshl_add_u64 v[106:107], v[114:115], 1, s[8:9]
	s_waitcnt vmcnt(0)
	v_pk_add_f32 v[94:95], v[94:95], v[98:99]
	v_pk_add_f32 v[98:99], v[92:93], v[104:105]
	v_pk_add_f32 v[92:93], v[90:91], v[102:103]
	v_pk_add_f32 v[96:97], v[96:97], v[100:101]
	v_cvt_pk_bf16_f32 v90, v94, v95
	s_nop 0
	v_cvt_pk_bf16_f32 v91, v96, v97
	v_cvt_pk_bf16_f32 v92, v92, v93
	v_cvt_pk_bf16_f32 v93, v98, v99
	global_store_dwordx4 v[106:107], v[90:93], off
	global_load_dwordx4 v[90:93], v[116:117], off offset:512
	s_nop 0
	global_load_dwordx4 v[94:97], v[116:117], off offset:528
	v_or_b32_e32 v98, 48, v142
	v_ashrrev_i32_e32 v99, 31, v98
	v_lshlrev_b64 v[98:99], 10, v[98:99]
	v_lshl_add_u64 v[98:99], v[98:99], 0, v[140:141]
	v_lshl_add_u64 v[100:101], v[98:99], 2, s[52:53]
	s_waitcnt vmcnt(0)
	v_pk_add_f32 v[86:87], v[86:87], v[90:91]
	v_pk_add_f32 v[90:91], v[84:85], v[96:97]
	v_pk_add_f32 v[84:85], v[82:83], v[94:95]
	v_pk_add_f32 v[88:89], v[88:89], v[92:93]
	v_cvt_pk_bf16_f32 v82, v86, v87
	s_nop 0
	v_cvt_pk_bf16_f32 v83, v88, v89
	v_cvt_pk_bf16_f32 v84, v84, v85
	v_cvt_pk_bf16_f32 v85, v90, v91
	global_store_dwordx4 v[106:107], v[82:85], off offset:256
	global_load_dwordx4 v[82:85], v[100:101], off
	s_nop 0
	global_load_dwordx4 v[86:89], v[100:101], off offset:16
	v_lshl_add_u64 v[90:91], v[98:99], 1, s[8:9]
	s_waitcnt vmcnt(0)
	v_pk_add_f32 v[78:79], v[78:79], v[82:83]
	v_pk_add_f32 v[82:83], v[76:77], v[88:89]
	v_pk_add_f32 v[76:77], v[74:75], v[86:87]
	v_pk_add_f32 v[80:81], v[80:81], v[84:85]
	v_cvt_pk_bf16_f32 v74, v78, v79
	s_nop 0
	v_cvt_pk_bf16_f32 v75, v80, v81
	v_cvt_pk_bf16_f32 v76, v76, v77
	v_cvt_pk_bf16_f32 v77, v82, v83
	global_store_dwordx4 v[90:91], v[74:77], off
	global_load_dwordx4 v[74:77], v[100:101], off offset:512
	s_nop 0
	global_load_dwordx4 v[78:81], v[100:101], off offset:528
	v_lshl_add_u64 v[82:83], v[138:139], 0, s[34:35]
	v_lshl_add_u64 v[84:85], v[82:83], 2, s[52:53]
	s_waitcnt vmcnt(0)
	v_pk_add_f32 v[70:71], v[70:71], v[74:75]
	v_pk_add_f32 v[74:75], v[68:69], v[80:81]
	v_pk_add_f32 v[68:69], v[66:67], v[78:79]
	v_pk_add_f32 v[72:73], v[72:73], v[76:77]
	v_cvt_pk_bf16_f32 v66, v70, v71
	s_nop 0
	v_cvt_pk_bf16_f32 v67, v72, v73
	v_cvt_pk_bf16_f32 v68, v68, v69
	v_cvt_pk_bf16_f32 v69, v74, v75
	global_store_dwordx4 v[90:91], v[66:69], off offset:256
	global_load_dwordx4 v[66:69], v[84:85], off
	s_nop 0
	global_load_dwordx4 v[70:73], v[84:85], off offset:16
	v_lshl_add_u64 v[74:75], v[82:83], 1, s[8:9]
	s_waitcnt vmcnt(0)
	v_pk_add_f32 v[62:63], v[62:63], v[66:67]
	v_pk_add_f32 v[66:67], v[60:61], v[72:73]
	v_pk_add_f32 v[60:61], v[58:59], v[70:71]
	v_pk_add_f32 v[64:65], v[64:65], v[68:69]
	v_cvt_pk_bf16_f32 v58, v62, v63
	s_nop 0
	v_cvt_pk_bf16_f32 v59, v64, v65
	v_cvt_pk_bf16_f32 v60, v60, v61
	v_cvt_pk_bf16_f32 v61, v66, v67
	global_store_dwordx4 v[74:75], v[58:61], off
	global_load_dwordx4 v[58:61], v[84:85], off offset:512
	s_nop 0
	global_load_dwordx4 v[62:65], v[84:85], off offset:528
	v_lshl_add_u64 v[66:67], v[138:139], 0, s[36:37]
	v_lshl_add_u64 v[68:69], v[66:67], 2, s[52:53]
	s_waitcnt vmcnt(0)
	v_pk_add_f32 v[54:55], v[54:55], v[58:59]
	v_pk_add_f32 v[58:59], v[52:53], v[64:65]
	v_pk_add_f32 v[52:53], v[50:51], v[62:63]
	v_pk_add_f32 v[56:57], v[56:57], v[60:61]
	v_cvt_pk_bf16_f32 v50, v54, v55
	s_nop 0
	v_cvt_pk_bf16_f32 v51, v56, v57
	v_cvt_pk_bf16_f32 v52, v52, v53
	v_cvt_pk_bf16_f32 v53, v58, v59
	global_store_dwordx4 v[74:75], v[50:53], off offset:256
	global_load_dwordx4 v[50:53], v[68:69], off
	s_nop 0
	global_load_dwordx4 v[54:57], v[68:69], off offset:16
	v_lshl_add_u64 v[58:59], v[66:67], 1, s[8:9]
	s_waitcnt vmcnt(0)
	v_pk_add_f32 v[46:47], v[46:47], v[50:51]
	v_pk_add_f32 v[50:51], v[44:45], v[56:57]
	v_pk_add_f32 v[44:45], v[42:43], v[54:55]
	v_pk_add_f32 v[48:49], v[48:49], v[52:53]
	v_cvt_pk_bf16_f32 v42, v46, v47
	s_nop 0
	v_cvt_pk_bf16_f32 v43, v48, v49
	v_cvt_pk_bf16_f32 v44, v44, v45
	v_cvt_pk_bf16_f32 v45, v50, v51
	global_store_dwordx4 v[58:59], v[42:45], off
	global_load_dwordx4 v[42:45], v[68:69], off offset:512
	s_nop 0
	global_load_dwordx4 v[46:49], v[68:69], off offset:528
	v_lshl_add_u64 v[50:51], v[138:139], 0, s[38:39]
	v_lshl_add_u64 v[52:53], v[50:51], 2, s[52:53]
	s_waitcnt vmcnt(0)
	v_pk_add_f32 v[38:39], v[38:39], v[42:43]
	v_pk_add_f32 v[42:43], v[36:37], v[48:49]
	v_pk_add_f32 v[36:37], v[34:35], v[46:47]
	v_pk_add_f32 v[40:41], v[40:41], v[44:45]
	v_cvt_pk_bf16_f32 v34, v38, v39
	s_nop 0
	v_cvt_pk_bf16_f32 v35, v40, v41
	v_cvt_pk_bf16_f32 v36, v36, v37
	v_cvt_pk_bf16_f32 v37, v42, v43
	global_store_dwordx4 v[58:59], v[34:37], off offset:256
	global_load_dwordx4 v[34:37], v[52:53], off
	s_nop 0
	global_load_dwordx4 v[38:41], v[52:53], off offset:16
	v_lshl_add_u64 v[42:43], v[50:51], 1, s[8:9]
	s_waitcnt vmcnt(0)
	v_pk_add_f32 v[30:31], v[30:31], v[34:35]
	v_pk_add_f32 v[34:35], v[28:29], v[40:41]
	v_pk_add_f32 v[28:29], v[26:27], v[38:39]
	v_pk_add_f32 v[32:33], v[32:33], v[36:37]
	v_cvt_pk_bf16_f32 v26, v30, v31
	s_nop 0
	v_cvt_pk_bf16_f32 v27, v32, v33
	v_cvt_pk_bf16_f32 v28, v28, v29
	v_cvt_pk_bf16_f32 v29, v34, v35
	global_store_dwordx4 v[42:43], v[26:29], off
	global_load_dwordx4 v[26:29], v[52:53], off offset:512
	s_nop 0
	global_load_dwordx4 v[30:33], v[52:53], off offset:528
	v_lshl_add_u64 v[34:35], v[138:139], 0, s[40:41]
	v_lshl_add_u64 v[36:37], v[34:35], 2, s[52:53]
	s_waitcnt vmcnt(0)
	v_pk_add_f32 v[22:23], v[22:23], v[26:27]
	v_pk_add_f32 v[26:27], v[20:21], v[32:33]
	v_pk_add_f32 v[20:21], v[18:19], v[30:31]
	v_pk_add_f32 v[24:25], v[24:25], v[28:29]
	v_cvt_pk_bf16_f32 v18, v22, v23
	s_nop 0
	v_cvt_pk_bf16_f32 v19, v24, v25
	v_cvt_pk_bf16_f32 v20, v20, v21
	v_cvt_pk_bf16_f32 v21, v26, v27
	global_store_dwordx4 v[42:43], v[18:21], off offset:256
	global_load_dwordx4 v[18:21], v[36:37], off
	s_nop 0
	global_load_dwordx4 v[22:25], v[36:37], off offset:16
	v_lshl_add_u64 v[26:27], v[34:35], 1, s[8:9]
	s_waitcnt vmcnt(0)
	v_pk_add_f32 v[14:15], v[14:15], v[18:19]
	v_pk_add_f32 v[18:19], v[12:13], v[24:25]
	v_pk_add_f32 v[12:13], v[10:11], v[22:23]
	v_pk_add_f32 v[16:17], v[16:17], v[20:21]
	v_cvt_pk_bf16_f32 v10, v14, v15
	s_nop 0
	v_cvt_pk_bf16_f32 v11, v16, v17
	v_cvt_pk_bf16_f32 v12, v12, v13
	v_cvt_pk_bf16_f32 v13, v18, v19
	global_store_dwordx4 v[26:27], v[10:13], off
	global_load_dwordx4 v[10:13], v[36:37], off offset:512
	s_nop 0
	global_load_dwordx4 v[14:17], v[36:37], off offset:528
	s_waitcnt vmcnt(0)
	v_pk_add_f32 v[6:7], v[6:7], v[10:11]
	v_pk_add_f32 v[10:11], v[4:5], v[16:17]
	v_pk_add_f32 v[4:5], v[2:3], v[14:15]
	v_pk_add_f32 v[8:9], v[8:9], v[12:13]
	v_cvt_pk_bf16_f32 v2, v6, v7
	s_nop 0
	v_cvt_pk_bf16_f32 v3, v8, v9
	v_cvt_pk_bf16_f32 v4, v4, v5
	v_cvt_pk_bf16_f32 v5, v10, v11
	global_store_dwordx4 v[26:27], v[2:5], off offset:256
	s_cbranch_vccz .LBB0_838
	s_waitcnt vmcnt(0)
	s_cmpk_gt_u32 s64, 0xff
	s_cbranch_scc1 .LBB0_849
	s_barrier

.LBB0_862:
	v_add_u32_e32 v159, s67, v142
	s_add_u32 s58, s0, s56
	ds_read_b128 v[144:147], v159
	ds_read_b128 v[186:189], v159 offset:1024
	ds_read_b128 v[190:193], v159 offset:2048
	ds_read_b128 v[194:197], v159 offset:3072
	s_addc_u32 s59, s1, s57
	s_add_u32 s58, s58, 0x100
	s_addc_u32 s59, s59, 0
	s_add_u32 s73, s49, s56
	s_addc_u32 s74, s69, s57
	s_cmpk_eq_i32 s56, 0x700
	s_cselect_b32 s61, s43, s59
	s_cselect_b32 s60, s70, s58
	s_cselect_b32 s59, s41, s74
	s_cselect_b32 s58, s71, s73
	v_lshl_add_u64 v[230:231], v[138:139], 0, s[56:57]
	s_add_i32 m0, s23, 0xc000
	ds_read_b128 v[198:201], v143
	ds_read_b128 v[202:205], v143 offset:1024
	ds_read_b128 v[206:209], v143 offset:2048
	ds_read_b128 v[210:213], v143 offset:3072
	ds_read_b128 v[214:217], v143 offset:4096
	ds_read_b128 v[218:221], v143 offset:5120
	ds_read_b128 v[222:225], v143 offset:6144
	ds_read_b128 v[226:229], v143 offset:7168
	global_load_lds_dwordx4 v[230:231], off
	v_lshl_add_u64 v[230:231], v[140:141], 0, s[56:57]
	s_add_i32 m0, s23, 0xe000
	s_nop 0
	global_load_lds_dwordx4 v[230:231], off
	s_waitcnt lgkmcnt(8)
	s_barrier
	s_waitcnt lgkmcnt(0)
	s_waitcnt lgkmcnt(0)
	v_mfma_f32_16x16x32_bf16 v[126:129], v[144:147], v[198:201], v[126:129]
	v_mfma_f32_16x16x32_bf16 v[122:125], v[190:193], v[198:201], v[122:125]
	v_mfma_f32_16x16x32_bf16 v[110:113], v[144:147], v[206:209], v[110:113]
	v_mfma_f32_16x16x32_bf16 v[106:109], v[190:193], v[206:209], v[106:109]
	v_mfma_f32_16x16x32_bf16 v[94:97], v[144:147], v[214:217], v[94:97]
	v_mfma_f32_16x16x32_bf16 v[90:93], v[190:193], v[214:217], v[90:93]
	v_mfma_f32_16x16x32_bf16 v[78:81], v[144:147], v[222:225], v[78:81]
	v_mfma_f32_16x16x32_bf16 v[74:77], v[190:193], v[222:225], v[74:77]
	v_mfma_f32_16x16x32_bf16 v[126:129], v[186:189], v[202:205], v[126:129]
	v_mfma_f32_16x16x32_bf16 v[122:125], v[194:197], v[202:205], v[122:125]
	v_mfma_f32_16x16x32_bf16 v[110:113], v[186:189], v[210:213], v[110:113]
	v_mfma_f32_16x16x32_bf16 v[106:109], v[194:197], v[210:213], v[106:109]
	v_mfma_f32_16x16x32_bf16 v[94:97], v[186:189], v[218:221], v[94:97]
	v_mfma_f32_16x16x32_bf16 v[90:93], v[194:197], v[218:221], v[90:93]
	v_mfma_f32_16x16x32_bf16 v[78:81], v[186:189], v[226:229], v[78:81]
	v_mfma_f32_16x16x32_bf16 v[74:77], v[194:197], v[226:229], v[74:77]
	s_barrier
	s_add_i32 s73, s67, s21
	v_add_u32_e32 v159, s68, v142
	v_lshl_add_u64 v[246:247], s[58:59], 0, v[152:153]
	s_mov_b32 m0, s73
	ds_read_b128 v[230:233], v159
	ds_read_b128 v[234:237], v159 offset:1024
	ds_read_b128 v[238:241], v159 offset:2048
	ds_read_b128 v[242:245], v159 offset:3072
	global_load_lds_dwordx4 v[246:247], off
	v_lshl_add_u64 v[248:249], s[58:59], 0, v[156:157]
	s_add_i32 m0, s73, 0x2000
	s_nop 0
	global_load_lds_dwordx4 v[248:249], off
	s_barrier
	s_waitcnt lgkmcnt(0)
	s_waitcnt lgkmcnt(0)
	v_mfma_f32_16x16x32_bf16 v[118:121], v[230:233], v[198:201], v[118:121]
	v_mfma_f32_16x16x32_bf16 v[114:117], v[238:241], v[198:201], v[114:117]
	v_mfma_f32_16x16x32_bf16 v[102:105], v[230:233], v[206:209], v[102:105]
	v_mfma_f32_16x16x32_bf16 v[98:101], v[238:241], v[206:209], v[98:101]
	v_mfma_f32_16x16x32_bf16 v[86:89], v[230:233], v[214:217], v[86:89]
	v_mfma_f32_16x16x32_bf16 v[82:85], v[238:241], v[214:217], v[82:85]
	v_mfma_f32_16x16x32_bf16 v[70:73], v[230:233], v[222:225], v[70:73]
	v_mfma_f32_16x16x32_bf16 v[66:69], v[238:241], v[222:225], v[66:69]
	v_mfma_f32_16x16x32_bf16 v[118:121], v[234:237], v[202:205], v[118:121]
	v_mfma_f32_16x16x32_bf16 v[114:117], v[242:245], v[202:205], v[114:117]
	v_mfma_f32_16x16x32_bf16 v[102:105], v[234:237], v[210:213], v[102:105]
	v_mfma_f32_16x16x32_bf16 v[98:101], v[242:245], v[210:213], v[98:101]
	v_mfma_f32_16x16x32_bf16 v[86:89], v[234:237], v[218:221], v[86:89]
	v_mfma_f32_16x16x32_bf16 v[82:85], v[242:245], v[218:221], v[82:85]
	v_mfma_f32_16x16x32_bf16 v[70:73], v[234:237], v[226:229], v[70:73]
	v_mfma_f32_16x16x32_bf16 v[66:69], v[242:245], v[226:229], v[66:69]
	s_mov_b32 m0, s23
	v_lshl_add_u64 v[250:251], s[60:61], 0, v[150:151]
	s_barrier
	ds_read_b128 v[198:201], v143 offset:16384
	ds_read_b128 v[202:205], v143 offset:17408
	ds_read_b128 v[206:209], v143 offset:18432
	ds_read_b128 v[210:213], v143 offset:19456
	ds_read_b128 v[214:217], v143 offset:20480
	ds_read_b128 v[218:221], v143 offset:21504
	ds_read_b128 v[222:225], v143 offset:22528
	ds_read_b128 v[226:229], v143 offset:23552
	global_load_lds_dwordx4 v[250:251], off
	v_lshl_add_u64 v[252:253], s[60:61], 0, v[154:155]
	s_mov_b32 m0, s35
	s_nop 0
	global_load_lds_dwordx4 v[252:253], off
	s_barrier
	s_waitcnt lgkmcnt(0)
	s_waitcnt lgkmcnt(0)
	v_mfma_f32_16x16x32_bf16 v[62:65], v[144:147], v[198:201], v[62:65]
	v_mfma_f32_16x16x32_bf16 v[58:61], v[190:193], v[198:201], v[58:61]
	v_mfma_f32_16x16x32_bf16 v[46:49], v[144:147], v[206:209], v[46:49]
	v_mfma_f32_16x16x32_bf16 v[42:45], v[190:193], v[206:209], v[42:45]
	v_mfma_f32_16x16x32_bf16 v[30:33], v[144:147], v[214:217], v[30:33]
	v_mfma_f32_16x16x32_bf16 v[26:29], v[190:193], v[214:217], v[26:29]
	v_mfma_f32_16x16x32_bf16 v[14:17], v[144:147], v[222:225], v[14:17]
	v_mfma_f32_16x16x32_bf16 v[10:13], v[190:193], v[222:225], v[10:13]
	v_mfma_f32_16x16x32_bf16 v[62:65], v[186:189], v[202:205], v[62:65]
	v_mfma_f32_16x16x32_bf16 v[58:61], v[194:197], v[202:205], v[58:61]
	v_mfma_f32_16x16x32_bf16 v[46:49], v[186:189], v[210:213], v[46:49]
	v_mfma_f32_16x16x32_bf16 v[42:45], v[194:197], v[210:213], v[42:45]
	v_mfma_f32_16x16x32_bf16 v[30:33], v[186:189], v[218:221], v[30:33]
	v_mfma_f32_16x16x32_bf16 v[26:29], v[194:197], v[218:221], v[26:29]
	v_mfma_f32_16x16x32_bf16 v[14:17], v[186:189], v[226:229], v[14:17]
	v_mfma_f32_16x16x32_bf16 v[10:13], v[194:197], v[226:229], v[10:13]
	s_barrier
	s_add_u32 s74, s58, 0x40000
	s_addc_u32 s75, s59, 0
	s_add_i32 s73, s68, s21
	v_lshl_add_u64 v[144:145], s[74:75], 0, v[152:153]
	s_mov_b32 m0, s73
	s_nop 0
	global_load_lds_dwordx4 v[144:145], off
	v_lshl_add_u64 v[144:145], s[74:75], 0, v[156:157]
	s_add_i32 m0, s73, 0x2000
	s_nop 0
	global_load_lds_dwordx4 v[144:145], off
	s_waitcnt vmcnt(6)
	s_barrier
	v_mfma_f32_16x16x32_bf16 v[54:57], v[230:233], v[198:201], v[54:57]
	v_mfma_f32_16x16x32_bf16 v[50:53], v[238:241], v[198:201], v[50:53]
	v_mfma_f32_16x16x32_bf16 v[38:41], v[230:233], v[206:209], v[38:41]
	v_mfma_f32_16x16x32_bf16 v[34:37], v[238:241], v[206:209], v[34:37]
	v_mfma_f32_16x16x32_bf16 v[22:25], v[230:233], v[214:217], v[22:25]
	v_mfma_f32_16x16x32_bf16 v[18:21], v[238:241], v[214:217], v[18:21]
	v_mfma_f32_16x16x32_bf16 v[6:9], v[230:233], v[222:225], v[6:9]
	v_mfma_f32_16x16x32_bf16 v[2:5], v[238:241], v[222:225], v[2:5]
	v_mfma_f32_16x16x32_bf16 v[54:57], v[234:237], v[202:205], v[54:57]
	v_mfma_f32_16x16x32_bf16 v[50:53], v[242:245], v[202:205], v[50:53]
	v_mfma_f32_16x16x32_bf16 v[38:41], v[234:237], v[210:213], v[38:41]
	v_mfma_f32_16x16x32_bf16 v[34:37], v[242:245], v[210:213], v[34:37]
	v_mfma_f32_16x16x32_bf16 v[22:25], v[234:237], v[218:221], v[22:25]
	v_mfma_f32_16x16x32_bf16 v[18:21], v[242:245], v[218:221], v[18:21]
	v_mfma_f32_16x16x32_bf16 v[6:9], v[234:237], v[226:229], v[6:9]
	v_mfma_f32_16x16x32_bf16 v[2:5], v[242:245], v[226:229], v[2:5]
	s_add_i32 s73, 0, 0x18000
	v_add_u32_e32 v159, s73, v142
	s_barrier
	ds_read_b128 v[144:147], v159
	ds_read_b128 v[186:189], v159 offset:1024
	ds_read_b128 v[190:193], v159 offset:2048
	ds_read_b128 v[194:197], v159 offset:3072
	s_add_u32 s60, s60, 0x40000
	s_addc_u32 s61, s61, 0
	s_mov_b32 m0, s46
	v_lshl_add_u64 v[230:231], s[60:61], 0, v[150:151]
	ds_read_b128 v[198:201], v143 offset:32768
	ds_read_b128 v[202:205], v143 offset:33792
	ds_read_b128 v[206:209], v143 offset:34816
	ds_read_b128 v[210:213], v143 offset:35840
	ds_read_b128 v[214:217], v143 offset:36864
	ds_read_b128 v[218:221], v143 offset:37888
	ds_read_b128 v[222:225], v143 offset:38912
	ds_read_b128 v[226:229], v143 offset:39936
	global_load_lds_dwordx4 v[230:231], off
	v_lshl_add_u64 v[230:231], s[60:61], 0, v[154:155]
	s_mov_b32 m0, s47
	s_nop 0
	global_load_lds_dwordx4 v[230:231], off
	s_waitcnt lgkmcnt(8)
	s_barrier
	s_waitcnt lgkmcnt(0)
	s_waitcnt lgkmcnt(0)
	v_mfma_f32_16x16x32_bf16 v[126:129], v[144:147], v[198:201], v[126:129]
	v_mfma_f32_16x16x32_bf16 v[122:125], v[190:193], v[198:201], v[122:125]
	v_mfma_f32_16x16x32_bf16 v[110:113], v[144:147], v[206:209], v[110:113]
	v_mfma_f32_16x16x32_bf16 v[106:109], v[190:193], v[206:209], v[106:109]
	v_mfma_f32_16x16x32_bf16 v[94:97], v[144:147], v[214:217], v[94:97]
	v_mfma_f32_16x16x32_bf16 v[90:93], v[190:193], v[214:217], v[90:93]
	v_mfma_f32_16x16x32_bf16 v[78:81], v[144:147], v[222:225], v[78:81]
	v_mfma_f32_16x16x32_bf16 v[74:77], v[190:193], v[222:225], v[74:77]
	v_mfma_f32_16x16x32_bf16 v[126:129], v[186:189], v[202:205], v[126:129]
	v_mfma_f32_16x16x32_bf16 v[122:125], v[194:197], v[202:205], v[122:125]
	v_mfma_f32_16x16x32_bf16 v[110:113], v[186:189], v[210:213], v[110:113]
	v_mfma_f32_16x16x32_bf16 v[106:109], v[194:197], v[210:213], v[106:109]
	v_mfma_f32_16x16x32_bf16 v[94:97], v[186:189], v[218:221], v[94:97]
	v_mfma_f32_16x16x32_bf16 v[90:93], v[194:197], v[218:221], v[90:93]
	v_mfma_f32_16x16x32_bf16 v[78:81], v[186:189], v[226:229], v[78:81]
	v_mfma_f32_16x16x32_bf16 v[74:77], v[194:197], v[226:229], v[74:77]
	s_barrier
	s_add_i32 s60, 0, 0x1c000
	s_add_i32 s61, s73, s21
	v_add_u32_e32 v159, s60, v142
	v_lshl_add_u64 v[246:247], v[246:247], 0, s[38:39]
	s_mov_b32 m0, s61
	ds_read_b128 v[230:233], v159
	ds_read_b128 v[234:237], v159 offset:1024
	ds_read_b128 v[238:241], v159 offset:2048
	ds_read_b128 v[242:245], v159 offset:3072
	global_load_lds_dwordx4 v[246:247], off
	v_lshl_add_u64 v[246:247], v[248:249], 0, s[38:39]
	s_add_i32 m0, s61, 0x2000
	s_nop 0
	global_load_lds_dwordx4 v[246:247], off
	s_barrier
	s_waitcnt lgkmcnt(0)
	s_waitcnt lgkmcnt(0)
	v_mfma_f32_16x16x32_bf16 v[118:121], v[230:233], v[198:201], v[118:121]
	v_mfma_f32_16x16x32_bf16 v[114:117], v[238:241], v[198:201], v[114:117]
	v_mfma_f32_16x16x32_bf16 v[102:105], v[230:233], v[206:209], v[102:105]
	v_mfma_f32_16x16x32_bf16 v[98:101], v[238:241], v[206:209], v[98:101]
	v_mfma_f32_16x16x32_bf16 v[86:89], v[230:233], v[214:217], v[86:89]
	v_mfma_f32_16x16x32_bf16 v[82:85], v[238:241], v[214:217], v[82:85]
	v_mfma_f32_16x16x32_bf16 v[70:73], v[230:233], v[222:225], v[70:73]
	v_mfma_f32_16x16x32_bf16 v[66:69], v[238:241], v[222:225], v[66:69]
	v_mfma_f32_16x16x32_bf16 v[118:121], v[234:237], v[202:205], v[118:121]
	v_mfma_f32_16x16x32_bf16 v[114:117], v[242:245], v[202:205], v[114:117]
	v_mfma_f32_16x16x32_bf16 v[102:105], v[234:237], v[210:213], v[102:105]
	v_mfma_f32_16x16x32_bf16 v[98:101], v[242:245], v[210:213], v[98:101]
	v_mfma_f32_16x16x32_bf16 v[86:89], v[234:237], v[218:221], v[86:89]
	v_mfma_f32_16x16x32_bf16 v[82:85], v[242:245], v[218:221], v[82:85]
	v_mfma_f32_16x16x32_bf16 v[70:73], v[234:237], v[226:229], v[70:73]
	v_mfma_f32_16x16x32_bf16 v[66:69], v[242:245], v[226:229], v[66:69]
	s_mov_b32 m0, s64
	v_lshl_add_u64 v[246:247], v[250:251], 0, s[38:39]
	s_barrier
	ds_read_b128 v[198:201], v143 offset:49152
	ds_read_b128 v[202:205], v143 offset:50176
	ds_read_b128 v[206:209], v143 offset:51200
	ds_read_b128 v[210:213], v143 offset:52224
	ds_read_b128 v[214:217], v143 offset:53248
	ds_read_b128 v[218:221], v143 offset:54272
	ds_read_b128 v[222:225], v143 offset:55296
	ds_read_b128 v[226:229], v143 offset:56320
	global_load_lds_dwordx4 v[246:247], off
	v_lshl_add_u64 v[246:247], v[252:253], 0, s[38:39]
	s_mov_b32 m0, s65
	s_nop 0
	global_load_lds_dwordx4 v[246:247], off
	s_barrier
	s_waitcnt lgkmcnt(0)
	s_waitcnt lgkmcnt(0)
	v_mfma_f32_16x16x32_bf16 v[62:65], v[144:147], v[198:201], v[62:65]
	v_mfma_f32_16x16x32_bf16 v[58:61], v[190:193], v[198:201], v[58:61]
	v_mfma_f32_16x16x32_bf16 v[46:49], v[144:147], v[206:209], v[46:49]
	v_mfma_f32_16x16x32_bf16 v[42:45], v[190:193], v[206:209], v[42:45]
	v_mfma_f32_16x16x32_bf16 v[30:33], v[144:147], v[214:217], v[30:33]
	v_mfma_f32_16x16x32_bf16 v[26:29], v[190:193], v[214:217], v[26:29]
	v_mfma_f32_16x16x32_bf16 v[14:17], v[144:147], v[222:225], v[14:17]
	v_mfma_f32_16x16x32_bf16 v[10:13], v[190:193], v[222:225], v[10:13]
	v_mfma_f32_16x16x32_bf16 v[62:65], v[186:189], v[202:205], v[62:65]
	v_mfma_f32_16x16x32_bf16 v[58:61], v[194:197], v[202:205], v[58:61]
	v_mfma_f32_16x16x32_bf16 v[46:49], v[186:189], v[210:213], v[46:49]
	v_mfma_f32_16x16x32_bf16 v[42:45], v[194:197], v[210:213], v[42:45]
	v_mfma_f32_16x16x32_bf16 v[30:33], v[186:189], v[218:221], v[30:33]
	v_mfma_f32_16x16x32_bf16 v[26:29], v[194:197], v[218:221], v[26:29]
	v_mfma_f32_16x16x32_bf16 v[14:17], v[186:189], v[226:229], v[14:17]
	v_mfma_f32_16x16x32_bf16 v[10:13], v[194:197], v[226:229], v[10:13]
	s_barrier
	s_add_u32 s58, s58, 0x40080
	s_addc_u32 s59, s59, 0
	s_add_i32 s60, s60, s21
	v_lshl_add_u64 v[144:145], s[58:59], 0, v[152:153]
	s_mov_b32 m0, s60
	s_nop 0
	global_load_lds_dwordx4 v[144:145], off
	v_lshl_add_u64 v[144:145], s[58:59], 0, v[156:157]
	s_add_i32 m0, s60, 0x2000
	s_nop 0
	global_load_lds_dwordx4 v[144:145], off
	s_waitcnt vmcnt(6)
	s_barrier
	v_mfma_f32_16x16x32_bf16 v[54:57], v[230:233], v[198:201], v[54:57]
	v_mfma_f32_16x16x32_bf16 v[50:53], v[238:241], v[198:201], v[50:53]
	v_mfma_f32_16x16x32_bf16 v[38:41], v[230:233], v[206:209], v[38:41]
	v_mfma_f32_16x16x32_bf16 v[34:37], v[238:241], v[206:209], v[34:37]
	v_mfma_f32_16x16x32_bf16 v[22:25], v[230:233], v[214:217], v[22:25]
	v_mfma_f32_16x16x32_bf16 v[18:21], v[238:241], v[214:217], v[18:21]
	v_mfma_f32_16x16x32_bf16 v[6:9], v[230:233], v[222:225], v[6:9]
	v_mfma_f32_16x16x32_bf16 v[2:5], v[238:241], v[222:225], v[2:5]
	v_mfma_f32_16x16x32_bf16 v[54:57], v[234:237], v[202:205], v[54:57]
	v_mfma_f32_16x16x32_bf16 v[50:53], v[242:245], v[202:205], v[50:53]
	v_mfma_f32_16x16x32_bf16 v[38:41], v[234:237], v[210:213], v[38:41]
	v_mfma_f32_16x16x32_bf16 v[34:37], v[242:245], v[210:213], v[34:37]
	v_mfma_f32_16x16x32_bf16 v[22:25], v[234:237], v[218:221], v[22:25]
	v_mfma_f32_16x16x32_bf16 v[18:21], v[242:245], v[218:221], v[18:21]
	v_mfma_f32_16x16x32_bf16 v[6:9], v[234:237], v[226:229], v[6:9]
	v_mfma_f32_16x16x32_bf16 v[2:5], v[242:245], v[226:229], v[2:5]
	s_add_i32 s72, s72, 2
	s_add_u32 s56, s56, 0x100
	s_addc_u32 s57, s57, 0
	s_cmp_gt_u32 s72, 13
	s_barrier
	s_cbranch_scc0 .LBB0_862
	s_add_u32 s56, s49, 0xffffff00
	s_addc_u32 s57, s69, -1
	s_andn2_b64 vcc, exec, s[4:5]
	s_cbranch_vccnz .LBB0_865
	v_mov_b32_e32 v2, 0
	s_mov_b32 s36, s40
	s_mov_b32 s34, s42
	s_mov_b64 s[0:1], s[50:51]
	s_mov_b32 s66, s48
	v_mov_b32_e32 v3, v2
	v_mov_b32_e32 v4, v2
	v_mov_b32_e32 v5, v2
	v_mov_b32_e32 v6, v2
	v_mov_b32_e32 v7, v2
	v_mov_b32_e32 v8, v2
	v_mov_b32_e32 v9, v2
	v_mov_b32_e32 v18, v2
	v_mov_b32_e32 v19, v2
	v_mov_b32_e32 v20, v2
	v_mov_b32_e32 v21, v2
	v_mov_b32_e32 v22, v2
	v_mov_b32_e32 v23, v2
	v_mov_b32_e32 v24, v2
	v_mov_b32_e32 v25, v2
	v_mov_b32_e32 v34, v2
	v_mov_b32_e32 v35, v2
	v_mov_b32_e32 v36, v2
	v_mov_b32_e32 v37, v2
	v_mov_b32_e32 v38, v2
	v_mov_b32_e32 v39, v2
	v_mov_b32_e32 v40, v2
	v_mov_b32_e32 v41, v2
	v_mov_b32_e32 v50, v2
	v_mov_b32_e32 v51, v2
	v_mov_b32_e32 v52, v2
	v_mov_b32_e32 v53, v2
	v_mov_b32_e32 v54, v2
	v_mov_b32_e32 v55, v2
	v_mov_b32_e32 v56, v2
	v_mov_b32_e32 v57, v2
	v_mov_b32_e32 v10, v2
	v_mov_b32_e32 v11, v2
	v_mov_b32_e32 v12, v2
	v_mov_b32_e32 v13, v2
	v_mov_b32_e32 v14, v2
	v_mov_b32_e32 v15, v2
	v_mov_b32_e32 v16, v2
	v_mov_b32_e32 v17, v2
	v_mov_b32_e32 v26, v2
	v_mov_b32_e32 v27, v2
	v_mov_b32_e32 v28, v2
	v_mov_b32_e32 v29, v2
	v_mov_b32_e32 v30, v2
	v_mov_b32_e32 v31, v2
	v_mov_b32_e32 v32, v2
	v_mov_b32_e32 v33, v2
	v_mov_b32_e32 v42, v2
	v_mov_b32_e32 v43, v2
	v_mov_b32_e32 v44, v2
	v_mov_b32_e32 v45, v2
	v_mov_b32_e32 v46, v2
	v_mov_b32_e32 v47, v2
	v_mov_b32_e32 v48, v2
	v_mov_b32_e32 v49, v2
	v_mov_b32_e32 v58, v2
	v_mov_b32_e32 v59, v2
	v_mov_b32_e32 v60, v2
	v_mov_b32_e32 v61, v2
	v_mov_b32_e32 v62, v2
	v_mov_b32_e32 v63, v2
	v_mov_b32_e32 v64, v2
	v_mov_b32_e32 v65, v2
	v_mov_b32_e32 v66, v2
	v_mov_b32_e32 v67, v2
	v_mov_b32_e32 v68, v2
	v_mov_b32_e32 v69, v2
	v_mov_b32_e32 v70, v2
	v_mov_b32_e32 v71, v2
	v_mov_b32_e32 v72, v2
	v_mov_b32_e32 v73, v2
	v_mov_b32_e32 v82, v2
	v_mov_b32_e32 v83, v2
	v_mov_b32_e32 v84, v2
	v_mov_b32_e32 v85, v2
	v_mov_b32_e32 v86, v2
	v_mov_b32_e32 v87, v2
	v_mov_b32_e32 v88, v2
	v_mov_b32_e32 v89, v2
	v_mov_b32_e32 v98, v2
	v_mov_b32_e32 v99, v2
	v_mov_b32_e32 v100, v2
	v_mov_b32_e32 v101, v2
	v_mov_b32_e32 v102, v2
	v_mov_b32_e32 v103, v2
	v_mov_b32_e32 v104, v2
	v_mov_b32_e32 v105, v2
	v_mov_b32_e32 v114, v2
	v_mov_b32_e32 v115, v2
	v_mov_b32_e32 v116, v2
	v_mov_b32_e32 v117, v2
	v_mov_b32_e32 v118, v2
	v_mov_b32_e32 v119, v2
	v_mov_b32_e32 v120, v2
	v_mov_b32_e32 v121, v2
	v_mov_b32_e32 v74, v2
	v_mov_b32_e32 v75, v2
	v_mov_b32_e32 v76, v2
	v_mov_b32_e32 v77, v2
	v_mov_b32_e32 v78, v2
	v_mov_b32_e32 v79, v2
	v_mov_b32_e32 v80, v2
	v_mov_b32_e32 v81, v2
	v_mov_b32_e32 v90, v2
	v_mov_b32_e32 v91, v2
	v_mov_b32_e32 v92, v2
	v_mov_b32_e32 v93, v2
	v_mov_b32_e32 v94, v2
	v_mov_b32_e32 v95, v2
	v_mov_b32_e32 v96, v2
	v_mov_b32_e32 v97, v2
	v_mov_b32_e32 v106, v2
	v_mov_b32_e32 v107, v2
	v_mov_b32_e32 v108, v2
	v_mov_b32_e32 v109, v2
	v_mov_b32_e32 v110, v2
	v_mov_b32_e32 v111, v2
	v_mov_b32_e32 v112, v2
	v_mov_b32_e32 v113, v2
	v_mov_b32_e32 v122, v2
	v_mov_b32_e32 v123, v2
	v_mov_b32_e32 v124, v2
	v_mov_b32_e32 v125, v2
	v_mov_b32_e32 v126, v2
	v_mov_b32_e32 v127, v2
	v_mov_b32_e32 v128, v2
	v_mov_b32_e32 v129, v2
	s_branch .LBB0_866

.LBB0_1038:
	ds_read_b128 v[184:187], v143
	ds_read_b128 v[188:191], v143 offset:1024
	ds_read_b128 v[192:195], v143 offset:2048
	ds_read_b128 v[196:199], v143 offset:3072
	s_add_u32 s40, s38, 0xfffc0080
	s_addc_u32 s41, s39, -1
	s_cmp_eq_u32 s60, 12
	s_cselect_b32 s43, s13, s41
	s_cselect_b32 s42, s21, s40
	s_cselect_b32 s41, s5, s59
	s_cselect_b32 s40, s22, s23
	v_lshl_add_u64 v[138:139], s[38:39], 0, v[130:131]
	s_add_i32 m0, s37, 0xc000
	ds_read_b128 v[200:203], v144
	ds_read_b128 v[204:207], v144 offset:1024
	ds_read_b128 v[208:211], v144 offset:2048
	ds_read_b128 v[212:215], v144 offset:3072
	ds_read_b128 v[216:219], v144 offset:4096
	ds_read_b128 v[220:223], v144 offset:5120
	ds_read_b128 v[224:227], v144 offset:6144
	ds_read_b128 v[228:231], v144 offset:7168
	global_load_lds_dwordx4 v[138:139], off
	v_lshl_add_u64 v[138:139], s[38:39], 0, v[132:133]
	s_add_i32 m0, s37, 0xe000
	s_nop 0
	global_load_lds_dwordx4 v[138:139], off
	s_waitcnt lgkmcnt(8)
	s_barrier
	s_waitcnt lgkmcnt(0)
	s_waitcnt lgkmcnt(0)
	v_mfma_f32_16x16x32_bf16 v[126:129], v[184:187], v[200:203], v[126:129]
	v_mfma_f32_16x16x32_bf16 v[122:125], v[192:195], v[200:203], v[122:125]
	v_mfma_f32_16x16x32_bf16 v[110:113], v[184:187], v[208:211], v[110:113]
	v_mfma_f32_16x16x32_bf16 v[106:109], v[192:195], v[208:211], v[106:109]
	v_mfma_f32_16x16x32_bf16 v[94:97], v[184:187], v[216:219], v[94:97]
	v_mfma_f32_16x16x32_bf16 v[90:93], v[192:195], v[216:219], v[90:93]
	v_mfma_f32_16x16x32_bf16 v[78:81], v[184:187], v[224:227], v[78:81]
	v_mfma_f32_16x16x32_bf16 v[74:77], v[192:195], v[224:227], v[74:77]
	v_mfma_f32_16x16x32_bf16 v[126:129], v[188:191], v[204:207], v[126:129]
	v_mfma_f32_16x16x32_bf16 v[122:125], v[196:199], v[204:207], v[122:125]
	v_mfma_f32_16x16x32_bf16 v[110:113], v[188:191], v[212:215], v[110:113]
	v_mfma_f32_16x16x32_bf16 v[106:109], v[196:199], v[212:215], v[106:109]
	v_mfma_f32_16x16x32_bf16 v[94:97], v[188:191], v[220:223], v[94:97]
	v_mfma_f32_16x16x32_bf16 v[90:93], v[196:199], v[220:223], v[90:93]
	v_mfma_f32_16x16x32_bf16 v[78:81], v[188:191], v[228:231], v[78:81]
	v_mfma_f32_16x16x32_bf16 v[74:77], v[196:199], v[228:231], v[74:77]
	s_barrier
	s_add_i32 s61, s56, s46
	v_lshl_add_u64 v[138:139], s[40:41], 0, v[152:153]
	s_mov_b32 m0, s61
	ds_read_b128 v[232:235], v145
	ds_read_b128 v[236:239], v145 offset:1024
	ds_read_b128 v[240:243], v145 offset:2048
	ds_read_b128 v[244:247], v145 offset:3072
	global_load_lds_dwordx4 v[138:139], off
	v_lshl_add_u64 v[146:147], s[40:41], 0, v[156:157]
	s_add_i32 m0, s61, 0x2000
	s_nop 0
	global_load_lds_dwordx4 v[146:147], off
	s_barrier
	s_waitcnt lgkmcnt(0)
	s_waitcnt lgkmcnt(0)
	v_mfma_f32_16x16x32_bf16 v[118:121], v[232:235], v[200:203], v[118:121]
	v_mfma_f32_16x16x32_bf16 v[114:117], v[240:243], v[200:203], v[114:117]
	v_mfma_f32_16x16x32_bf16 v[102:105], v[232:235], v[208:211], v[102:105]
	v_mfma_f32_16x16x32_bf16 v[98:101], v[240:243], v[208:211], v[98:101]
	v_mfma_f32_16x16x32_bf16 v[86:89], v[232:235], v[216:219], v[86:89]
	v_mfma_f32_16x16x32_bf16 v[82:85], v[240:243], v[216:219], v[82:85]
	v_mfma_f32_16x16x32_bf16 v[70:73], v[232:235], v[224:227], v[70:73]
	v_mfma_f32_16x16x32_bf16 v[66:69], v[240:243], v[224:227], v[66:69]
	v_mfma_f32_16x16x32_bf16 v[118:121], v[236:239], v[204:207], v[118:121]
	v_mfma_f32_16x16x32_bf16 v[114:117], v[244:247], v[204:207], v[114:117]
	v_mfma_f32_16x16x32_bf16 v[102:105], v[236:239], v[212:215], v[102:105]
	v_mfma_f32_16x16x32_bf16 v[98:101], v[244:247], v[212:215], v[98:101]
	v_mfma_f32_16x16x32_bf16 v[86:89], v[236:239], v[220:223], v[86:89]
	v_mfma_f32_16x16x32_bf16 v[82:85], v[244:247], v[220:223], v[82:85]
	v_mfma_f32_16x16x32_bf16 v[70:73], v[236:239], v[228:231], v[70:73]
	v_mfma_f32_16x16x32_bf16 v[66:69], v[244:247], v[228:231], v[66:69]
	s_mov_b32 m0, s37
	v_lshl_add_u64 v[158:159], s[42:43], 0, v[150:151]
	s_barrier
	ds_read_b128 v[200:203], v144 offset:16384
	ds_read_b128 v[204:207], v144 offset:17408
	ds_read_b128 v[208:211], v144 offset:18432
	ds_read_b128 v[212:215], v144 offset:19456
	ds_read_b128 v[216:219], v144 offset:20480
	ds_read_b128 v[220:223], v144 offset:21504
	ds_read_b128 v[224:227], v144 offset:22528
	ds_read_b128 v[228:231], v144 offset:23552
	global_load_lds_dwordx4 v[158:159], off
	v_lshl_add_u64 v[248:249], s[42:43], 0, v[154:155]
	s_mov_b32 m0, s47
	s_nop 0
	global_load_lds_dwordx4 v[248:249], off
	s_barrier
	s_waitcnt lgkmcnt(0)
	s_waitcnt lgkmcnt(0)
	v_mfma_f32_16x16x32_bf16 v[62:65], v[184:187], v[200:203], v[62:65]
	v_mfma_f32_16x16x32_bf16 v[58:61], v[192:195], v[200:203], v[58:61]
	v_mfma_f32_16x16x32_bf16 v[46:49], v[184:187], v[208:211], v[46:49]
	v_mfma_f32_16x16x32_bf16 v[42:45], v[192:195], v[208:211], v[42:45]
	v_mfma_f32_16x16x32_bf16 v[30:33], v[184:187], v[216:219], v[30:33]
	v_mfma_f32_16x16x32_bf16 v[26:29], v[192:195], v[216:219], v[26:29]
	v_mfma_f32_16x16x32_bf16 v[14:17], v[184:187], v[224:227], v[14:17]
	v_mfma_f32_16x16x32_bf16 v[10:13], v[192:195], v[224:227], v[10:13]
	v_mfma_f32_16x16x32_bf16 v[62:65], v[188:191], v[204:207], v[62:65]
	v_mfma_f32_16x16x32_bf16 v[58:61], v[196:199], v[204:207], v[58:61]
	v_mfma_f32_16x16x32_bf16 v[46:49], v[188:191], v[212:215], v[46:49]
	v_mfma_f32_16x16x32_bf16 v[42:45], v[196:199], v[212:215], v[42:45]
	v_mfma_f32_16x16x32_bf16 v[30:33], v[188:191], v[220:223], v[30:33]
	v_mfma_f32_16x16x32_bf16 v[26:29], v[196:199], v[220:223], v[26:29]
	v_mfma_f32_16x16x32_bf16 v[14:17], v[188:191], v[228:231], v[14:17]
	v_mfma_f32_16x16x32_bf16 v[10:13], v[196:199], v[228:231], v[10:13]
	s_barrier
	s_add_u32 s62, s40, 0x40000
	s_addc_u32 s63, s41, 0
	s_add_i32 s61, s57, s46
	v_lshl_add_u64 v[184:185], s[62:63], 0, v[152:153]
	s_mov_b32 m0, s61
	s_nop 0
	global_load_lds_dwordx4 v[184:185], off
	v_lshl_add_u64 v[184:185], s[62:63], 0, v[156:157]
	s_add_i32 m0, s61, 0x2000
	s_nop 0
	global_load_lds_dwordx4 v[184:185], off
	s_waitcnt vmcnt(6)
	s_barrier
	v_mfma_f32_16x16x32_bf16 v[54:57], v[232:235], v[200:203], v[54:57]
	v_mfma_f32_16x16x32_bf16 v[50:53], v[240:243], v[200:203], v[50:53]
	v_mfma_f32_16x16x32_bf16 v[38:41], v[232:235], v[208:211], v[38:41]
	v_mfma_f32_16x16x32_bf16 v[34:37], v[240:243], v[208:211], v[34:37]
	v_mfma_f32_16x16x32_bf16 v[22:25], v[232:235], v[216:219], v[22:25]
	v_mfma_f32_16x16x32_bf16 v[18:21], v[240:243], v[216:219], v[18:21]
	v_mfma_f32_16x16x32_bf16 v[6:9], v[232:235], v[224:227], v[6:9]
	v_mfma_f32_16x16x32_bf16 v[2:5], v[240:243], v[224:227], v[2:5]
	v_mfma_f32_16x16x32_bf16 v[54:57], v[236:239], v[204:207], v[54:57]
	v_mfma_f32_16x16x32_bf16 v[50:53], v[244:247], v[204:207], v[50:53]
	v_mfma_f32_16x16x32_bf16 v[38:41], v[236:239], v[212:215], v[38:41]
	v_mfma_f32_16x16x32_bf16 v[34:37], v[244:247], v[212:215], v[34:37]
	v_mfma_f32_16x16x32_bf16 v[22:25], v[236:239], v[220:223], v[22:25]
	v_mfma_f32_16x16x32_bf16 v[18:21], v[244:247], v[220:223], v[18:21]
	v_mfma_f32_16x16x32_bf16 v[6:9], v[236:239], v[228:231], v[6:9]
	v_mfma_f32_16x16x32_bf16 v[2:5], v[244:247], v[228:231], v[2:5]
	s_add_i32 s61, 0, 0x18000
	v_add_u32_e32 v169, s61, v141
	s_barrier
	ds_read_b128 v[184:187], v169
	ds_read_b128 v[188:191], v169 offset:1024
	ds_read_b128 v[192:195], v169 offset:2048
	ds_read_b128 v[196:199], v169 offset:3072
	s_add_u32 s42, s42, 0x40000
	s_addc_u32 s43, s43, 0
	s_mov_b32 m0, s50
	v_lshl_add_u64 v[232:233], s[42:43], 0, v[150:151]
	ds_read_b128 v[200:203], v144 offset:32768
	ds_read_b128 v[204:207], v144 offset:33792
	ds_read_b128 v[208:211], v144 offset:34816
	ds_read_b128 v[212:215], v144 offset:35840
	ds_read_b128 v[216:219], v144 offset:36864
	ds_read_b128 v[220:223], v144 offset:37888
	ds_read_b128 v[224:227], v144 offset:38912
	ds_read_b128 v[228:231], v144 offset:39936
	global_load_lds_dwordx4 v[232:233], off
	v_lshl_add_u64 v[232:233], s[42:43], 0, v[154:155]
	s_mov_b32 m0, s51
	s_nop 0
	global_load_lds_dwordx4 v[232:233], off
	s_waitcnt lgkmcnt(8)
	s_barrier
	s_waitcnt lgkmcnt(0)
	s_waitcnt lgkmcnt(0)
	v_mfma_f32_16x16x32_bf16 v[126:129], v[184:187], v[200:203], v[126:129]
	v_mfma_f32_16x16x32_bf16 v[122:125], v[192:195], v[200:203], v[122:125]
	v_mfma_f32_16x16x32_bf16 v[110:113], v[184:187], v[208:211], v[110:113]
	v_mfma_f32_16x16x32_bf16 v[106:109], v[192:195], v[208:211], v[106:109]
	v_mfma_f32_16x16x32_bf16 v[94:97], v[184:187], v[216:219], v[94:97]
	v_mfma_f32_16x16x32_bf16 v[90:93], v[192:195], v[216:219], v[90:93]
	v_mfma_f32_16x16x32_bf16 v[78:81], v[184:187], v[224:227], v[78:81]
	v_mfma_f32_16x16x32_bf16 v[74:77], v[192:195], v[224:227], v[74:77]
	v_mfma_f32_16x16x32_bf16 v[126:129], v[188:191], v[204:207], v[126:129]
	v_mfma_f32_16x16x32_bf16 v[122:125], v[196:199], v[204:207], v[122:125]
	v_mfma_f32_16x16x32_bf16 v[110:113], v[188:191], v[212:215], v[110:113]
	v_mfma_f32_16x16x32_bf16 v[106:109], v[196:199], v[212:215], v[106:109]
	v_mfma_f32_16x16x32_bf16 v[94:97], v[188:191], v[220:223], v[94:97]
	v_mfma_f32_16x16x32_bf16 v[90:93], v[196:199], v[220:223], v[90:93]
	v_mfma_f32_16x16x32_bf16 v[78:81], v[188:191], v[228:231], v[78:81]
	v_mfma_f32_16x16x32_bf16 v[74:77], v[196:199], v[228:231], v[74:77]
	s_barrier
	s_add_i32 s42, 0, 0x1c000
	s_add_i32 s43, s61, s46
	v_add_u32_e32 v169, s42, v141
	v_lshl_add_u64 v[138:139], v[138:139], 0, s[0:1]
	s_mov_b32 m0, s43
	ds_read_b128 v[232:235], v169
	ds_read_b128 v[236:239], v169 offset:1024
	ds_read_b128 v[240:243], v169 offset:2048
	ds_read_b128 v[244:247], v169 offset:3072
	global_load_lds_dwordx4 v[138:139], off
	v_lshl_add_u64 v[138:139], v[146:147], 0, s[0:1]
	s_add_i32 m0, s43, 0x2000
	s_nop 0
	global_load_lds_dwordx4 v[138:139], off
	s_barrier
	s_waitcnt lgkmcnt(0)
	s_waitcnt lgkmcnt(0)
	v_mfma_f32_16x16x32_bf16 v[118:121], v[232:235], v[200:203], v[118:121]
	v_mfma_f32_16x16x32_bf16 v[114:117], v[240:243], v[200:203], v[114:117]
	v_mfma_f32_16x16x32_bf16 v[102:105], v[232:235], v[208:211], v[102:105]
	v_mfma_f32_16x16x32_bf16 v[98:101], v[240:243], v[208:211], v[98:101]
	v_mfma_f32_16x16x32_bf16 v[86:89], v[232:235], v[216:219], v[86:89]
	v_mfma_f32_16x16x32_bf16 v[82:85], v[240:243], v[216:219], v[82:85]
	v_mfma_f32_16x16x32_bf16 v[70:73], v[232:235], v[224:227], v[70:73]
	v_mfma_f32_16x16x32_bf16 v[66:69], v[240:243], v[224:227], v[66:69]
	v_mfma_f32_16x16x32_bf16 v[118:121], v[236:239], v[204:207], v[118:121]
	v_mfma_f32_16x16x32_bf16 v[114:117], v[244:247], v[204:207], v[114:117]
	v_mfma_f32_16x16x32_bf16 v[102:105], v[236:239], v[212:215], v[102:105]
	v_mfma_f32_16x16x32_bf16 v[98:101], v[244:247], v[212:215], v[98:101]
	v_mfma_f32_16x16x32_bf16 v[86:89], v[236:239], v[220:223], v[86:89]
	v_mfma_f32_16x16x32_bf16 v[82:85], v[244:247], v[220:223], v[82:85]
	v_mfma_f32_16x16x32_bf16 v[70:73], v[236:239], v[228:231], v[70:73]
	v_mfma_f32_16x16x32_bf16 v[66:69], v[244:247], v[228:231], v[66:69]
	s_mov_b32 m0, s53
	v_lshl_add_u64 v[138:139], v[158:159], 0, s[0:1]
	s_barrier
	ds_read_b128 v[200:203], v144 offset:49152
	ds_read_b128 v[204:207], v144 offset:50176
	ds_read_b128 v[208:211], v144 offset:51200
	ds_read_b128 v[212:215], v144 offset:52224
	ds_read_b128 v[216:219], v144 offset:53248
	ds_read_b128 v[220:223], v144 offset:54272
	ds_read_b128 v[224:227], v144 offset:55296
	ds_read_b128 v[228:231], v144 offset:56320
	global_load_lds_dwordx4 v[138:139], off
	v_lshl_add_u64 v[138:139], v[248:249], 0, s[0:1]
	s_mov_b32 m0, s54
	s_nop 0
	global_load_lds_dwordx4 v[138:139], off
	s_barrier
	s_waitcnt lgkmcnt(0)
	s_waitcnt lgkmcnt(0)
	v_mfma_f32_16x16x32_bf16 v[62:65], v[184:187], v[200:203], v[62:65]
	v_mfma_f32_16x16x32_bf16 v[58:61], v[192:195], v[200:203], v[58:61]
	v_mfma_f32_16x16x32_bf16 v[46:49], v[184:187], v[208:211], v[46:49]
	v_mfma_f32_16x16x32_bf16 v[42:45], v[192:195], v[208:211], v[42:45]
	v_mfma_f32_16x16x32_bf16 v[30:33], v[184:187], v[216:219], v[30:33]
	v_mfma_f32_16x16x32_bf16 v[26:29], v[192:195], v[216:219], v[26:29]
	v_mfma_f32_16x16x32_bf16 v[14:17], v[184:187], v[224:227], v[14:17]
	v_mfma_f32_16x16x32_bf16 v[10:13], v[192:195], v[224:227], v[10:13]
	v_mfma_f32_16x16x32_bf16 v[62:65], v[188:191], v[204:207], v[62:65]
	v_mfma_f32_16x16x32_bf16 v[58:61], v[196:199], v[204:207], v[58:61]
	v_mfma_f32_16x16x32_bf16 v[46:49], v[188:191], v[212:215], v[46:49]
	v_mfma_f32_16x16x32_bf16 v[42:45], v[196:199], v[212:215], v[42:45]
	v_mfma_f32_16x16x32_bf16 v[30:33], v[188:191], v[220:223], v[30:33]
	v_mfma_f32_16x16x32_bf16 v[26:29], v[196:199], v[220:223], v[26:29]
	v_mfma_f32_16x16x32_bf16 v[14:17], v[188:191], v[228:231], v[14:17]
	v_mfma_f32_16x16x32_bf16 v[10:13], v[196:199], v[228:231], v[10:13]
	s_barrier
	s_add_u32 s40, s40, 0x40080
	s_addc_u32 s41, s41, 0
	s_add_i32 s42, s42, s46
	v_lshl_add_u64 v[138:139], s[40:41], 0, v[152:153]
	s_mov_b32 m0, s42
	s_nop 0
	global_load_lds_dwordx4 v[138:139], off
	v_lshl_add_u64 v[138:139], s[40:41], 0, v[156:157]
	s_add_i32 m0, s42, 0x2000
	s_nop 0
	global_load_lds_dwordx4 v[138:139], off
	s_waitcnt vmcnt(6)
	s_barrier
	v_mfma_f32_16x16x32_bf16 v[54:57], v[232:235], v[200:203], v[54:57]
	v_mfma_f32_16x16x32_bf16 v[50:53], v[240:243], v[200:203], v[50:53]
	v_mfma_f32_16x16x32_bf16 v[38:41], v[232:235], v[208:211], v[38:41]
	v_mfma_f32_16x16x32_bf16 v[34:37], v[240:243], v[208:211], v[34:37]
	v_mfma_f32_16x16x32_bf16 v[22:25], v[232:235], v[216:219], v[22:25]
	v_mfma_f32_16x16x32_bf16 v[18:21], v[240:243], v[216:219], v[18:21]
	v_mfma_f32_16x16x32_bf16 v[6:9], v[232:235], v[224:227], v[6:9]
	v_mfma_f32_16x16x32_bf16 v[2:5], v[240:243], v[224:227], v[2:5]
	v_mfma_f32_16x16x32_bf16 v[54:57], v[236:239], v[204:207], v[54:57]
	v_mfma_f32_16x16x32_bf16 v[50:53], v[244:247], v[204:207], v[50:53]
	v_mfma_f32_16x16x32_bf16 v[38:41], v[236:239], v[212:215], v[38:41]
	v_mfma_f32_16x16x32_bf16 v[34:37], v[244:247], v[212:215], v[34:37]
	v_mfma_f32_16x16x32_bf16 v[22:25], v[236:239], v[220:223], v[22:25]
	v_mfma_f32_16x16x32_bf16 v[18:21], v[244:247], v[220:223], v[18:21]
	v_mfma_f32_16x16x32_bf16 v[6:9], v[236:239], v[228:231], v[6:9]
	v_mfma_f32_16x16x32_bf16 v[2:5], v[244:247], v[228:231], v[2:5]
	s_add_i32 s60, s60, 2
	s_add_u32 s38, s38, 0x100
	s_addc_u32 s39, s39, 0
	s_add_u32 s23, s23, 0x100
	s_addc_u32 s59, s59, 0
	s_cmp_gt_u32 s60, 13
	s_barrier
	s_cbranch_scc0 .LBB0_1038
	v_mul_f32_e32 v138, 0xbfb8aa3b, v126
	v_exp_f32_e32 v147, v138
	v_mul_f32_e32 v138, 0xbfb8aa3b, v122
	v_exp_f32_e32 v169, v138
	v_lshl_or_b32 v158, s20, 7, v142
	v_add_f32_e32 v147, 1.0, v147
	v_rcp_f32_e32 v147, v147
	v_add_f32_e32 v169, 1.0, v169
	v_rcp_f32_e32 v169, v169
	v_lshl_add_u32 v146, s36, 8, v140
	v_mul_f32_e32 v126, v126, v147
	v_mul_f32_e32 v118, v126, v118
	v_mul_f32_e32 v126, 0xbfb8aa3b, v127
	v_exp_f32_e32 v126, v126
	v_mul_f32_e32 v147, 0xbfb8aa3b, v123
	v_exp_f32_e32 v147, v147
	v_mul_f32_e32 v122, v122, v169
	v_mul_f32_e32 v122, v122, v114
	v_add_f32_e32 v114, 1.0, v126
	v_rcp_f32_e32 v114, v114
	v_add_f32_e32 v126, 1.0, v147
	v_mul_f32_e32 v147, 0xbfb8aa3b, v128
	v_rcp_f32_e32 v126, v126
	v_exp_f32_e32 v147, v147
	v_mul_f32_e32 v114, v127, v114
	v_mul_f32_e32 v119, v114, v119
	v_mul_f32_e32 v114, v123, v126
	v_add_f32_e32 v123, 1.0, v147
	v_rcp_f32_e32 v123, v123
	v_mul_f32_e32 v126, 0xbfb8aa3b, v124
	v_exp_f32_e32 v126, v126
	v_mul_f32_e32 v127, v114, v115
	v_mul_f32_e32 v114, v128, v123
	v_mul_f32_e32 v115, 0xbfb8aa3b, v129
	v_mul_f32_e32 v123, v114, v120
	v_exp_f32_e32 v115, v115
	v_mul_f32_e32 v120, 0xbfb8aa3b, v125
	v_exp_f32_e32 v120, v120
	v_add_f32_e32 v114, 1.0, v126
	v_rcp_f32_e32 v114, v114
	v_add_f32_e32 v115, 1.0, v115
	v_rcp_f32_e32 v115, v115
	v_add_f32_e32 v120, 1.0, v120
	v_rcp_f32_e32 v120, v120
	v_mul_f32_e32 v114, v124, v114
	v_mul_f32_e32 v124, v114, v116
	v_mul_f32_e32 v114, v129, v115
	v_ashrrev_i32_e32 v159, 31, v158
	v_mov_b64_e32 v[138:139], s[18:19]
	v_mul_f32_e32 v126, v114, v121
	v_mul_f32_e32 v114, v125, v120
	v_mad_i64_i32 v[184:185], s[20:21], v146, s58, v[138:139]
	v_mul_f32_e32 v125, v114, v117
	v_lshlrev_b64 v[114:115], 1, v[158:159]
	v_lshl_add_u64 v[120:121], v[184:185], 0, v[114:115]
	v_cvt_pk_bf16_f32 v116, v118, v119
	v_cvt_pk_bf16_f32 v117, v123, v126
	v_cvt_pk_bf16_f32 v118, v122, v127
	v_cvt_pk_bf16_f32 v119, v124, v125
	global_store_dwordx4 v[120:121], v[116:119], off
	s_and_b64 vcc, exec, s[2:3]
	s_mov_b32 s36, s12
	v_mul_f32_e32 v116, 0xbfb8aa3b, v110
	v_exp_f32_e32 v116, v116
	v_mul_f32_e32 v117, 0xbfb8aa3b, v106
	v_exp_f32_e32 v117, v117
	v_or_b32_e32 v118, 16, v146
	v_add_f32_e32 v116, 1.0, v116
	v_rcp_f32_e32 v119, v116
	v_add_f32_e32 v116, 1.0, v117
	v_rcp_f32_e32 v120, v116
	v_mad_i64_i32 v[116:117], s[20:21], v118, s58, v[138:139]
	v_mul_f32_e32 v110, v110, v119
	v_mul_f32_e32 v110, v110, v102
	v_mul_f32_e32 v102, v106, v120
	v_mul_f32_e32 v106, 0xbfb8aa3b, v111
	v_exp_f32_e32 v106, v106
	v_mul_f32_e32 v118, 0xbfb8aa3b, v107
	v_mul_f32_e32 v119, v102, v98
	v_exp_f32_e32 v118, v118
	v_add_f32_e32 v98, 1.0, v106
	v_rcp_f32_e32 v98, v98
	v_mul_f32_e32 v106, 0xbfb8aa3b, v112
	v_exp_f32_e32 v106, v106
	v_add_f32_e32 v102, 1.0, v118
	v_mul_f32_e32 v98, v111, v98
	v_rcp_f32_e32 v102, v102
	v_mul_f32_e32 v98, v98, v103
	v_add_f32_e32 v103, 1.0, v106
	v_rcp_f32_e32 v103, v103
	v_mul_f32_e32 v102, v107, v102
	v_mul_f32_e32 v106, 0xbfb8aa3b, v108
	v_mul_f32_e32 v107, v102, v99
	v_mul_f32_e32 v99, v112, v103
	v_exp_f32_e32 v106, v106
	v_mul_f32_e32 v99, v99, v104
	v_mul_f32_e32 v103, 0xbfb8aa3b, v113
	v_mul_f32_e32 v104, 0xbfb8aa3b, v109
	v_exp_f32_e32 v103, v103
	v_exp_f32_e32 v104, v104
	v_add_f32_e32 v102, 1.0, v106
	v_rcp_f32_e32 v102, v102
	v_add_f32_e32 v103, 1.0, v103
	v_add_f32_e32 v104, 1.0, v104
	v_rcp_f32_e32 v103, v103
	v_rcp_f32_e32 v104, v104
	v_mul_f32_e32 v102, v108, v102
	v_mul_f32_e32 v106, v102, v100
	v_mul_f32_e32 v100, v113, v103
	v_mul_f32_e32 v102, v109, v104
	v_mul_f32_e32 v100, v100, v105
	v_mul_f32_e32 v101, v102, v101
	v_lshl_add_u64 v[102:103], v[116:117], 0, v[114:115]
	v_cvt_pk_bf16_f32 v98, v110, v98
	v_cvt_pk_bf16_f32 v99, v99, v100
	v_cvt_pk_bf16_f32 v100, v119, v107
	v_cvt_pk_bf16_f32 v101, v106, v101
	global_store_dwordx4 v[102:103], v[98:101], off
	s_mov_b64 s[40:41], s[34:35]
	s_mov_b64 s[38:39], s[28:29]
	v_mul_f32_e32 v98, 0xbfb8aa3b, v94
	v_exp_f32_e32 v98, v98
	v_mul_f32_e32 v99, 0xbfb8aa3b, v90
	v_exp_f32_e32 v99, v99
	v_or_b32_e32 v100, 32, v146
	v_add_f32_e32 v98, 1.0, v98
	v_rcp_f32_e32 v101, v98
	v_add_f32_e32 v98, 1.0, v99
	v_rcp_f32_e32 v102, v98
	v_mad_i64_i32 v[98:99], s[20:21], v100, s58, v[138:139]
	v_mul_f32_e32 v94, v94, v101
	v_mul_f32_e32 v94, v94, v86
	v_mul_f32_e32 v86, v90, v102
	v_mul_f32_e32 v90, 0xbfb8aa3b, v95
	v_exp_f32_e32 v90, v90
	v_mul_f32_e32 v100, 0xbfb8aa3b, v91
	v_mul_f32_e32 v101, v86, v82
	v_exp_f32_e32 v100, v100
	v_add_f32_e32 v82, 1.0, v90
	v_rcp_f32_e32 v82, v82
	v_mul_f32_e32 v90, 0xbfb8aa3b, v96
	v_exp_f32_e32 v90, v90
	v_add_f32_e32 v86, 1.0, v100
	v_mul_f32_e32 v82, v95, v82
	v_rcp_f32_e32 v86, v86
	v_mul_f32_e32 v82, v82, v87
	v_add_f32_e32 v87, 1.0, v90
	v_rcp_f32_e32 v87, v87
	v_mul_f32_e32 v86, v91, v86
	v_mul_f32_e32 v90, 0xbfb8aa3b, v92
	v_mul_f32_e32 v91, v86, v83
	v_mul_f32_e32 v83, v96, v87
	v_exp_f32_e32 v90, v90
	v_mul_f32_e32 v83, v83, v88
	v_mul_f32_e32 v87, 0xbfb8aa3b, v97
	v_mul_f32_e32 v88, 0xbfb8aa3b, v93
	v_exp_f32_e32 v87, v87
	v_exp_f32_e32 v88, v88
	v_add_f32_e32 v86, 1.0, v90
	v_rcp_f32_e32 v86, v86
	v_add_f32_e32 v87, 1.0, v87
	v_add_f32_e32 v88, 1.0, v88
	v_rcp_f32_e32 v87, v87
	v_rcp_f32_e32 v88, v88
	v_mul_f32_e32 v86, v92, v86
	v_mul_f32_e32 v90, v86, v84
	v_mul_f32_e32 v84, v97, v87
	v_mul_f32_e32 v86, v93, v88
	v_mul_f32_e32 v84, v84, v89
	v_mul_f32_e32 v85, v86, v85
	v_lshl_add_u64 v[86:87], v[98:99], 0, v[114:115]
	v_cvt_pk_bf16_f32 v82, v94, v82
	v_cvt_pk_bf16_f32 v83, v83, v84
	v_cvt_pk_bf16_f32 v84, v101, v91
	v_cvt_pk_bf16_f32 v85, v90, v85
	global_store_dwordx4 v[86:87], v[82:85], off
	s_nop 1
	v_mul_f32_e32 v82, 0xbfb8aa3b, v78
	v_exp_f32_e32 v82, v82
	v_mul_f32_e32 v83, 0xbfb8aa3b, v74
	v_exp_f32_e32 v83, v83
	v_or_b32_e32 v84, 48, v146
	v_add_f32_e32 v82, 1.0, v82
	v_rcp_f32_e32 v85, v82
	v_add_f32_e32 v82, 1.0, v83
	v_rcp_f32_e32 v86, v82
	v_mad_i64_i32 v[82:83], s[20:21], v84, s58, v[138:139]
	v_mul_f32_e32 v78, v78, v85
	v_mul_f32_e32 v78, v78, v70
	v_mul_f32_e32 v70, v74, v86
	v_mul_f32_e32 v74, 0xbfb8aa3b, v79
	v_exp_f32_e32 v74, v74
	v_mul_f32_e32 v84, 0xbfb8aa3b, v75
	v_mul_f32_e32 v85, v70, v66
	v_exp_f32_e32 v84, v84
	v_add_f32_e32 v66, 1.0, v74
	v_rcp_f32_e32 v66, v66
	v_mul_f32_e32 v74, 0xbfb8aa3b, v80
	v_exp_f32_e32 v74, v74
	v_add_f32_e32 v70, 1.0, v84
	v_mul_f32_e32 v66, v79, v66
	v_rcp_f32_e32 v70, v70
	v_mul_f32_e32 v66, v66, v71
	v_add_f32_e32 v71, 1.0, v74
	v_rcp_f32_e32 v71, v71
	v_mul_f32_e32 v70, v75, v70
	v_mul_f32_e32 v74, 0xbfb8aa3b, v76
	v_mul_f32_e32 v75, v70, v67
	v_mul_f32_e32 v67, v80, v71
	v_exp_f32_e32 v74, v74
	v_mul_f32_e32 v67, v67, v72
	v_mul_f32_e32 v71, 0xbfb8aa3b, v81
	v_mul_f32_e32 v72, 0xbfb8aa3b, v77
	v_exp_f32_e32 v71, v71
	v_exp_f32_e32 v72, v72
	v_add_f32_e32 v70, 1.0, v74
	v_rcp_f32_e32 v70, v70
	v_add_f32_e32 v71, 1.0, v71
	v_add_f32_e32 v72, 1.0, v72
	v_rcp_f32_e32 v71, v71
	v_rcp_f32_e32 v72, v72
	v_mul_f32_e32 v70, v76, v70
	v_mul_f32_e32 v74, v70, v68
	v_mul_f32_e32 v68, v81, v71
	v_mul_f32_e32 v70, v77, v72
	v_mul_f32_e32 v68, v68, v73
	v_mul_f32_e32 v69, v70, v69
	v_lshl_add_u64 v[70:71], v[82:83], 0, v[114:115]
	v_cvt_pk_bf16_f32 v66, v78, v66
	v_cvt_pk_bf16_f32 v67, v67, v68
	v_cvt_pk_bf16_f32 v68, v85, v75
	v_cvt_pk_bf16_f32 v69, v74, v69
	global_store_dwordx4 v[70:71], v[66:69], off
	s_nop 1
	v_mul_f32_e32 v66, 0xbfb8aa3b, v62
	v_exp_f32_e32 v66, v66
	v_mul_f32_e32 v67, 0xbfb8aa3b, v58
	v_exp_f32_e32 v67, v67
	v_add_u32_e32 v68, 0x80, v146
	v_add_f32_e32 v66, 1.0, v66
	v_rcp_f32_e32 v69, v66
	v_add_f32_e32 v66, 1.0, v67
	v_rcp_f32_e32 v70, v66
	v_mad_i64_i32 v[66:67], s[20:21], v68, s58, v[138:139]
	v_mul_f32_e32 v62, v62, v69
	v_mul_f32_e32 v62, v62, v54
	v_mul_f32_e32 v54, v58, v70
	v_mul_f32_e32 v58, 0xbfb8aa3b, v63
	v_exp_f32_e32 v58, v58
	v_mul_f32_e32 v68, 0xbfb8aa3b, v59
	v_mul_f32_e32 v69, v54, v50
	v_exp_f32_e32 v68, v68
	v_add_f32_e32 v50, 1.0, v58
	v_rcp_f32_e32 v50, v50
	v_mul_f32_e32 v58, 0xbfb8aa3b, v64
	v_exp_f32_e32 v58, v58
	v_add_f32_e32 v54, 1.0, v68
	v_mul_f32_e32 v50, v63, v50
	v_rcp_f32_e32 v54, v54
	v_mul_f32_e32 v50, v50, v55
	v_add_f32_e32 v55, 1.0, v58
	v_rcp_f32_e32 v55, v55
	v_mul_f32_e32 v54, v59, v54
	v_mul_f32_e32 v58, 0xbfb8aa3b, v60
	v_mul_f32_e32 v59, v54, v51
	v_mul_f32_e32 v51, v64, v55
	v_exp_f32_e32 v58, v58
	v_mul_f32_e32 v51, v51, v56
	v_mul_f32_e32 v55, 0xbfb8aa3b, v65
	v_mul_f32_e32 v56, 0xbfb8aa3b, v61
	v_exp_f32_e32 v55, v55
	v_exp_f32_e32 v56, v56
	v_add_f32_e32 v54, 1.0, v58
	v_rcp_f32_e32 v54, v54
	v_add_f32_e32 v55, 1.0, v55
	v_add_f32_e32 v56, 1.0, v56
	v_rcp_f32_e32 v55, v55
	v_rcp_f32_e32 v56, v56
	v_mul_f32_e32 v54, v60, v54
	v_mul_f32_e32 v58, v54, v52
	v_mul_f32_e32 v52, v65, v55
	v_mul_f32_e32 v54, v61, v56
	v_mul_f32_e32 v52, v52, v57
	v_mul_f32_e32 v53, v54, v53
	v_lshl_add_u64 v[54:55], v[66:67], 0, v[114:115]
	v_cvt_pk_bf16_f32 v50, v62, v50
	v_cvt_pk_bf16_f32 v51, v51, v52
	v_cvt_pk_bf16_f32 v52, v69, v59
	v_cvt_pk_bf16_f32 v53, v58, v53
	global_store_dwordx4 v[54:55], v[50:53], off
	s_nop 1
	v_mul_f32_e32 v50, 0xbfb8aa3b, v46
	v_exp_f32_e32 v50, v50
	v_mul_f32_e32 v51, 0xbfb8aa3b, v42
	v_exp_f32_e32 v51, v51
	v_add_u32_e32 v52, 0x90, v146
	v_add_f32_e32 v50, 1.0, v50
	v_rcp_f32_e32 v53, v50
	v_add_f32_e32 v50, 1.0, v51
	v_rcp_f32_e32 v54, v50
	v_mad_i64_i32 v[50:51], s[20:21], v52, s58, v[138:139]
	v_mul_f32_e32 v46, v46, v53
	v_mul_f32_e32 v46, v46, v38
	v_mul_f32_e32 v38, v42, v54
	v_mul_f32_e32 v42, 0xbfb8aa3b, v47
	v_exp_f32_e32 v42, v42
	v_mul_f32_e32 v52, 0xbfb8aa3b, v43
	v_mul_f32_e32 v53, v38, v34
	v_exp_f32_e32 v52, v52
	v_add_f32_e32 v34, 1.0, v42
	v_rcp_f32_e32 v34, v34
	v_mul_f32_e32 v42, 0xbfb8aa3b, v48
	v_exp_f32_e32 v42, v42
	v_add_f32_e32 v38, 1.0, v52
	v_mul_f32_e32 v34, v47, v34
	v_rcp_f32_e32 v38, v38
	v_mul_f32_e32 v34, v34, v39
	v_add_f32_e32 v39, 1.0, v42
	v_rcp_f32_e32 v39, v39
	v_mul_f32_e32 v38, v43, v38
	v_mul_f32_e32 v42, 0xbfb8aa3b, v44
	v_mul_f32_e32 v43, v38, v35
	v_mul_f32_e32 v35, v48, v39
	v_exp_f32_e32 v42, v42
	v_mul_f32_e32 v35, v35, v40
	v_mul_f32_e32 v39, 0xbfb8aa3b, v49
	v_mul_f32_e32 v40, 0xbfb8aa3b, v45
	v_exp_f32_e32 v39, v39
	v_exp_f32_e32 v40, v40
	v_add_f32_e32 v38, 1.0, v42
	v_rcp_f32_e32 v38, v38
	v_add_f32_e32 v39, 1.0, v39
	v_add_f32_e32 v40, 1.0, v40
	v_rcp_f32_e32 v39, v39
	v_rcp_f32_e32 v40, v40
	v_mul_f32_e32 v38, v44, v38
	v_mul_f32_e32 v42, v38, v36
	v_mul_f32_e32 v36, v49, v39
	v_mul_f32_e32 v38, v45, v40
	v_mul_f32_e32 v36, v36, v41
	v_mul_f32_e32 v37, v38, v37
	v_lshl_add_u64 v[38:39], v[50:51], 0, v[114:115]
	v_cvt_pk_bf16_f32 v34, v46, v34
	v_cvt_pk_bf16_f32 v35, v35, v36
	v_cvt_pk_bf16_f32 v36, v53, v43
	v_cvt_pk_bf16_f32 v37, v42, v37
	global_store_dwordx4 v[38:39], v[34:37], off
	s_nop 1
	v_mul_f32_e32 v34, 0xbfb8aa3b, v30
	v_exp_f32_e32 v34, v34
	v_mul_f32_e32 v35, 0xbfb8aa3b, v26
	v_exp_f32_e32 v35, v35
	v_add_u32_e32 v36, 0xa0, v146
	v_add_f32_e32 v34, 1.0, v34
	v_rcp_f32_e32 v37, v34
	v_add_f32_e32 v34, 1.0, v35
	v_rcp_f32_e32 v38, v34
	v_mad_i64_i32 v[34:35], s[20:21], v36, s58, v[138:139]
	v_mul_f32_e32 v30, v30, v37
	v_mul_f32_e32 v30, v30, v22
	v_mul_f32_e32 v22, v26, v38
	v_mul_f32_e32 v26, 0xbfb8aa3b, v31
	v_exp_f32_e32 v26, v26
	v_mul_f32_e32 v36, 0xbfb8aa3b, v27
	v_mul_f32_e32 v37, v22, v18
	v_exp_f32_e32 v36, v36
	v_add_f32_e32 v18, 1.0, v26
	v_rcp_f32_e32 v18, v18
	v_mul_f32_e32 v26, 0xbfb8aa3b, v32
	v_exp_f32_e32 v26, v26
	v_add_f32_e32 v22, 1.0, v36
	v_mul_f32_e32 v18, v31, v18
	v_rcp_f32_e32 v22, v22
	v_mul_f32_e32 v18, v18, v23
	v_add_f32_e32 v23, 1.0, v26
	v_rcp_f32_e32 v23, v23
	v_mul_f32_e32 v22, v27, v22
	v_mul_f32_e32 v26, 0xbfb8aa3b, v28
	v_mul_f32_e32 v27, v22, v19
	v_mul_f32_e32 v19, v32, v23
	v_exp_f32_e32 v26, v26
	v_mul_f32_e32 v19, v19, v24
	v_mul_f32_e32 v23, 0xbfb8aa3b, v33
	v_mul_f32_e32 v24, 0xbfb8aa3b, v29
	v_exp_f32_e32 v23, v23
	v_exp_f32_e32 v24, v24
	v_add_f32_e32 v22, 1.0, v26
	v_rcp_f32_e32 v22, v22
	v_add_f32_e32 v23, 1.0, v23
	v_add_f32_e32 v24, 1.0, v24
	v_rcp_f32_e32 v23, v23
	v_rcp_f32_e32 v24, v24
	v_mul_f32_e32 v22, v28, v22
	v_mul_f32_e32 v26, v22, v20
	v_mul_f32_e32 v20, v33, v23
	v_mul_f32_e32 v22, v29, v24
	v_mul_f32_e32 v20, v20, v25
	v_mul_f32_e32 v21, v22, v21
	v_lshl_add_u64 v[22:23], v[34:35], 0, v[114:115]
	v_cvt_pk_bf16_f32 v18, v30, v18
	v_cvt_pk_bf16_f32 v19, v19, v20
	v_cvt_pk_bf16_f32 v20, v37, v27
	v_cvt_pk_bf16_f32 v21, v26, v21
	global_store_dwordx4 v[22:23], v[18:21], off
	s_nop 1
	v_mul_f32_e32 v18, 0xbfb8aa3b, v14
	v_exp_f32_e32 v18, v18
	v_mul_f32_e32 v19, 0xbfb8aa3b, v10
	v_exp_f32_e32 v19, v19
	v_add_u32_e32 v20, 0xb0, v146
	v_add_f32_e32 v18, 1.0, v18
	v_rcp_f32_e32 v21, v18
	v_add_f32_e32 v18, 1.0, v19
	v_rcp_f32_e32 v22, v18
	v_mad_i64_i32 v[18:19], s[20:21], v20, s58, v[138:139]
	v_mul_f32_e32 v14, v14, v21
	v_mul_f32_e32 v14, v14, v6
	v_mul_f32_e32 v6, v10, v22
	v_mul_f32_e32 v10, 0xbfb8aa3b, v15
	v_exp_f32_e32 v10, v10
	v_mul_f32_e32 v20, 0xbfb8aa3b, v11
	v_mul_f32_e32 v21, v6, v2
	v_exp_f32_e32 v20, v20
	v_add_f32_e32 v2, 1.0, v10
	v_rcp_f32_e32 v2, v2
	v_mul_f32_e32 v10, 0xbfb8aa3b, v16
	v_exp_f32_e32 v10, v10
	v_add_f32_e32 v6, 1.0, v20
	v_mul_f32_e32 v2, v15, v2
	v_rcp_f32_e32 v6, v6
	v_mul_f32_e32 v2, v2, v7
	v_add_f32_e32 v7, 1.0, v10
	v_rcp_f32_e32 v7, v7
	v_mul_f32_e32 v6, v11, v6
	v_mul_f32_e32 v10, 0xbfb8aa3b, v12
	v_mul_f32_e32 v11, v6, v3
	v_mul_f32_e32 v3, v16, v7
	v_exp_f32_e32 v10, v10
	v_mul_f32_e32 v3, v3, v8
	v_mul_f32_e32 v7, 0xbfb8aa3b, v17
	v_mul_f32_e32 v8, 0xbfb8aa3b, v13
	v_exp_f32_e32 v7, v7
	v_exp_f32_e32 v8, v8
	v_add_f32_e32 v6, 1.0, v10
	v_rcp_f32_e32 v6, v6
	v_add_f32_e32 v7, 1.0, v7
	v_add_f32_e32 v8, 1.0, v8
	v_rcp_f32_e32 v7, v7
	v_rcp_f32_e32 v8, v8
	v_mul_f32_e32 v6, v12, v6
	v_mul_f32_e32 v10, v6, v4
	v_mul_f32_e32 v4, v17, v7
	v_mul_f32_e32 v6, v13, v8
	v_mul_f32_e32 v4, v4, v9
	v_mul_f32_e32 v5, v6, v5
	v_lshl_add_u64 v[6:7], v[18:19], 0, v[114:115]
	s_mov_b32 s20, s4
	v_cvt_pk_bf16_f32 v2, v14, v2
	v_cvt_pk_bf16_f32 v3, v3, v4
	v_cvt_pk_bf16_f32 v4, v21, v11
	v_cvt_pk_bf16_f32 v5, v10, v5
	global_store_dwordx4 v[6:7], v[2:5], off
	s_cbranch_vccz .LBB0_1031
	s_waitcnt vmcnt(0)
	s_cmpk_gt_u32 s24, 0xff
	s_cbranch_scc1 .LBB0_1042
	s_barrier

.LBB0_1120:
	ds_read_b128 v[150:153], v157
	ds_read_b128 v[182:185], v157 offset:1024
	ds_read_b128 v[186:189], v157 offset:2048
	ds_read_b128 v[190:193], v157 offset:3072
	s_add_u32 s40, s38, 0xfff50080
	s_addc_u32 s41, s39, -1
	s_cmp_eq_u32 s65, 40
	s_cselect_b32 s43, s5, s41
	s_cselect_b32 s42, s4, s40
	s_cselect_b32 s41, s1, s23
	s_cselect_b32 s40, s0, s22
	v_lshl_add_u64 v[146:147], s[38:39], 0, v[138:139]
	s_add_i32 m0, s47, 0xc000
	ds_read_b128 v[194:197], v158
	ds_read_b128 v[198:201], v158 offset:1024
	ds_read_b128 v[202:205], v158 offset:2048
	ds_read_b128 v[206:209], v158 offset:3072
	ds_read_b128 v[210:213], v158 offset:4096
	ds_read_b128 v[214:217], v158 offset:5120
	ds_read_b128 v[218:221], v158 offset:6144
	ds_read_b128 v[222:225], v158 offset:7168
	global_load_lds_dwordx4 v[146:147], off
	v_lshl_add_u64 v[146:147], s[38:39], 0, v[140:141]
	s_add_i32 m0, s47, 0xe000
	s_nop 0
	global_load_lds_dwordx4 v[146:147], off
	s_waitcnt lgkmcnt(8)
	s_barrier
	s_waitcnt lgkmcnt(0)
	s_waitcnt lgkmcnt(0)
	v_mfma_f32_16x16x32_bf16 v[126:129], v[150:153], v[194:197], v[126:129]
	v_mfma_f32_16x16x32_bf16 v[122:125], v[186:189], v[194:197], v[122:125]
	v_mfma_f32_16x16x32_bf16 v[114:117], v[150:153], v[202:205], v[114:117]
	v_mfma_f32_16x16x32_bf16 v[106:109], v[186:189], v[202:205], v[106:109]
	v_mfma_f32_16x16x32_bf16 v[98:101], v[150:153], v[210:213], v[98:101]
	v_mfma_f32_16x16x32_bf16 v[90:93], v[186:189], v[210:213], v[90:93]
	v_mfma_f32_16x16x32_bf16 v[82:85], v[150:153], v[218:221], v[82:85]
	v_mfma_f32_16x16x32_bf16 v[74:77], v[186:189], v[218:221], v[74:77]
	v_mfma_f32_16x16x32_bf16 v[126:129], v[182:185], v[198:201], v[126:129]
	v_mfma_f32_16x16x32_bf16 v[122:125], v[190:193], v[198:201], v[122:125]
	v_mfma_f32_16x16x32_bf16 v[114:117], v[182:185], v[206:209], v[114:117]
	v_mfma_f32_16x16x32_bf16 v[106:109], v[190:193], v[206:209], v[106:109]
	v_mfma_f32_16x16x32_bf16 v[98:101], v[182:185], v[214:217], v[98:101]
	v_mfma_f32_16x16x32_bf16 v[90:93], v[190:193], v[214:217], v[90:93]
	v_mfma_f32_16x16x32_bf16 v[82:85], v[182:185], v[222:225], v[82:85]
	v_mfma_f32_16x16x32_bf16 v[74:77], v[190:193], v[222:225], v[74:77]
	s_barrier
	s_add_i32 s66, s57, s46
	v_lshl_add_u64 v[146:147], s[40:41], 0, v[132:133]
	s_mov_b32 m0, s66
	ds_read_b128 v[226:229], v159
	ds_read_b128 v[230:233], v159 offset:1024
	ds_read_b128 v[234:237], v159 offset:2048
	ds_read_b128 v[238:241], v159 offset:3072
	global_load_lds_dwordx4 v[146:147], off
	v_lshl_add_u64 v[242:243], s[40:41], 0, v[136:137]
	s_add_i32 m0, s66, 0x2000
	s_nop 0
	global_load_lds_dwordx4 v[242:243], off
	s_barrier
	s_waitcnt lgkmcnt(0)
	s_waitcnt lgkmcnt(0)
	v_mfma_f32_16x16x32_bf16 v[118:121], v[226:229], v[194:197], v[118:121]
	v_mfma_f32_16x16x32_bf16 v[110:113], v[234:237], v[194:197], v[110:113]
	v_mfma_f32_16x16x32_bf16 v[102:105], v[226:229], v[202:205], v[102:105]
	v_mfma_f32_16x16x32_bf16 v[94:97], v[234:237], v[202:205], v[94:97]
	v_mfma_f32_16x16x32_bf16 v[86:89], v[226:229], v[210:213], v[86:89]
	v_mfma_f32_16x16x32_bf16 v[78:81], v[234:237], v[210:213], v[78:81]
	v_mfma_f32_16x16x32_bf16 v[70:73], v[226:229], v[218:221], v[70:73]
	v_mfma_f32_16x16x32_bf16 v[66:69], v[234:237], v[218:221], v[66:69]
	v_mfma_f32_16x16x32_bf16 v[118:121], v[230:233], v[198:201], v[118:121]
	v_mfma_f32_16x16x32_bf16 v[110:113], v[238:241], v[198:201], v[110:113]
	v_mfma_f32_16x16x32_bf16 v[102:105], v[230:233], v[206:209], v[102:105]
	v_mfma_f32_16x16x32_bf16 v[94:97], v[238:241], v[206:209], v[94:97]
	v_mfma_f32_16x16x32_bf16 v[86:89], v[230:233], v[214:217], v[86:89]
	v_mfma_f32_16x16x32_bf16 v[78:81], v[238:241], v[214:217], v[78:81]
	v_mfma_f32_16x16x32_bf16 v[70:73], v[230:233], v[222:225], v[70:73]
	v_mfma_f32_16x16x32_bf16 v[66:69], v[238:241], v[222:225], v[66:69]
	s_mov_b32 m0, s47
	v_lshl_add_u64 v[244:245], s[42:43], 0, v[130:131]
	s_barrier
	ds_read_b128 v[194:197], v158 offset:16384
	ds_read_b128 v[198:201], v158 offset:17408
	ds_read_b128 v[202:205], v158 offset:18432
	ds_read_b128 v[206:209], v158 offset:19456
	ds_read_b128 v[210:213], v158 offset:20480
	ds_read_b128 v[214:217], v158 offset:21504
	ds_read_b128 v[218:221], v158 offset:22528
	ds_read_b128 v[222:225], v158 offset:23552
	global_load_lds_dwordx4 v[244:245], off
	v_lshl_add_u64 v[246:247], s[42:43], 0, v[134:135]
	s_mov_b32 m0, s50
	s_nop 0
	global_load_lds_dwordx4 v[246:247], off
	s_barrier
	s_waitcnt lgkmcnt(0)
	s_waitcnt lgkmcnt(0)
	v_mfma_f32_16x16x32_bf16 v[62:65], v[150:153], v[194:197], v[62:65]
	v_mfma_f32_16x16x32_bf16 v[58:61], v[186:189], v[194:197], v[58:61]
	v_mfma_f32_16x16x32_bf16 v[50:53], v[150:153], v[202:205], v[50:53]
	v_mfma_f32_16x16x32_bf16 v[42:45], v[186:189], v[202:205], v[42:45]
	v_mfma_f32_16x16x32_bf16 v[34:37], v[150:153], v[210:213], v[34:37]
	v_mfma_f32_16x16x32_bf16 v[26:29], v[186:189], v[210:213], v[26:29]
	v_mfma_f32_16x16x32_bf16 v[18:21], v[150:153], v[218:221], v[18:21]
	v_mfma_f32_16x16x32_bf16 v[10:13], v[186:189], v[218:221], v[10:13]
	v_mfma_f32_16x16x32_bf16 v[62:65], v[182:185], v[198:201], v[62:65]
	v_mfma_f32_16x16x32_bf16 v[58:61], v[190:193], v[198:201], v[58:61]
	v_mfma_f32_16x16x32_bf16 v[50:53], v[182:185], v[206:209], v[50:53]
	v_mfma_f32_16x16x32_bf16 v[42:45], v[190:193], v[206:209], v[42:45]
	v_mfma_f32_16x16x32_bf16 v[34:37], v[182:185], v[214:217], v[34:37]
	v_mfma_f32_16x16x32_bf16 v[26:29], v[190:193], v[214:217], v[26:29]
	v_mfma_f32_16x16x32_bf16 v[18:21], v[182:185], v[222:225], v[18:21]
	v_mfma_f32_16x16x32_bf16 v[10:13], v[190:193], v[222:225], v[10:13]
	s_barrier
	s_add_u32 s66, s40, 0xb0000
	s_addc_u32 s67, s41, 0
	s_add_i32 s68, s58, s46
	v_lshl_add_u64 v[150:151], s[66:67], 0, v[132:133]
	s_mov_b32 m0, s68
	s_nop 0
	global_load_lds_dwordx4 v[150:151], off
	v_lshl_add_u64 v[150:151], s[66:67], 0, v[136:137]
	s_add_i32 m0, s68, 0x2000
	s_nop 0
	global_load_lds_dwordx4 v[150:151], off
	s_waitcnt vmcnt(6)
	s_barrier
	v_mfma_f32_16x16x32_bf16 v[54:57], v[226:229], v[194:197], v[54:57]
	v_mfma_f32_16x16x32_bf16 v[46:49], v[234:237], v[194:197], v[46:49]
	v_mfma_f32_16x16x32_bf16 v[38:41], v[226:229], v[202:205], v[38:41]
	v_mfma_f32_16x16x32_bf16 v[30:33], v[234:237], v[202:205], v[30:33]
	v_mfma_f32_16x16x32_bf16 v[22:25], v[226:229], v[210:213], v[22:25]
	v_mfma_f32_16x16x32_bf16 v[14:17], v[234:237], v[210:213], v[14:17]
	v_mfma_f32_16x16x32_bf16 v[6:9], v[226:229], v[218:221], v[6:9]
	v_mfma_f32_16x16x32_bf16 v[2:5], v[234:237], v[218:221], v[2:5]
	v_mfma_f32_16x16x32_bf16 v[54:57], v[230:233], v[198:201], v[54:57]
	v_mfma_f32_16x16x32_bf16 v[46:49], v[238:241], v[198:201], v[46:49]
	v_mfma_f32_16x16x32_bf16 v[38:41], v[230:233], v[206:209], v[38:41]
	v_mfma_f32_16x16x32_bf16 v[30:33], v[238:241], v[206:209], v[30:33]
	v_mfma_f32_16x16x32_bf16 v[22:25], v[230:233], v[214:217], v[22:25]
	v_mfma_f32_16x16x32_bf16 v[14:17], v[238:241], v[214:217], v[14:17]
	v_mfma_f32_16x16x32_bf16 v[6:9], v[230:233], v[222:225], v[6:9]
	v_mfma_f32_16x16x32_bf16 v[2:5], v[238:241], v[222:225], v[2:5]
	s_add_i32 s66, 0, 0x18000
	v_add_u32_e32 v169, s66, v155
	s_barrier
	ds_read_b128 v[150:153], v169
	ds_read_b128 v[182:185], v169 offset:1024
	ds_read_b128 v[186:189], v169 offset:2048
	ds_read_b128 v[190:193], v169 offset:3072
	s_add_u32 s42, s42, 0xb0000
	s_addc_u32 s43, s43, 0
	s_mov_b32 m0, s51
	v_lshl_add_u64 v[226:227], s[42:43], 0, v[130:131]
	ds_read_b128 v[194:197], v158 offset:32768
	ds_read_b128 v[198:201], v158 offset:33792
	ds_read_b128 v[202:205], v158 offset:34816
	ds_read_b128 v[206:209], v158 offset:35840
	ds_read_b128 v[210:213], v158 offset:36864
	ds_read_b128 v[214:217], v158 offset:37888
	ds_read_b128 v[218:221], v158 offset:38912
	ds_read_b128 v[222:225], v158 offset:39936
	global_load_lds_dwordx4 v[226:227], off
	v_lshl_add_u64 v[226:227], s[42:43], 0, v[134:135]
	s_mov_b32 m0, s52
	s_nop 0
	global_load_lds_dwordx4 v[226:227], off
	s_waitcnt lgkmcnt(8)
	s_barrier
	s_waitcnt lgkmcnt(0)
	s_waitcnt lgkmcnt(0)
	v_mfma_f32_16x16x32_bf16 v[126:129], v[150:153], v[194:197], v[126:129]
	v_mfma_f32_16x16x32_bf16 v[122:125], v[186:189], v[194:197], v[122:125]
	v_mfma_f32_16x16x32_bf16 v[114:117], v[150:153], v[202:205], v[114:117]
	v_mfma_f32_16x16x32_bf16 v[106:109], v[186:189], v[202:205], v[106:109]
	v_mfma_f32_16x16x32_bf16 v[98:101], v[150:153], v[210:213], v[98:101]
	v_mfma_f32_16x16x32_bf16 v[90:93], v[186:189], v[210:213], v[90:93]
	v_mfma_f32_16x16x32_bf16 v[82:85], v[150:153], v[218:221], v[82:85]
	v_mfma_f32_16x16x32_bf16 v[74:77], v[186:189], v[218:221], v[74:77]
	v_mfma_f32_16x16x32_bf16 v[126:129], v[182:185], v[198:201], v[126:129]
	v_mfma_f32_16x16x32_bf16 v[122:125], v[190:193], v[198:201], v[122:125]
	v_mfma_f32_16x16x32_bf16 v[114:117], v[182:185], v[206:209], v[114:117]
	v_mfma_f32_16x16x32_bf16 v[106:109], v[190:193], v[206:209], v[106:109]
	v_mfma_f32_16x16x32_bf16 v[98:101], v[182:185], v[214:217], v[98:101]
	v_mfma_f32_16x16x32_bf16 v[90:93], v[190:193], v[214:217], v[90:93]
	v_mfma_f32_16x16x32_bf16 v[82:85], v[182:185], v[222:225], v[82:85]
	v_mfma_f32_16x16x32_bf16 v[74:77], v[190:193], v[222:225], v[74:77]
	s_barrier
	s_add_i32 s42, 0, 0x1c000
	s_add_i32 s43, s66, s46
	v_add_u32_e32 v169, s42, v155
	v_lshl_add_u64 v[146:147], v[146:147], 0, s[12:13]
	s_mov_b32 m0, s43
	ds_read_b128 v[226:229], v169
	ds_read_b128 v[230:233], v169 offset:1024
	ds_read_b128 v[234:237], v169 offset:2048
	ds_read_b128 v[238:241], v169 offset:3072
	global_load_lds_dwordx4 v[146:147], off
	v_lshl_add_u64 v[146:147], v[242:243], 0, s[12:13]
	s_add_i32 m0, s43, 0x2000
	s_nop 0
	global_load_lds_dwordx4 v[146:147], off
	s_barrier
	s_waitcnt lgkmcnt(0)
	s_waitcnt lgkmcnt(0)
	v_mfma_f32_16x16x32_bf16 v[118:121], v[226:229], v[194:197], v[118:121]
	v_mfma_f32_16x16x32_bf16 v[110:113], v[234:237], v[194:197], v[110:113]
	v_mfma_f32_16x16x32_bf16 v[102:105], v[226:229], v[202:205], v[102:105]
	v_mfma_f32_16x16x32_bf16 v[94:97], v[234:237], v[202:205], v[94:97]
	v_mfma_f32_16x16x32_bf16 v[86:89], v[226:229], v[210:213], v[86:89]
	v_mfma_f32_16x16x32_bf16 v[78:81], v[234:237], v[210:213], v[78:81]
	v_mfma_f32_16x16x32_bf16 v[70:73], v[226:229], v[218:221], v[70:73]
	v_mfma_f32_16x16x32_bf16 v[66:69], v[234:237], v[218:221], v[66:69]
	v_mfma_f32_16x16x32_bf16 v[118:121], v[230:233], v[198:201], v[118:121]
	v_mfma_f32_16x16x32_bf16 v[110:113], v[238:241], v[198:201], v[110:113]
	v_mfma_f32_16x16x32_bf16 v[102:105], v[230:233], v[206:209], v[102:105]
	v_mfma_f32_16x16x32_bf16 v[94:97], v[238:241], v[206:209], v[94:97]
	v_mfma_f32_16x16x32_bf16 v[86:89], v[230:233], v[214:217], v[86:89]
	v_mfma_f32_16x16x32_bf16 v[78:81], v[238:241], v[214:217], v[78:81]
	v_mfma_f32_16x16x32_bf16 v[70:73], v[230:233], v[222:225], v[70:73]
	v_mfma_f32_16x16x32_bf16 v[66:69], v[238:241], v[222:225], v[66:69]
	s_mov_b32 m0, s54
	v_lshl_add_u64 v[146:147], v[244:245], 0, s[12:13]
	s_barrier
	ds_read_b128 v[194:197], v158 offset:49152
	ds_read_b128 v[198:201], v158 offset:50176
	ds_read_b128 v[202:205], v158 offset:51200
	ds_read_b128 v[206:209], v158 offset:52224
	ds_read_b128 v[210:213], v158 offset:53248
	ds_read_b128 v[214:217], v158 offset:54272
	ds_read_b128 v[218:221], v158 offset:55296
	ds_read_b128 v[222:225], v158 offset:56320
	global_load_lds_dwordx4 v[146:147], off
	v_lshl_add_u64 v[146:147], v[246:247], 0, s[12:13]
	s_mov_b32 m0, s55
	s_nop 0
	global_load_lds_dwordx4 v[146:147], off
	s_barrier
	s_waitcnt lgkmcnt(0)
	s_waitcnt lgkmcnt(0)
	v_mfma_f32_16x16x32_bf16 v[62:65], v[150:153], v[194:197], v[62:65]
	v_mfma_f32_16x16x32_bf16 v[58:61], v[186:189], v[194:197], v[58:61]
	v_mfma_f32_16x16x32_bf16 v[50:53], v[150:153], v[202:205], v[50:53]
	v_mfma_f32_16x16x32_bf16 v[42:45], v[186:189], v[202:205], v[42:45]
	v_mfma_f32_16x16x32_bf16 v[34:37], v[150:153], v[210:213], v[34:37]
	v_mfma_f32_16x16x32_bf16 v[26:29], v[186:189], v[210:213], v[26:29]
	v_mfma_f32_16x16x32_bf16 v[18:21], v[150:153], v[218:221], v[18:21]
	v_mfma_f32_16x16x32_bf16 v[10:13], v[186:189], v[218:221], v[10:13]
	v_mfma_f32_16x16x32_bf16 v[62:65], v[182:185], v[198:201], v[62:65]
	v_mfma_f32_16x16x32_bf16 v[58:61], v[190:193], v[198:201], v[58:61]
	v_mfma_f32_16x16x32_bf16 v[50:53], v[182:185], v[206:209], v[50:53]
	v_mfma_f32_16x16x32_bf16 v[42:45], v[190:193], v[206:209], v[42:45]
	v_mfma_f32_16x16x32_bf16 v[34:37], v[182:185], v[214:217], v[34:37]
	v_mfma_f32_16x16x32_bf16 v[26:29], v[190:193], v[214:217], v[26:29]
	v_mfma_f32_16x16x32_bf16 v[18:21], v[182:185], v[222:225], v[18:21]
	v_mfma_f32_16x16x32_bf16 v[10:13], v[190:193], v[222:225], v[10:13]
	s_barrier
	s_add_u32 s40, s40, 0xb0080
	s_addc_u32 s41, s41, 0
	s_add_i32 s42, s42, s46
	v_lshl_add_u64 v[146:147], s[40:41], 0, v[132:133]
	s_mov_b32 m0, s42
	s_nop 0
	global_load_lds_dwordx4 v[146:147], off
	v_lshl_add_u64 v[146:147], s[40:41], 0, v[136:137]
	s_add_i32 m0, s42, 0x2000
	s_nop 0
	global_load_lds_dwordx4 v[146:147], off
	s_waitcnt vmcnt(6)
	s_barrier
	v_mfma_f32_16x16x32_bf16 v[54:57], v[226:229], v[194:197], v[54:57]
	v_mfma_f32_16x16x32_bf16 v[46:49], v[234:237], v[194:197], v[46:49]
	v_mfma_f32_16x16x32_bf16 v[38:41], v[226:229], v[202:205], v[38:41]
	v_mfma_f32_16x16x32_bf16 v[30:33], v[234:237], v[202:205], v[30:33]
	v_mfma_f32_16x16x32_bf16 v[22:25], v[226:229], v[210:213], v[22:25]
	v_mfma_f32_16x16x32_bf16 v[14:17], v[234:237], v[210:213], v[14:17]
	v_mfma_f32_16x16x32_bf16 v[6:9], v[226:229], v[218:221], v[6:9]
	v_mfma_f32_16x16x32_bf16 v[2:5], v[234:237], v[218:221], v[2:5]
	v_mfma_f32_16x16x32_bf16 v[54:57], v[230:233], v[198:201], v[54:57]
	v_mfma_f32_16x16x32_bf16 v[46:49], v[238:241], v[198:201], v[46:49]
	v_mfma_f32_16x16x32_bf16 v[38:41], v[230:233], v[206:209], v[38:41]
	v_mfma_f32_16x16x32_bf16 v[30:33], v[238:241], v[206:209], v[30:33]
	v_mfma_f32_16x16x32_bf16 v[22:25], v[230:233], v[214:217], v[22:25]
	v_mfma_f32_16x16x32_bf16 v[14:17], v[238:241], v[214:217], v[14:17]
	v_mfma_f32_16x16x32_bf16 v[6:9], v[230:233], v[222:225], v[6:9]
	v_mfma_f32_16x16x32_bf16 v[2:5], v[238:241], v[222:225], v[2:5]
	s_add_i32 s65, s65, 2
	s_add_u32 s38, s38, 0x100
	s_addc_u32 s39, s39, 0
	s_add_u32 s22, s22, 0x100
	s_addc_u32 s23, s23, 0
	s_cmp_gt_u32 s65, 41
	s_barrier
	s_cbranch_scc0 .LBB0_1120
	v_lshl_add_u32 v150, s20, 8, v154
	v_lshl_or_b32 v146, s21, 8, v156
	v_ashrrev_i32_e32 v151, 31, v150
	v_ashrrev_i32_e32 v147, 31, v146
	v_lshlrev_b64 v[152:153], 11, v[150:151]
	v_lshl_add_u64 v[182:183], s[8:9], 0, v[152:153]
	v_lshlrev_b64 v[152:153], 1, v[146:147]
	v_lshl_add_u64 v[146:147], v[182:183], 0, v[152:153]
	global_load_dwordx4 v[182:185], v[146:147], off
	s_mov_b32 s21, s63
	s_mov_b32 s20, s64
	s_mov_b64 s[40:41], s[0:1]
	s_mov_b64 s[38:39], s[4:5]
	s_waitcnt vmcnt(0)
	v_lshlrev_b32_e32 v186, 16, v182
	v_and_b32_e32 v187, 0xffff0000, v182
	v_lshlrev_b32_e32 v182, 16, v183
	v_and_b32_e32 v183, 0xffff0000, v183
	v_lshlrev_b32_e32 v188, 16, v184
	v_and_b32_e32 v189, 0xffff0000, v184
	v_lshlrev_b32_e32 v184, 16, v185
	v_and_b32_e32 v185, 0xffff0000, v185
	v_pk_add_f32 v[128:129], v[128:129], v[182:183]
	v_pk_add_f32 v[126:127], v[126:127], v[186:187]
	v_pk_add_f32 v[182:183], v[124:125], v[184:185]
	v_pk_add_f32 v[124:125], v[122:123], v[188:189]
	v_cvt_pk_bf16_f32 v122, v126, v127
	v_cvt_pk_bf16_f32 v123, v128, v129
	s_nop 0
	v_cvt_pk_bf16_f32 v124, v124, v125
	v_cvt_pk_bf16_f32 v125, v182, v183
	global_load_dwordx4 v[126:129], v[146:147], off offset:256
	v_or_b32_e32 v182, 16, v150
	v_ashrrev_i32_e32 v183, 31, v182
	v_lshlrev_b64 v[182:183], 11, v[182:183]
	v_lshl_add_u64 v[182:183], s[8:9], 0, v[182:183]
	global_store_dwordx4 v[146:147], v[122:125], off
	v_lshl_add_u64 v[182:183], v[182:183], 0, v[152:153]
	s_waitcnt vmcnt(0)
	v_lshlrev_b32_e32 v122, 16, v126
	v_and_b32_e32 v123, 0xffff0000, v126
	v_lshlrev_b32_e32 v124, 16, v127
	v_and_b32_e32 v125, 0xffff0000, v127
	v_lshlrev_b32_e32 v126, 16, v128
	v_and_b32_e32 v127, 0xffff0000, v128
	v_lshlrev_b32_e32 v128, 16, v129
	v_and_b32_e32 v129, 0xffff0000, v129
	v_pk_add_f32 v[120:121], v[120:121], v[124:125]
	v_pk_add_f32 v[118:119], v[118:119], v[122:123]
	v_pk_add_f32 v[122:123], v[112:113], v[128:129]
	v_pk_add_f32 v[112:113], v[110:111], v[126:127]
	v_cvt_pk_bf16_f32 v110, v118, v119
	v_cvt_pk_bf16_f32 v111, v120, v121
	s_nop 0
	v_cvt_pk_bf16_f32 v112, v112, v113
	v_cvt_pk_bf16_f32 v113, v122, v123
	global_load_dwordx4 v[118:121], v[182:183], off
	s_nop 0
	global_store_dwordx4 v[146:147], v[110:113], off offset:256
	s_waitcnt vmcnt(0)
	s_nop 0
	v_lshlrev_b32_e32 v110, 16, v118
	v_and_b32_e32 v111, 0xffff0000, v118
	v_lshlrev_b32_e32 v112, 16, v119
	v_and_b32_e32 v113, 0xffff0000, v119
	v_lshlrev_b32_e32 v118, 16, v120
	v_and_b32_e32 v119, 0xffff0000, v120
	v_lshlrev_b32_e32 v120, 16, v121
	v_and_b32_e32 v121, 0xffff0000, v121
	v_pk_add_f32 v[112:113], v[116:117], v[112:113]
	v_pk_add_f32 v[110:111], v[114:115], v[110:111]
	v_pk_add_f32 v[114:115], v[108:109], v[120:121]
	v_pk_add_f32 v[108:109], v[106:107], v[118:119]
	v_cvt_pk_bf16_f32 v106, v110, v111
	v_cvt_pk_bf16_f32 v107, v112, v113
	s_nop 0
	v_cvt_pk_bf16_f32 v108, v108, v109
	v_cvt_pk_bf16_f32 v109, v114, v115
	global_load_dwordx4 v[110:113], v[182:183], off offset:256
	v_or_b32_e32 v114, 32, v150
	v_ashrrev_i32_e32 v115, 31, v114
	v_lshlrev_b64 v[114:115], 11, v[114:115]
	v_lshl_add_u64 v[114:115], s[8:9], 0, v[114:115]
	global_store_dwordx4 v[182:183], v[106:109], off
	v_lshl_add_u64 v[114:115], v[114:115], 0, v[152:153]
	s_waitcnt vmcnt(0)
	v_lshlrev_b32_e32 v106, 16, v110
	v_and_b32_e32 v107, 0xffff0000, v110
	v_lshlrev_b32_e32 v108, 16, v111
	v_and_b32_e32 v109, 0xffff0000, v111
	v_lshlrev_b32_e32 v110, 16, v112
	v_and_b32_e32 v111, 0xffff0000, v112
	v_lshlrev_b32_e32 v112, 16, v113
	v_and_b32_e32 v113, 0xffff0000, v113
	v_pk_add_f32 v[104:105], v[104:105], v[108:109]
	v_pk_add_f32 v[102:103], v[102:103], v[106:107]
	v_pk_add_f32 v[106:107], v[96:97], v[112:113]
	v_pk_add_f32 v[96:97], v[94:95], v[110:111]
	v_cvt_pk_bf16_f32 v94, v102, v103
	v_cvt_pk_bf16_f32 v95, v104, v105
	s_nop 0
	v_cvt_pk_bf16_f32 v96, v96, v97
	v_cvt_pk_bf16_f32 v97, v106, v107
	global_load_dwordx4 v[102:105], v[114:115], off
	s_nop 0
	global_store_dwordx4 v[182:183], v[94:97], off offset:256
	s_waitcnt vmcnt(0)
	s_nop 0
	v_lshlrev_b32_e32 v94, 16, v102
	v_and_b32_e32 v95, 0xffff0000, v102
	v_lshlrev_b32_e32 v96, 16, v103
	v_and_b32_e32 v97, 0xffff0000, v103
	v_lshlrev_b32_e32 v102, 16, v104
	v_and_b32_e32 v103, 0xffff0000, v104
	v_lshlrev_b32_e32 v104, 16, v105
	v_and_b32_e32 v105, 0xffff0000, v105
	v_pk_add_f32 v[96:97], v[100:101], v[96:97]
	v_pk_add_f32 v[94:95], v[98:99], v[94:95]
	v_pk_add_f32 v[98:99], v[92:93], v[104:105]
	v_pk_add_f32 v[92:93], v[90:91], v[102:103]
	v_cvt_pk_bf16_f32 v90, v94, v95
	v_cvt_pk_bf16_f32 v91, v96, v97
	s_nop 0
	v_cvt_pk_bf16_f32 v92, v92, v93
	v_cvt_pk_bf16_f32 v93, v98, v99
	global_load_dwordx4 v[94:97], v[114:115], off offset:256
	v_or_b32_e32 v98, 48, v150
	v_ashrrev_i32_e32 v99, 31, v98
	v_lshlrev_b64 v[98:99], 11, v[98:99]
	v_lshl_add_u64 v[98:99], s[8:9], 0, v[98:99]
	global_store_dwordx4 v[114:115], v[90:93], off
	v_lshl_add_u64 v[98:99], v[98:99], 0, v[152:153]
	s_waitcnt vmcnt(0)
	v_lshlrev_b32_e32 v90, 16, v94
	v_and_b32_e32 v91, 0xffff0000, v94
	v_lshlrev_b32_e32 v92, 16, v95
	v_and_b32_e32 v93, 0xffff0000, v95
	v_lshlrev_b32_e32 v94, 16, v96
	v_and_b32_e32 v95, 0xffff0000, v96
	v_lshlrev_b32_e32 v96, 16, v97
	v_and_b32_e32 v97, 0xffff0000, v97
	v_pk_add_f32 v[88:89], v[88:89], v[92:93]
	v_pk_add_f32 v[86:87], v[86:87], v[90:91]
	v_pk_add_f32 v[90:91], v[80:81], v[96:97]
	v_pk_add_f32 v[80:81], v[78:79], v[94:95]
	v_cvt_pk_bf16_f32 v78, v86, v87
	v_cvt_pk_bf16_f32 v79, v88, v89
	s_nop 0
	v_cvt_pk_bf16_f32 v80, v80, v81
	v_cvt_pk_bf16_f32 v81, v90, v91
	global_load_dwordx4 v[86:89], v[98:99], off
	s_nop 0
	global_store_dwordx4 v[114:115], v[78:81], off offset:256
	s_waitcnt vmcnt(0)
	s_nop 0
	v_lshlrev_b32_e32 v78, 16, v86
	v_and_b32_e32 v79, 0xffff0000, v86
	v_lshlrev_b32_e32 v80, 16, v87
	v_and_b32_e32 v81, 0xffff0000, v87
	v_lshlrev_b32_e32 v86, 16, v88
	v_and_b32_e32 v87, 0xffff0000, v88
	v_lshlrev_b32_e32 v88, 16, v89
	v_and_b32_e32 v89, 0xffff0000, v89
	v_pk_add_f32 v[80:81], v[84:85], v[80:81]
	v_pk_add_f32 v[78:79], v[82:83], v[78:79]
	v_pk_add_f32 v[82:83], v[76:77], v[88:89]
	v_pk_add_f32 v[76:77], v[74:75], v[86:87]
	v_cvt_pk_bf16_f32 v74, v78, v79
	v_cvt_pk_bf16_f32 v75, v80, v81
	s_nop 0
	v_cvt_pk_bf16_f32 v76, v76, v77
	v_cvt_pk_bf16_f32 v77, v82, v83
	global_load_dwordx4 v[78:81], v[98:99], off offset:256
	v_add_co_u32_e32 v82, vcc, s59, v146
	global_store_dwordx4 v[98:99], v[74:77], off
	s_nop 0
	v_addc_co_u32_e32 v83, vcc, 0, v147, vcc
	s_waitcnt vmcnt(0)
	v_lshlrev_b32_e32 v74, 16, v78
	v_and_b32_e32 v75, 0xffff0000, v78
	v_lshlrev_b32_e32 v76, 16, v79
	v_and_b32_e32 v77, 0xffff0000, v79
	v_lshlrev_b32_e32 v78, 16, v80
	v_and_b32_e32 v79, 0xffff0000, v80
	v_lshlrev_b32_e32 v80, 16, v81
	v_and_b32_e32 v81, 0xffff0000, v81
	v_pk_add_f32 v[72:73], v[72:73], v[76:77]
	v_pk_add_f32 v[70:71], v[70:71], v[74:75]
	v_pk_add_f32 v[74:75], v[68:69], v[80:81]
	v_pk_add_f32 v[68:69], v[66:67], v[78:79]
	v_cvt_pk_bf16_f32 v66, v70, v71
	v_cvt_pk_bf16_f32 v67, v72, v73
	s_nop 0
	v_cvt_pk_bf16_f32 v68, v68, v69
	v_cvt_pk_bf16_f32 v69, v74, v75
	global_load_dwordx4 v[70:73], v[82:83], off
	v_lshl_add_u64 v[74:75], v[146:147], 0, s[28:29]
	global_store_dwordx4 v[98:99], v[66:69], off offset:256
	s_waitcnt vmcnt(0)
	s_nop 0
	v_lshlrev_b32_e32 v66, 16, v70
	v_and_b32_e32 v67, 0xffff0000, v70
	v_lshlrev_b32_e32 v68, 16, v71
	v_and_b32_e32 v69, 0xffff0000, v71
	v_lshlrev_b32_e32 v70, 16, v72
	v_and_b32_e32 v71, 0xffff0000, v72
	v_lshlrev_b32_e32 v72, 16, v73
	v_and_b32_e32 v73, 0xffff0000, v73
	v_pk_add_f32 v[64:65], v[64:65], v[68:69]
	v_pk_add_f32 v[62:63], v[62:63], v[66:67]
	v_pk_add_f32 v[66:67], v[60:61], v[72:73]
	v_pk_add_f32 v[60:61], v[58:59], v[70:71]
	v_cvt_pk_bf16_f32 v58, v62, v63
	v_cvt_pk_bf16_f32 v59, v64, v65
	s_nop 0
	v_cvt_pk_bf16_f32 v60, v60, v61
	v_cvt_pk_bf16_f32 v61, v66, v67
	global_load_dwordx4 v[62:65], v[74:75], off offset:256
	v_add_co_u32_e32 v66, vcc, s60, v146
	global_store_dwordx4 v[82:83], v[58:61], off
	s_nop 0
	v_addc_co_u32_e32 v67, vcc, 0, v147, vcc
	s_waitcnt vmcnt(0)
	v_lshlrev_b32_e32 v58, 16, v62
	v_and_b32_e32 v59, 0xffff0000, v62
	v_lshlrev_b32_e32 v60, 16, v63
	v_and_b32_e32 v61, 0xffff0000, v63
	v_lshlrev_b32_e32 v62, 16, v64
	v_and_b32_e32 v63, 0xffff0000, v64
	v_lshlrev_b32_e32 v64, 16, v65
	v_and_b32_e32 v65, 0xffff0000, v65
	v_pk_add_f32 v[56:57], v[56:57], v[60:61]
	v_pk_add_f32 v[54:55], v[54:55], v[58:59]
	v_pk_add_f32 v[58:59], v[48:49], v[64:65]
	v_pk_add_f32 v[48:49], v[46:47], v[62:63]
	v_cvt_pk_bf16_f32 v46, v54, v55
	v_cvt_pk_bf16_f32 v47, v56, v57
	s_nop 0
	v_cvt_pk_bf16_f32 v48, v48, v49
	v_cvt_pk_bf16_f32 v49, v58, v59
	global_load_dwordx4 v[54:57], v[66:67], off
	v_lshl_add_u64 v[58:59], v[146:147], 0, s[30:31]
	global_store_dwordx4 v[74:75], v[46:49], off offset:256
	s_waitcnt vmcnt(0)
	s_nop 0
	v_lshlrev_b32_e32 v46, 16, v54
	v_and_b32_e32 v47, 0xffff0000, v54
	v_lshlrev_b32_e32 v48, 16, v55
	v_and_b32_e32 v49, 0xffff0000, v55
	v_lshlrev_b32_e32 v54, 16, v56
	v_and_b32_e32 v55, 0xffff0000, v56
	v_lshlrev_b32_e32 v56, 16, v57
	v_and_b32_e32 v57, 0xffff0000, v57
	v_pk_add_f32 v[48:49], v[52:53], v[48:49]
	v_pk_add_f32 v[46:47], v[50:51], v[46:47]
	v_pk_add_f32 v[50:51], v[44:45], v[56:57]
	v_pk_add_f32 v[44:45], v[42:43], v[54:55]
	v_cvt_pk_bf16_f32 v42, v46, v47
	v_cvt_pk_bf16_f32 v43, v48, v49
	s_nop 0
	v_cvt_pk_bf16_f32 v44, v44, v45
	v_cvt_pk_bf16_f32 v45, v50, v51
	global_load_dwordx4 v[46:49], v[58:59], off offset:256
	v_add_co_u32_e32 v50, vcc, s61, v146
	global_store_dwordx4 v[66:67], v[42:45], off
	s_nop 0
	v_addc_co_u32_e32 v51, vcc, 0, v147, vcc
	s_waitcnt vmcnt(0)
	v_lshlrev_b32_e32 v42, 16, v46
	v_and_b32_e32 v43, 0xffff0000, v46
	v_lshlrev_b32_e32 v44, 16, v47
	v_and_b32_e32 v45, 0xffff0000, v47
	v_lshlrev_b32_e32 v46, 16, v48
	v_and_b32_e32 v47, 0xffff0000, v48
	v_lshlrev_b32_e32 v48, 16, v49
	v_and_b32_e32 v49, 0xffff0000, v49
	v_pk_add_f32 v[40:41], v[40:41], v[44:45]
	v_pk_add_f32 v[38:39], v[38:39], v[42:43]
	v_pk_add_f32 v[42:43], v[32:33], v[48:49]
	v_pk_add_f32 v[32:33], v[30:31], v[46:47]
	v_cvt_pk_bf16_f32 v30, v38, v39
	v_cvt_pk_bf16_f32 v31, v40, v41
	s_nop 0
	v_cvt_pk_bf16_f32 v32, v32, v33
	v_cvt_pk_bf16_f32 v33, v42, v43
	global_load_dwordx4 v[38:41], v[50:51], off
	v_lshl_add_u64 v[42:43], v[146:147], 0, s[34:35]
	global_store_dwordx4 v[58:59], v[30:33], off offset:256
	s_waitcnt vmcnt(0)
	s_nop 0
	v_lshlrev_b32_e32 v30, 16, v38
	v_and_b32_e32 v31, 0xffff0000, v38
	v_lshlrev_b32_e32 v32, 16, v39
	v_and_b32_e32 v33, 0xffff0000, v39
	v_lshlrev_b32_e32 v38, 16, v40
	v_and_b32_e32 v39, 0xffff0000, v40
	v_lshlrev_b32_e32 v40, 16, v41
	v_and_b32_e32 v41, 0xffff0000, v41
	v_pk_add_f32 v[32:33], v[36:37], v[32:33]
	v_pk_add_f32 v[30:31], v[34:35], v[30:31]
	v_pk_add_f32 v[34:35], v[28:29], v[40:41]
	v_pk_add_f32 v[28:29], v[26:27], v[38:39]
	v_cvt_pk_bf16_f32 v26, v30, v31
	v_cvt_pk_bf16_f32 v27, v32, v33
	s_nop 0
	v_cvt_pk_bf16_f32 v28, v28, v29
	v_cvt_pk_bf16_f32 v29, v34, v35
	global_load_dwordx4 v[30:33], v[42:43], off offset:256
	v_add_co_u32_e32 v34, vcc, s62, v146
	global_store_dwordx4 v[50:51], v[26:29], off
	s_nop 0
	v_addc_co_u32_e32 v35, vcc, 0, v147, vcc
	s_and_b64 vcc, exec, s[2:3]
	s_waitcnt vmcnt(0)
	v_lshlrev_b32_e32 v26, 16, v30
	v_and_b32_e32 v27, 0xffff0000, v30
	v_lshlrev_b32_e32 v28, 16, v31
	v_and_b32_e32 v29, 0xffff0000, v31
	v_lshlrev_b32_e32 v30, 16, v32
	v_and_b32_e32 v31, 0xffff0000, v32
	v_lshlrev_b32_e32 v32, 16, v33
	v_and_b32_e32 v33, 0xffff0000, v33
	v_pk_add_f32 v[24:25], v[24:25], v[28:29]
	v_pk_add_f32 v[22:23], v[22:23], v[26:27]
	v_pk_add_f32 v[26:27], v[16:17], v[32:33]
	v_pk_add_f32 v[16:17], v[14:15], v[30:31]
	v_cvt_pk_bf16_f32 v14, v22, v23
	v_cvt_pk_bf16_f32 v15, v24, v25
	s_nop 0
	v_cvt_pk_bf16_f32 v16, v16, v17
	v_cvt_pk_bf16_f32 v17, v26, v27
	global_load_dwordx4 v[22:25], v[34:35], off
	v_lshl_add_u64 v[26:27], v[146:147], 0, s[36:37]
	global_store_dwordx4 v[42:43], v[14:17], off offset:256
	s_waitcnt vmcnt(0)
	s_nop 0
	v_lshlrev_b32_e32 v14, 16, v22
	v_and_b32_e32 v15, 0xffff0000, v22
	v_lshlrev_b32_e32 v16, 16, v23
	v_and_b32_e32 v17, 0xffff0000, v23
	v_lshlrev_b32_e32 v22, 16, v24
	v_and_b32_e32 v23, 0xffff0000, v24
	v_lshlrev_b32_e32 v24, 16, v25
	v_and_b32_e32 v25, 0xffff0000, v25
	v_pk_add_f32 v[16:17], v[20:21], v[16:17]
	v_pk_add_f32 v[14:15], v[18:19], v[14:15]
	v_pk_add_f32 v[18:19], v[12:13], v[24:25]
	v_pk_add_f32 v[12:13], v[10:11], v[22:23]
	v_cvt_pk_bf16_f32 v10, v14, v15
	v_cvt_pk_bf16_f32 v11, v16, v17
	s_nop 0
	v_cvt_pk_bf16_f32 v12, v12, v13
	v_cvt_pk_bf16_f32 v13, v18, v19
	global_load_dwordx4 v[14:17], v[26:27], off offset:256
	s_nop 0
	global_store_dwordx4 v[34:35], v[10:13], off
	s_waitcnt vmcnt(0)
	s_nop 0
	v_lshlrev_b32_e32 v10, 16, v14
	v_and_b32_e32 v11, 0xffff0000, v14
	v_lshlrev_b32_e32 v12, 16, v15
	v_and_b32_e32 v13, 0xffff0000, v15
	v_lshlrev_b32_e32 v14, 16, v16
	v_and_b32_e32 v15, 0xffff0000, v16
	v_lshlrev_b32_e32 v16, 16, v17
	v_and_b32_e32 v17, 0xffff0000, v17
	v_pk_add_f32 v[6:7], v[6:7], v[10:11]
	v_pk_add_f32 v[10:11], v[4:5], v[16:17]
	v_pk_add_f32 v[4:5], v[2:3], v[14:15]
	v_pk_add_f32 v[8:9], v[8:9], v[12:13]
	v_cvt_pk_bf16_f32 v2, v6, v7
	s_nop 0
	v_cvt_pk_bf16_f32 v3, v8, v9
	v_cvt_pk_bf16_f32 v4, v4, v5
	v_cvt_pk_bf16_f32 v5, v10, v11
	global_store_dwordx4 v[26:27], v[2:5], off offset:256
	s_cbranch_vccz .LBB0_1109
	s_waitcnt vmcnt(0)
	s_cmpk_gt_u32 s44, 0xff
	s_cbranch_scc1 .LBB0_1124
	s_barrier

.LBB0_1143:
	v_add_u32_e32 v155, s53, v153
	s_add_u32 s38, s12, s36
	ds_read_b128 v[156:159], v155
	ds_read_b128 v[172:175], v155 offset:1024
	ds_read_b128 v[176:179], v155 offset:2048
	ds_read_b128 v[180:183], v155 offset:3072
	s_addc_u32 s39, s13, s37
	s_add_u32 s38, s38, 0x100
	s_addc_u32 s39, s39, 0
	s_add_u32 s59, s31, s36
	s_addc_u32 s60, s57, s37
	s_cmpk_eq_i32 s36, 0x1500
	s_cselect_b32 s41, s35, s39
	s_cselect_b32 s40, s34, s38
	s_cselect_b32 s39, s7, s60
	s_cselect_b32 s38, s6, s59
	v_lshl_add_u64 v[216:217], v[146:147], 0, s[36:37]
	s_add_i32 m0, s23, 0xc000
	ds_read_b128 v[184:187], v154
	ds_read_b128 v[188:191], v154 offset:1024
	ds_read_b128 v[192:195], v154 offset:2048
	ds_read_b128 v[196:199], v154 offset:3072
	ds_read_b128 v[200:203], v154 offset:4096
	ds_read_b128 v[204:207], v154 offset:5120
	ds_read_b128 v[208:211], v154 offset:6144
	ds_read_b128 v[212:215], v154 offset:7168
	global_load_lds_dwordx4 v[216:217], off
	v_lshl_add_u64 v[216:217], v[150:151], 0, s[36:37]
	s_add_i32 m0, s23, 0xe000
	s_nop 0
	global_load_lds_dwordx4 v[216:217], off
	s_waitcnt lgkmcnt(8)
	s_barrier
	s_waitcnt lgkmcnt(0)
	s_waitcnt lgkmcnt(0)
	v_mfma_f32_16x16x32_bf16 v[126:129], v[156:159], v[184:187], v[126:129]
	v_mfma_f32_16x16x32_bf16 v[122:125], v[176:179], v[184:187], v[122:125]
	v_mfma_f32_16x16x32_bf16 v[110:113], v[156:159], v[192:195], v[110:113]
	v_mfma_f32_16x16x32_bf16 v[106:109], v[176:179], v[192:195], v[106:109]
	v_mfma_f32_16x16x32_bf16 v[94:97], v[156:159], v[200:203], v[94:97]
	v_mfma_f32_16x16x32_bf16 v[90:93], v[176:179], v[200:203], v[90:93]
	v_mfma_f32_16x16x32_bf16 v[78:81], v[156:159], v[208:211], v[78:81]
	v_mfma_f32_16x16x32_bf16 v[74:77], v[176:179], v[208:211], v[74:77]
	v_mfma_f32_16x16x32_bf16 v[126:129], v[172:175], v[188:191], v[126:129]
	v_mfma_f32_16x16x32_bf16 v[122:125], v[180:183], v[188:191], v[122:125]
	v_mfma_f32_16x16x32_bf16 v[110:113], v[172:175], v[196:199], v[110:113]
	v_mfma_f32_16x16x32_bf16 v[106:109], v[180:183], v[196:199], v[106:109]
	v_mfma_f32_16x16x32_bf16 v[94:97], v[172:175], v[204:207], v[94:97]
	v_mfma_f32_16x16x32_bf16 v[90:93], v[180:183], v[204:207], v[90:93]
	v_mfma_f32_16x16x32_bf16 v[78:81], v[172:175], v[212:215], v[78:81]
	v_mfma_f32_16x16x32_bf16 v[74:77], v[180:183], v[212:215], v[74:77]
	s_barrier
	s_add_i32 s59, s53, s22
	v_add_u32_e32 v155, s54, v153
	v_lshl_add_u64 v[232:233], s[38:39], 0, v[132:133]
	s_mov_b32 m0, s59
	ds_read_b128 v[216:219], v155
	ds_read_b128 v[220:223], v155 offset:1024
	ds_read_b128 v[224:227], v155 offset:2048
	ds_read_b128 v[228:231], v155 offset:3072
	global_load_lds_dwordx4 v[232:233], off
	v_lshl_add_u64 v[234:235], s[38:39], 0, v[136:137]
	s_add_i32 m0, s59, 0x2000
	s_nop 0
	global_load_lds_dwordx4 v[234:235], off
	s_barrier
	s_waitcnt lgkmcnt(0)
	s_waitcnt lgkmcnt(0)
	v_mfma_f32_16x16x32_bf16 v[118:121], v[216:219], v[184:187], v[118:121]
	v_mfma_f32_16x16x32_bf16 v[114:117], v[224:227], v[184:187], v[114:117]
	v_mfma_f32_16x16x32_bf16 v[102:105], v[216:219], v[192:195], v[102:105]
	v_mfma_f32_16x16x32_bf16 v[98:101], v[224:227], v[192:195], v[98:101]
	v_mfma_f32_16x16x32_bf16 v[86:89], v[216:219], v[200:203], v[86:89]
	v_mfma_f32_16x16x32_bf16 v[82:85], v[224:227], v[200:203], v[82:85]
	v_mfma_f32_16x16x32_bf16 v[70:73], v[216:219], v[208:211], v[70:73]
	v_mfma_f32_16x16x32_bf16 v[66:69], v[224:227], v[208:211], v[66:69]
	v_mfma_f32_16x16x32_bf16 v[118:121], v[220:223], v[188:191], v[118:121]
	v_mfma_f32_16x16x32_bf16 v[114:117], v[228:231], v[188:191], v[114:117]
	v_mfma_f32_16x16x32_bf16 v[102:105], v[220:223], v[196:199], v[102:105]
	v_mfma_f32_16x16x32_bf16 v[98:101], v[228:231], v[196:199], v[98:101]
	v_mfma_f32_16x16x32_bf16 v[86:89], v[220:223], v[204:207], v[86:89]
	v_mfma_f32_16x16x32_bf16 v[82:85], v[228:231], v[204:207], v[82:85]
	v_mfma_f32_16x16x32_bf16 v[70:73], v[220:223], v[212:215], v[70:73]
	v_mfma_f32_16x16x32_bf16 v[66:69], v[228:231], v[212:215], v[66:69]
	s_mov_b32 m0, s23
	v_lshl_add_u64 v[236:237], s[40:41], 0, v[130:131]
	s_barrier
	ds_read_b128 v[184:187], v154 offset:16384
	ds_read_b128 v[188:191], v154 offset:17408
	ds_read_b128 v[192:195], v154 offset:18432
	ds_read_b128 v[196:199], v154 offset:19456
	ds_read_b128 v[200:203], v154 offset:20480
	ds_read_b128 v[204:207], v154 offset:21504
	ds_read_b128 v[208:211], v154 offset:22528
	ds_read_b128 v[212:215], v154 offset:23552
	global_load_lds_dwordx4 v[236:237], off
	v_lshl_add_u64 v[238:239], s[40:41], 0, v[134:135]
	s_mov_b32 m0, s44
	s_nop 0
	global_load_lds_dwordx4 v[238:239], off
	s_barrier
	s_waitcnt lgkmcnt(0)
	s_waitcnt lgkmcnt(0)
	v_mfma_f32_16x16x32_bf16 v[62:65], v[156:159], v[184:187], v[62:65]
	v_mfma_f32_16x16x32_bf16 v[58:61], v[176:179], v[184:187], v[58:61]
	v_mfma_f32_16x16x32_bf16 v[46:49], v[156:159], v[192:195], v[46:49]
	v_mfma_f32_16x16x32_bf16 v[42:45], v[176:179], v[192:195], v[42:45]
	v_mfma_f32_16x16x32_bf16 v[30:33], v[156:159], v[200:203], v[30:33]
	v_mfma_f32_16x16x32_bf16 v[26:29], v[176:179], v[200:203], v[26:29]
	v_mfma_f32_16x16x32_bf16 v[14:17], v[156:159], v[208:211], v[14:17]
	v_mfma_f32_16x16x32_bf16 v[10:13], v[176:179], v[208:211], v[10:13]
	v_mfma_f32_16x16x32_bf16 v[62:65], v[172:175], v[188:191], v[62:65]
	v_mfma_f32_16x16x32_bf16 v[58:61], v[180:183], v[188:191], v[58:61]
	v_mfma_f32_16x16x32_bf16 v[46:49], v[172:175], v[196:199], v[46:49]
	v_mfma_f32_16x16x32_bf16 v[42:45], v[180:183], v[196:199], v[42:45]
	v_mfma_f32_16x16x32_bf16 v[30:33], v[172:175], v[204:207], v[30:33]
	v_mfma_f32_16x16x32_bf16 v[26:29], v[180:183], v[204:207], v[26:29]
	v_mfma_f32_16x16x32_bf16 v[14:17], v[172:175], v[212:215], v[14:17]
	v_mfma_f32_16x16x32_bf16 v[10:13], v[180:183], v[212:215], v[10:13]
	s_barrier
	s_add_u32 s60, s38, 0xb0000
	s_addc_u32 s61, s39, 0
	s_add_i32 s59, s54, s22
	v_lshl_add_u64 v[156:157], s[60:61], 0, v[132:133]
	s_mov_b32 m0, s59
	s_nop 0
	global_load_lds_dwordx4 v[156:157], off
	v_lshl_add_u64 v[156:157], s[60:61], 0, v[136:137]
	s_add_i32 m0, s59, 0x2000
	s_nop 0
	global_load_lds_dwordx4 v[156:157], off
	s_waitcnt vmcnt(6)
	s_barrier
	v_mfma_f32_16x16x32_bf16 v[54:57], v[216:219], v[184:187], v[54:57]
	v_mfma_f32_16x16x32_bf16 v[50:53], v[224:227], v[184:187], v[50:53]
	v_mfma_f32_16x16x32_bf16 v[38:41], v[216:219], v[192:195], v[38:41]
	v_mfma_f32_16x16x32_bf16 v[34:37], v[224:227], v[192:195], v[34:37]
	v_mfma_f32_16x16x32_bf16 v[22:25], v[216:219], v[200:203], v[22:25]
	v_mfma_f32_16x16x32_bf16 v[18:21], v[224:227], v[200:203], v[18:21]
	v_mfma_f32_16x16x32_bf16 v[6:9], v[216:219], v[208:211], v[6:9]
	v_mfma_f32_16x16x32_bf16 v[2:5], v[224:227], v[208:211], v[2:5]
	v_mfma_f32_16x16x32_bf16 v[54:57], v[220:223], v[188:191], v[54:57]
	v_mfma_f32_16x16x32_bf16 v[50:53], v[228:231], v[188:191], v[50:53]
	v_mfma_f32_16x16x32_bf16 v[38:41], v[220:223], v[196:199], v[38:41]
	v_mfma_f32_16x16x32_bf16 v[34:37], v[228:231], v[196:199], v[34:37]
	v_mfma_f32_16x16x32_bf16 v[22:25], v[220:223], v[204:207], v[22:25]
	v_mfma_f32_16x16x32_bf16 v[18:21], v[228:231], v[204:207], v[18:21]
	v_mfma_f32_16x16x32_bf16 v[6:9], v[220:223], v[212:215], v[6:9]
	v_mfma_f32_16x16x32_bf16 v[2:5], v[228:231], v[212:215], v[2:5]
	s_add_i32 s59, 0, 0x18000
	v_add_u32_e32 v155, s59, v153
	s_barrier
	ds_read_b128 v[156:159], v155
	ds_read_b128 v[172:175], v155 offset:1024
	ds_read_b128 v[176:179], v155 offset:2048
	ds_read_b128 v[180:183], v155 offset:3072
	s_add_u32 s40, s40, 0xb0000
	s_addc_u32 s41, s41, 0
	s_mov_b32 m0, s45
	v_lshl_add_u64 v[216:217], s[40:41], 0, v[130:131]
	ds_read_b128 v[184:187], v154 offset:32768
	ds_read_b128 v[188:191], v154 offset:33792
	ds_read_b128 v[192:195], v154 offset:34816
	ds_read_b128 v[196:199], v154 offset:35840
	ds_read_b128 v[200:203], v154 offset:36864
	ds_read_b128 v[204:207], v154 offset:37888
	ds_read_b128 v[208:211], v154 offset:38912
	ds_read_b128 v[212:215], v154 offset:39936
	global_load_lds_dwordx4 v[216:217], off
	v_lshl_add_u64 v[216:217], s[40:41], 0, v[134:135]
	s_mov_b32 m0, s46
	s_nop 0
	global_load_lds_dwordx4 v[216:217], off
	s_waitcnt lgkmcnt(8)
	s_barrier
	s_waitcnt lgkmcnt(0)
	s_waitcnt lgkmcnt(0)
	v_mfma_f32_16x16x32_bf16 v[126:129], v[156:159], v[184:187], v[126:129]
	v_mfma_f32_16x16x32_bf16 v[122:125], v[176:179], v[184:187], v[122:125]
	v_mfma_f32_16x16x32_bf16 v[110:113], v[156:159], v[192:195], v[110:113]
	v_mfma_f32_16x16x32_bf16 v[106:109], v[176:179], v[192:195], v[106:109]
	v_mfma_f32_16x16x32_bf16 v[94:97], v[156:159], v[200:203], v[94:97]
	v_mfma_f32_16x16x32_bf16 v[90:93], v[176:179], v[200:203], v[90:93]
	v_mfma_f32_16x16x32_bf16 v[78:81], v[156:159], v[208:211], v[78:81]
	v_mfma_f32_16x16x32_bf16 v[74:77], v[176:179], v[208:211], v[74:77]
	v_mfma_f32_16x16x32_bf16 v[126:129], v[172:175], v[188:191], v[126:129]
	v_mfma_f32_16x16x32_bf16 v[122:125], v[180:183], v[188:191], v[122:125]
	v_mfma_f32_16x16x32_bf16 v[110:113], v[172:175], v[196:199], v[110:113]
	v_mfma_f32_16x16x32_bf16 v[106:109], v[180:183], v[196:199], v[106:109]
	v_mfma_f32_16x16x32_bf16 v[94:97], v[172:175], v[204:207], v[94:97]
	v_mfma_f32_16x16x32_bf16 v[90:93], v[180:183], v[204:207], v[90:93]
	v_mfma_f32_16x16x32_bf16 v[78:81], v[172:175], v[212:215], v[78:81]
	v_mfma_f32_16x16x32_bf16 v[74:77], v[180:183], v[212:215], v[74:77]
	s_barrier
	s_add_i32 s40, 0, 0x1c000
	s_add_i32 s41, s59, s22
	v_add_u32_e32 v155, s40, v153
	v_lshl_add_u64 v[232:233], v[232:233], 0, s[28:29]
	s_mov_b32 m0, s41
	ds_read_b128 v[216:219], v155
	ds_read_b128 v[220:223], v155 offset:1024
	ds_read_b128 v[224:227], v155 offset:2048
	ds_read_b128 v[228:231], v155 offset:3072
	global_load_lds_dwordx4 v[232:233], off
	v_lshl_add_u64 v[232:233], v[234:235], 0, s[28:29]
	s_add_i32 m0, s41, 0x2000
	s_nop 0
	global_load_lds_dwordx4 v[232:233], off
	s_barrier
	s_waitcnt lgkmcnt(0)
	s_waitcnt lgkmcnt(0)
	v_mfma_f32_16x16x32_bf16 v[118:121], v[216:219], v[184:187], v[118:121]
	v_mfma_f32_16x16x32_bf16 v[114:117], v[224:227], v[184:187], v[114:117]
	v_mfma_f32_16x16x32_bf16 v[102:105], v[216:219], v[192:195], v[102:105]
	v_mfma_f32_16x16x32_bf16 v[98:101], v[224:227], v[192:195], v[98:101]
	v_mfma_f32_16x16x32_bf16 v[86:89], v[216:219], v[200:203], v[86:89]
	v_mfma_f32_16x16x32_bf16 v[82:85], v[224:227], v[200:203], v[82:85]
	v_mfma_f32_16x16x32_bf16 v[70:73], v[216:219], v[208:211], v[70:73]
	v_mfma_f32_16x16x32_bf16 v[66:69], v[224:227], v[208:211], v[66:69]
	v_mfma_f32_16x16x32_bf16 v[118:121], v[220:223], v[188:191], v[118:121]
	v_mfma_f32_16x16x32_bf16 v[114:117], v[228:231], v[188:191], v[114:117]
	v_mfma_f32_16x16x32_bf16 v[102:105], v[220:223], v[196:199], v[102:105]
	v_mfma_f32_16x16x32_bf16 v[98:101], v[228:231], v[196:199], v[98:101]
	v_mfma_f32_16x16x32_bf16 v[86:89], v[220:223], v[204:207], v[86:89]
	v_mfma_f32_16x16x32_bf16 v[82:85], v[228:231], v[204:207], v[82:85]
	v_mfma_f32_16x16x32_bf16 v[70:73], v[220:223], v[212:215], v[70:73]
	v_mfma_f32_16x16x32_bf16 v[66:69], v[228:231], v[212:215], v[66:69]
	s_mov_b32 m0, s50
	v_lshl_add_u64 v[232:233], v[236:237], 0, s[28:29]
	s_barrier
	ds_read_b128 v[184:187], v154 offset:49152
	ds_read_b128 v[188:191], v154 offset:50176
	ds_read_b128 v[192:195], v154 offset:51200
	ds_read_b128 v[196:199], v154 offset:52224
	ds_read_b128 v[200:203], v154 offset:53248
	ds_read_b128 v[204:207], v154 offset:54272
	ds_read_b128 v[208:211], v154 offset:55296
	ds_read_b128 v[212:215], v154 offset:56320
	global_load_lds_dwordx4 v[232:233], off
	v_lshl_add_u64 v[232:233], v[238:239], 0, s[28:29]
	s_mov_b32 m0, s51
	s_nop 0
	global_load_lds_dwordx4 v[232:233], off
	s_barrier
	s_waitcnt lgkmcnt(0)
	s_waitcnt lgkmcnt(0)
	v_mfma_f32_16x16x32_bf16 v[62:65], v[156:159], v[184:187], v[62:65]
	v_mfma_f32_16x16x32_bf16 v[58:61], v[176:179], v[184:187], v[58:61]
	v_mfma_f32_16x16x32_bf16 v[46:49], v[156:159], v[192:195], v[46:49]
	v_mfma_f32_16x16x32_bf16 v[42:45], v[176:179], v[192:195], v[42:45]
	v_mfma_f32_16x16x32_bf16 v[30:33], v[156:159], v[200:203], v[30:33]
	v_mfma_f32_16x16x32_bf16 v[26:29], v[176:179], v[200:203], v[26:29]
	v_mfma_f32_16x16x32_bf16 v[14:17], v[156:159], v[208:211], v[14:17]
	v_mfma_f32_16x16x32_bf16 v[10:13], v[176:179], v[208:211], v[10:13]
	v_mfma_f32_16x16x32_bf16 v[62:65], v[172:175], v[188:191], v[62:65]
	v_mfma_f32_16x16x32_bf16 v[58:61], v[180:183], v[188:191], v[58:61]
	v_mfma_f32_16x16x32_bf16 v[46:49], v[172:175], v[196:199], v[46:49]
	v_mfma_f32_16x16x32_bf16 v[42:45], v[180:183], v[196:199], v[42:45]
	v_mfma_f32_16x16x32_bf16 v[30:33], v[172:175], v[204:207], v[30:33]
	v_mfma_f32_16x16x32_bf16 v[26:29], v[180:183], v[204:207], v[26:29]
	v_mfma_f32_16x16x32_bf16 v[14:17], v[172:175], v[212:215], v[14:17]
	v_mfma_f32_16x16x32_bf16 v[10:13], v[180:183], v[212:215], v[10:13]
	s_barrier
	s_add_u32 s38, s38, 0xb0080
	s_addc_u32 s39, s39, 0
	s_add_i32 s40, s40, s22
	v_lshl_add_u64 v[156:157], s[38:39], 0, v[132:133]
	s_mov_b32 m0, s40
	s_nop 0
	global_load_lds_dwordx4 v[156:157], off
	v_lshl_add_u64 v[156:157], s[38:39], 0, v[136:137]
	s_add_i32 m0, s40, 0x2000
	s_nop 0
	global_load_lds_dwordx4 v[156:157], off
	s_waitcnt vmcnt(6)
	s_barrier
	v_mfma_f32_16x16x32_bf16 v[54:57], v[216:219], v[184:187], v[54:57]
	v_mfma_f32_16x16x32_bf16 v[50:53], v[224:227], v[184:187], v[50:53]
	v_mfma_f32_16x16x32_bf16 v[38:41], v[216:219], v[192:195], v[38:41]
	v_mfma_f32_16x16x32_bf16 v[34:37], v[224:227], v[192:195], v[34:37]
	v_mfma_f32_16x16x32_bf16 v[22:25], v[216:219], v[200:203], v[22:25]
	v_mfma_f32_16x16x32_bf16 v[18:21], v[224:227], v[200:203], v[18:21]
	v_mfma_f32_16x16x32_bf16 v[6:9], v[216:219], v[208:211], v[6:9]
	v_mfma_f32_16x16x32_bf16 v[2:5], v[224:227], v[208:211], v[2:5]
	v_mfma_f32_16x16x32_bf16 v[54:57], v[220:223], v[188:191], v[54:57]
	v_mfma_f32_16x16x32_bf16 v[50:53], v[228:231], v[188:191], v[50:53]
	v_mfma_f32_16x16x32_bf16 v[38:41], v[220:223], v[196:199], v[38:41]
	v_mfma_f32_16x16x32_bf16 v[34:37], v[228:231], v[196:199], v[34:37]
	v_mfma_f32_16x16x32_bf16 v[22:25], v[220:223], v[204:207], v[22:25]
	v_mfma_f32_16x16x32_bf16 v[18:21], v[228:231], v[204:207], v[18:21]
	v_mfma_f32_16x16x32_bf16 v[6:9], v[220:223], v[212:215], v[6:9]
	v_mfma_f32_16x16x32_bf16 v[2:5], v[228:231], v[212:215], v[2:5]
	s_add_i32 s58, s58, 2
	s_add_u32 s36, s36, 0x100
	s_addc_u32 s37, s37, 0
	s_cmp_gt_u32 s58, 41
	s_barrier
	s_cbranch_scc0 .LBB0_1143
	s_add_u32 s36, s31, 0xffffff00
	s_addc_u32 s37, s57, -1
	s_and_b64 vcc, exec, s[4:5]
	s_cbranch_vccnz .LBB0_1130
	v_mov_b32_e32 v2, 0
	s_mov_b32 s0, s55
	s_mov_b32 s43, s56
	s_mov_b64 s[12:13], s[34:35]
	s_mov_b32 s52, s30
	v_mov_b32_e32 v3, v2
	v_mov_b32_e32 v4, v2
	v_mov_b32_e32 v5, v2
	v_mov_b32_e32 v6, v2
	v_mov_b32_e32 v7, v2
	v_mov_b32_e32 v8, v2
	v_mov_b32_e32 v9, v2
	v_mov_b32_e32 v18, v2
	v_mov_b32_e32 v19, v2
	v_mov_b32_e32 v20, v2
	v_mov_b32_e32 v21, v2
	v_mov_b32_e32 v22, v2
	v_mov_b32_e32 v23, v2
	v_mov_b32_e32 v24, v2
	v_mov_b32_e32 v25, v2
	v_mov_b32_e32 v34, v2
	v_mov_b32_e32 v35, v2
	v_mov_b32_e32 v36, v2
	v_mov_b32_e32 v37, v2
	v_mov_b32_e32 v38, v2
	v_mov_b32_e32 v39, v2
	v_mov_b32_e32 v40, v2
	v_mov_b32_e32 v41, v2
	v_mov_b32_e32 v50, v2
	v_mov_b32_e32 v51, v2
	v_mov_b32_e32 v52, v2
	v_mov_b32_e32 v53, v2
	v_mov_b32_e32 v54, v2
	v_mov_b32_e32 v55, v2
	v_mov_b32_e32 v56, v2
	v_mov_b32_e32 v57, v2
	v_mov_b32_e32 v10, v2
	v_mov_b32_e32 v11, v2
	v_mov_b32_e32 v12, v2
	v_mov_b32_e32 v13, v2
	v_mov_b32_e32 v14, v2
	v_mov_b32_e32 v15, v2
	v_mov_b32_e32 v16, v2
	v_mov_b32_e32 v17, v2
	v_mov_b32_e32 v26, v2
	v_mov_b32_e32 v27, v2
	v_mov_b32_e32 v28, v2
	v_mov_b32_e32 v29, v2
	v_mov_b32_e32 v30, v2
	v_mov_b32_e32 v31, v2
	v_mov_b32_e32 v32, v2
	v_mov_b32_e32 v33, v2
	v_mov_b32_e32 v42, v2
	v_mov_b32_e32 v43, v2
	v_mov_b32_e32 v44, v2
	v_mov_b32_e32 v45, v2
	v_mov_b32_e32 v46, v2
	v_mov_b32_e32 v47, v2
	v_mov_b32_e32 v48, v2
	v_mov_b32_e32 v49, v2
	v_mov_b32_e32 v58, v2
	v_mov_b32_e32 v59, v2
	v_mov_b32_e32 v60, v2
	v_mov_b32_e32 v61, v2
	v_mov_b32_e32 v62, v2
	v_mov_b32_e32 v63, v2
	v_mov_b32_e32 v64, v2
	v_mov_b32_e32 v65, v2
	v_mov_b32_e32 v66, v2
	v_mov_b32_e32 v67, v2
	v_mov_b32_e32 v68, v2
	v_mov_b32_e32 v69, v2
	v_mov_b32_e32 v70, v2
	v_mov_b32_e32 v71, v2
	v_mov_b32_e32 v72, v2
	v_mov_b32_e32 v73, v2
	v_mov_b32_e32 v82, v2
	v_mov_b32_e32 v83, v2
	v_mov_b32_e32 v84, v2
	v_mov_b32_e32 v85, v2
	v_mov_b32_e32 v86, v2
	v_mov_b32_e32 v87, v2
	v_mov_b32_e32 v88, v2
	v_mov_b32_e32 v89, v2
	v_mov_b32_e32 v98, v2
	v_mov_b32_e32 v99, v2
	v_mov_b32_e32 v100, v2
	v_mov_b32_e32 v101, v2
	v_mov_b32_e32 v102, v2
	v_mov_b32_e32 v103, v2
	v_mov_b32_e32 v104, v2
	v_mov_b32_e32 v105, v2
	v_mov_b32_e32 v114, v2
	v_mov_b32_e32 v115, v2
	v_mov_b32_e32 v116, v2
	v_mov_b32_e32 v117, v2
	v_mov_b32_e32 v118, v2
	v_mov_b32_e32 v119, v2
	v_mov_b32_e32 v120, v2
	v_mov_b32_e32 v121, v2
	v_mov_b32_e32 v74, v2
	v_mov_b32_e32 v75, v2
	v_mov_b32_e32 v76, v2
	v_mov_b32_e32 v77, v2
	v_mov_b32_e32 v78, v2
	v_mov_b32_e32 v79, v2
	v_mov_b32_e32 v80, v2
	v_mov_b32_e32 v81, v2
	v_mov_b32_e32 v90, v2
	v_mov_b32_e32 v91, v2
	v_mov_b32_e32 v92, v2
	v_mov_b32_e32 v93, v2
	v_mov_b32_e32 v94, v2
	v_mov_b32_e32 v95, v2
	v_mov_b32_e32 v96, v2
	v_mov_b32_e32 v97, v2
	v_mov_b32_e32 v106, v2
	v_mov_b32_e32 v107, v2
	v_mov_b32_e32 v108, v2
	v_mov_b32_e32 v109, v2
	v_mov_b32_e32 v110, v2
	v_mov_b32_e32 v111, v2
	v_mov_b32_e32 v112, v2
	v_mov_b32_e32 v113, v2
	v_mov_b32_e32 v122, v2
	v_mov_b32_e32 v123, v2
	v_mov_b32_e32 v124, v2
	v_mov_b32_e32 v125, v2
	v_mov_b32_e32 v126, v2
	v_mov_b32_e32 v127, v2
	v_mov_b32_e32 v128, v2
	v_mov_b32_e32 v129, v2
	s_andn2_b64 vcc, exec, s[2:3]
	s_cbranch_vccnz .LBB0_1131
